# lane-permuted epilogue stores extended to all eight GEMM epilogues (GU1 GU2 WIN PA PR D1 WO D2)
# speedup vs baseline: 1.0788x; 1.0005x over previous
.LBB0_397:
	v_and_b32_e32 v254, 63, v128
	v_and_b32_e32 v255, 3, v254
	v_lshrrev_b32_e32 v254, 2, v254
	v_lshl_or_b32 v254, v255, 4, v254
	v_lshlrev_b32_e32 v254, 2, v254
	v_mul_f32_e32 v158, 0xbfb8aa3b, v124
	v_mul_f32_e32 v159, 0xbfb8aa3b, v125
	v_exp_f32_e32 v158, v158
	v_exp_f32_e32 v159, v159
	v_mul_f32_e32 v160, 0xbfb8aa3b, v126
	v_mul_f32_e32 v161, 0xbfb8aa3b, v127
	v_exp_f32_e32 v160, v160
	v_exp_f32_e32 v161, v161
	v_add_f32_e32 v158, 1.0, v158
	v_add_f32_e32 v159, 1.0, v159
	v_rcp_f32_e32 v158, v158
	v_rcp_f32_e32 v159, v159
	v_add_f32_e32 v160, 1.0, v160
	v_add_f32_e32 v161, 1.0, v161
	v_rcp_f32_e32 v160, v160
	v_rcp_f32_e32 v161, v161
	v_pk_mul_f32 v[124:125], v[124:125], v[158:159]
	v_lshl_add_u32 v155, s54, 8, v129
	v_pk_mul_f32 v[120:121], v[124:125], v[120:121]
	v_pk_mul_f32 v[124:125], v[126:127], v[160:161]
	v_cvt_pk_bf16_f32 v120, v120, v121
	v_mul_f32_e32 v121, 0xbfb8aa3b, v116
	v_pk_mul_f32 v[122:123], v[124:125], v[122:123]
	v_exp_f32_e32 v124, v121
	v_mul_f32_e32 v121, 0xbfb8aa3b, v117
	v_exp_f32_e32 v125, v121
	v_cvt_pk_bf16_f32 v121, v122, v123
	v_add_f32_e32 v122, 1.0, v124
	v_mul_f32_e32 v124, 0xbfb8aa3b, v118
	v_add_f32_e32 v123, 1.0, v125
	v_mul_f32_e32 v125, 0xbfb8aa3b, v119
	v_exp_f32_e32 v124, v124
	v_exp_f32_e32 v125, v125
	v_rcp_f32_e32 v122, v122
	v_rcp_f32_e32 v123, v123
	v_add_f32_e32 v124, 1.0, v124
	v_add_f32_e32 v125, 1.0, v125
	v_rcp_f32_e32 v124, v124
	v_rcp_f32_e32 v125, v125
	v_pk_mul_f32 v[116:117], v[116:117], v[122:123]
	v_lshl_or_b32 v146, s52, 7, v151
	v_pk_mul_f32 v[112:113], v[116:117], v[112:113]
	v_mul_f32_e32 v116, 0xbfb8aa3b, v110
	v_cvt_pk_bf16_f32 v122, v112, v113
	v_pk_mul_f32 v[112:113], v[118:119], v[124:125]
	v_mul_f32_e32 v117, 0xbfb8aa3b, v111
	v_pk_mul_f32 v[112:113], v[112:113], v[114:115]
	v_mul_f32_e32 v114, 0xbfb8aa3b, v108
	v_mul_f32_e32 v115, 0xbfb8aa3b, v109
	v_exp_f32_e32 v114, v114
	v_exp_f32_e32 v115, v115
	v_exp_f32_e32 v116, v116
	v_exp_f32_e32 v117, v117
	v_add_f32_e32 v114, 1.0, v114
	v_add_f32_e32 v115, 1.0, v115
	v_rcp_f32_e32 v114, v114
	v_rcp_f32_e32 v115, v115
	v_add_f32_e32 v116, 1.0, v116
	v_add_f32_e32 v117, 1.0, v117
	v_rcp_f32_e32 v116, v116
	v_rcp_f32_e32 v117, v117
	v_pk_mul_f32 v[108:109], v[108:109], v[114:115]
	v_ashrrev_i32_e32 v147, 31, v146
	v_pk_mul_f32 v[104:105], v[108:109], v[104:105]
	v_pk_mul_f32 v[108:109], v[110:111], v[116:117]
	v_cvt_pk_bf16_f32 v104, v104, v105
	v_mul_f32_e32 v105, 0xbfb8aa3b, v100
	v_pk_mul_f32 v[106:107], v[108:109], v[106:107]
	v_exp_f32_e32 v108, v105
	v_mul_f32_e32 v105, 0xbfb8aa3b, v101
	v_exp_f32_e32 v109, v105
	v_cvt_pk_bf16_f32 v105, v106, v107
	v_add_f32_e32 v106, 1.0, v108
	v_mul_f32_e32 v108, 0xbfb8aa3b, v102
	v_add_f32_e32 v107, 1.0, v109
	v_mul_f32_e32 v109, 0xbfb8aa3b, v103
	v_exp_f32_e32 v108, v108
	v_exp_f32_e32 v109, v109
	v_rcp_f32_e32 v106, v106
	v_rcp_f32_e32 v107, v107
	v_add_f32_e32 v108, 1.0, v108
	v_add_f32_e32 v109, 1.0, v109
	v_rcp_f32_e32 v108, v108
	v_rcp_f32_e32 v109, v109
	v_pk_mul_f32 v[100:101], v[100:101], v[106:107]
	v_mov_b64_e32 v[148:149], s[6:7]
	v_pk_mul_f32 v[96:97], v[100:101], v[96:97]
	v_mul_f32_e32 v100, 0xbfb8aa3b, v94
	v_cvt_pk_bf16_f32 v106, v96, v97
	v_pk_mul_f32 v[96:97], v[102:103], v[108:109]
	v_mul_f32_e32 v101, 0xbfb8aa3b, v95
	v_pk_mul_f32 v[96:97], v[96:97], v[98:99]
	v_mul_f32_e32 v98, 0xbfb8aa3b, v92
	v_mul_f32_e32 v99, 0xbfb8aa3b, v93
	v_exp_f32_e32 v98, v98
	v_exp_f32_e32 v99, v99
	v_exp_f32_e32 v100, v100
	v_exp_f32_e32 v101, v101
	v_add_f32_e32 v98, 1.0, v98
	v_add_f32_e32 v99, 1.0, v99
	v_rcp_f32_e32 v98, v98
	v_rcp_f32_e32 v99, v99
	v_add_f32_e32 v100, 1.0, v100
	v_add_f32_e32 v101, 1.0, v101
	v_rcp_f32_e32 v100, v100
	v_rcp_f32_e32 v101, v101
	v_pk_mul_f32 v[92:93], v[92:93], v[98:99]
	v_cvt_pk_bf16_f32 v123, v112, v113
	v_pk_mul_f32 v[88:89], v[92:93], v[88:89]
	v_pk_mul_f32 v[92:93], v[94:95], v[100:101]
	v_cvt_pk_bf16_f32 v88, v88, v89
	v_mul_f32_e32 v89, 0xbfb8aa3b, v84
	v_pk_mul_f32 v[90:91], v[92:93], v[90:91]
	v_exp_f32_e32 v92, v89
	v_mul_f32_e32 v89, 0xbfb8aa3b, v85
	v_exp_f32_e32 v93, v89
	v_cvt_pk_bf16_f32 v89, v90, v91
	v_add_f32_e32 v90, 1.0, v92
	v_mul_f32_e32 v92, 0xbfb8aa3b, v86
	v_add_f32_e32 v91, 1.0, v93
	v_mul_f32_e32 v93, 0xbfb8aa3b, v87
	v_exp_f32_e32 v92, v92
	v_exp_f32_e32 v93, v93
	v_rcp_f32_e32 v90, v90
	v_rcp_f32_e32 v91, v91
	v_add_f32_e32 v92, 1.0, v92
	v_add_f32_e32 v93, 1.0, v93
	v_rcp_f32_e32 v92, v92
	v_rcp_f32_e32 v93, v93
	v_pk_mul_f32 v[84:85], v[84:85], v[90:91]
	v_or_b32_e32 v112, 16, v155
	v_pk_mul_f32 v[80:81], v[84:85], v[80:81]
	v_mul_f32_e32 v84, 0xbfb8aa3b, v78
	v_cvt_pk_bf16_f32 v90, v80, v81
	v_pk_mul_f32 v[80:81], v[86:87], v[92:93]
	v_mul_f32_e32 v85, 0xbfb8aa3b, v79
	v_pk_mul_f32 v[80:81], v[80:81], v[82:83]
	v_mul_f32_e32 v82, 0xbfb8aa3b, v76
	v_mul_f32_e32 v83, 0xbfb8aa3b, v77
	v_exp_f32_e32 v82, v82
	v_exp_f32_e32 v83, v83
	v_exp_f32_e32 v84, v84
	v_exp_f32_e32 v85, v85
	v_add_f32_e32 v82, 1.0, v82
	v_add_f32_e32 v83, 1.0, v83
	v_rcp_f32_e32 v82, v82
	v_rcp_f32_e32 v83, v83
	v_add_f32_e32 v84, 1.0, v84
	v_add_f32_e32 v85, 1.0, v85
	v_rcp_f32_e32 v84, v84
	v_rcp_f32_e32 v85, v85
	v_pk_mul_f32 v[76:77], v[76:77], v[82:83]
	v_cvt_pk_bf16_f32 v107, v96, v97
	v_pk_mul_f32 v[72:73], v[76:77], v[72:73]
	v_pk_mul_f32 v[76:77], v[78:79], v[84:85]
	v_cvt_pk_bf16_f32 v72, v72, v73
	v_mul_f32_e32 v73, 0xbfb8aa3b, v68
	v_pk_mul_f32 v[74:75], v[76:77], v[74:75]
	v_exp_f32_e32 v76, v73
	v_mul_f32_e32 v73, 0xbfb8aa3b, v69
	v_exp_f32_e32 v77, v73
	v_cvt_pk_bf16_f32 v73, v74, v75
	v_add_f32_e32 v74, 1.0, v76
	v_mul_f32_e32 v76, 0xbfb8aa3b, v70
	v_add_f32_e32 v75, 1.0, v77
	v_mul_f32_e32 v77, 0xbfb8aa3b, v71
	v_exp_f32_e32 v76, v76
	v_exp_f32_e32 v77, v77
	v_rcp_f32_e32 v74, v74
	v_rcp_f32_e32 v75, v75
	v_add_f32_e32 v76, 1.0, v76
	v_add_f32_e32 v77, 1.0, v77
	v_rcp_f32_e32 v76, v76
	v_rcp_f32_e32 v77, v77
	v_pk_mul_f32 v[68:69], v[68:69], v[74:75]
	v_or_b32_e32 v96, 32, v155
	v_pk_mul_f32 v[64:65], v[68:69], v[64:65]
	v_mul_f32_e32 v68, 0xbfb8aa3b, v62
	v_cvt_pk_bf16_f32 v74, v64, v65
	v_pk_mul_f32 v[64:65], v[70:71], v[76:77]
	v_mul_f32_e32 v69, 0xbfb8aa3b, v63
	v_pk_mul_f32 v[64:65], v[64:65], v[66:67]
	v_mul_f32_e32 v66, 0xbfb8aa3b, v60
	v_mul_f32_e32 v67, 0xbfb8aa3b, v61
	v_exp_f32_e32 v66, v66
	v_exp_f32_e32 v67, v67
	v_exp_f32_e32 v68, v68
	v_exp_f32_e32 v69, v69
	v_add_f32_e32 v66, 1.0, v66
	v_add_f32_e32 v67, 1.0, v67
	v_rcp_f32_e32 v66, v66
	v_rcp_f32_e32 v67, v67
	v_add_f32_e32 v68, 1.0, v68
	v_add_f32_e32 v69, 1.0, v69
	v_rcp_f32_e32 v68, v68
	v_rcp_f32_e32 v69, v69
	v_pk_mul_f32 v[60:61], v[60:61], v[66:67]
	v_cvt_pk_bf16_f32 v91, v80, v81
	v_pk_mul_f32 v[56:57], v[60:61], v[56:57]
	v_pk_mul_f32 v[60:61], v[62:63], v[68:69]
	v_cvt_pk_bf16_f32 v56, v56, v57
	v_mul_f32_e32 v57, 0xbfb8aa3b, v52
	v_pk_mul_f32 v[58:59], v[60:61], v[58:59]
	v_exp_f32_e32 v60, v57
	v_mul_f32_e32 v57, 0xbfb8aa3b, v53
	v_exp_f32_e32 v61, v57
	v_cvt_pk_bf16_f32 v57, v58, v59
	v_add_f32_e32 v58, 1.0, v60
	v_mul_f32_e32 v60, 0xbfb8aa3b, v54
	v_add_f32_e32 v59, 1.0, v61
	v_mul_f32_e32 v61, 0xbfb8aa3b, v55
	v_exp_f32_e32 v60, v60
	v_exp_f32_e32 v61, v61
	v_rcp_f32_e32 v58, v58
	v_rcp_f32_e32 v59, v59
	v_add_f32_e32 v60, 1.0, v60
	v_add_f32_e32 v61, 1.0, v61
	v_rcp_f32_e32 v60, v60
	v_rcp_f32_e32 v61, v61
	v_pk_mul_f32 v[52:53], v[52:53], v[58:59]
	v_or_b32_e32 v80, 48, v155
	v_pk_mul_f32 v[48:49], v[52:53], v[48:49]
	v_mul_f32_e32 v52, 0xbfb8aa3b, v46
	v_cvt_pk_bf16_f32 v58, v48, v49
	v_pk_mul_f32 v[48:49], v[54:55], v[60:61]
	v_mul_f32_e32 v53, 0xbfb8aa3b, v47
	v_pk_mul_f32 v[48:49], v[48:49], v[50:51]
	v_mul_f32_e32 v50, 0xbfb8aa3b, v44
	v_mul_f32_e32 v51, 0xbfb8aa3b, v45
	v_exp_f32_e32 v50, v50
	v_exp_f32_e32 v51, v51
	v_exp_f32_e32 v52, v52
	v_exp_f32_e32 v53, v53
	v_add_f32_e32 v50, 1.0, v50
	v_add_f32_e32 v51, 1.0, v51
	v_rcp_f32_e32 v50, v50
	v_rcp_f32_e32 v51, v51
	v_add_f32_e32 v52, 1.0, v52
	v_add_f32_e32 v53, 1.0, v53
	v_rcp_f32_e32 v52, v52
	v_rcp_f32_e32 v53, v53
	v_pk_mul_f32 v[44:45], v[44:45], v[50:51]
	v_cvt_pk_bf16_f32 v75, v64, v65
	v_pk_mul_f32 v[40:41], v[44:45], v[40:41]
	v_pk_mul_f32 v[44:45], v[46:47], v[52:53]
	v_cvt_pk_bf16_f32 v40, v40, v41
	v_mul_f32_e32 v41, 0xbfb8aa3b, v36
	v_pk_mul_f32 v[42:43], v[44:45], v[42:43]
	v_exp_f32_e32 v44, v41
	v_mul_f32_e32 v41, 0xbfb8aa3b, v37
	v_exp_f32_e32 v45, v41
	v_cvt_pk_bf16_f32 v41, v42, v43
	v_add_f32_e32 v42, 1.0, v44
	v_mul_f32_e32 v44, 0xbfb8aa3b, v38
	v_add_f32_e32 v43, 1.0, v45
	v_mul_f32_e32 v45, 0xbfb8aa3b, v39
	v_exp_f32_e32 v44, v44
	v_exp_f32_e32 v45, v45
	v_rcp_f32_e32 v42, v42
	v_rcp_f32_e32 v43, v43
	v_add_f32_e32 v44, 1.0, v44
	v_add_f32_e32 v45, 1.0, v45
	v_rcp_f32_e32 v44, v44
	v_rcp_f32_e32 v45, v45
	v_pk_mul_f32 v[36:37], v[36:37], v[42:43]
	v_add_u32_e32 v64, 0x80, v155
	v_pk_mul_f32 v[32:33], v[36:37], v[32:33]
	v_mul_f32_e32 v36, 0xbfb8aa3b, v30
	v_cvt_pk_bf16_f32 v42, v32, v33
	v_pk_mul_f32 v[32:33], v[38:39], v[44:45]
	v_mul_f32_e32 v37, 0xbfb8aa3b, v31
	v_pk_mul_f32 v[32:33], v[32:33], v[34:35]
	v_mul_f32_e32 v34, 0xbfb8aa3b, v28
	v_mul_f32_e32 v35, 0xbfb8aa3b, v29
	v_exp_f32_e32 v34, v34
	v_exp_f32_e32 v35, v35
	v_exp_f32_e32 v36, v36
	v_exp_f32_e32 v37, v37
	v_add_f32_e32 v34, 1.0, v34
	v_add_f32_e32 v35, 1.0, v35
	v_rcp_f32_e32 v34, v34
	v_rcp_f32_e32 v35, v35
	v_add_f32_e32 v36, 1.0, v36
	v_add_f32_e32 v37, 1.0, v37
	v_rcp_f32_e32 v36, v36
	v_rcp_f32_e32 v37, v37
	v_pk_mul_f32 v[28:29], v[28:29], v[34:35]
	v_cvt_pk_bf16_f32 v59, v48, v49
	v_pk_mul_f32 v[24:25], v[28:29], v[24:25]
	v_pk_mul_f32 v[28:29], v[30:31], v[36:37]
	v_cvt_pk_bf16_f32 v24, v24, v25
	v_mul_f32_e32 v25, 0xbfb8aa3b, v20
	v_pk_mul_f32 v[26:27], v[28:29], v[26:27]
	v_exp_f32_e32 v28, v25
	v_mul_f32_e32 v25, 0xbfb8aa3b, v21
	v_exp_f32_e32 v29, v25
	v_cvt_pk_bf16_f32 v25, v26, v27
	v_add_f32_e32 v26, 1.0, v28
	v_mul_f32_e32 v28, 0xbfb8aa3b, v22
	v_add_f32_e32 v27, 1.0, v29
	v_mul_f32_e32 v29, 0xbfb8aa3b, v23
	v_exp_f32_e32 v28, v28
	v_exp_f32_e32 v29, v29
	v_rcp_f32_e32 v26, v26
	v_rcp_f32_e32 v27, v27
	v_add_f32_e32 v28, 1.0, v28
	v_add_f32_e32 v29, 1.0, v29
	v_rcp_f32_e32 v28, v28
	v_rcp_f32_e32 v29, v29
	v_pk_mul_f32 v[20:21], v[20:21], v[26:27]
	v_add_u32_e32 v48, 0x90, v155
	v_pk_mul_f32 v[16:17], v[20:21], v[16:17]
	v_mul_f32_e32 v20, 0xbfb8aa3b, v14
	v_cvt_pk_bf16_f32 v26, v16, v17
	v_pk_mul_f32 v[16:17], v[22:23], v[28:29]
	v_mul_f32_e32 v21, 0xbfb8aa3b, v15
	v_pk_mul_f32 v[16:17], v[16:17], v[18:19]
	v_mul_f32_e32 v18, 0xbfb8aa3b, v12
	v_mul_f32_e32 v19, 0xbfb8aa3b, v13
	v_exp_f32_e32 v18, v18
	v_exp_f32_e32 v19, v19
	v_exp_f32_e32 v20, v20
	v_exp_f32_e32 v21, v21
	v_add_f32_e32 v18, 1.0, v18
	v_add_f32_e32 v19, 1.0, v19
	v_rcp_f32_e32 v18, v18
	v_rcp_f32_e32 v19, v19
	v_add_f32_e32 v20, 1.0, v20
	v_add_f32_e32 v21, 1.0, v21
	v_rcp_f32_e32 v20, v20
	v_rcp_f32_e32 v21, v21
	v_pk_mul_f32 v[12:13], v[12:13], v[18:19]
	v_cvt_pk_bf16_f32 v43, v32, v33
	v_pk_mul_f32 v[8:9], v[12:13], v[8:9]
	v_pk_mul_f32 v[12:13], v[14:15], v[20:21]
	v_cvt_pk_bf16_f32 v8, v8, v9
	v_mul_f32_e32 v9, 0xbfb8aa3b, v4
	v_pk_mul_f32 v[10:11], v[12:13], v[10:11]
	v_exp_f32_e32 v12, v9
	v_mul_f32_e32 v9, 0xbfb8aa3b, v5
	v_exp_f32_e32 v13, v9
	v_cvt_pk_bf16_f32 v9, v10, v11
	v_add_f32_e32 v10, 1.0, v12
	v_mul_f32_e32 v12, 0xbfb8aa3b, v6
	v_add_f32_e32 v11, 1.0, v13
	v_mul_f32_e32 v13, 0xbfb8aa3b, v7
	v_exp_f32_e32 v12, v12
	v_exp_f32_e32 v13, v13
	v_rcp_f32_e32 v10, v10
	v_rcp_f32_e32 v11, v11
	v_add_f32_e32 v12, 1.0, v12
	v_add_f32_e32 v13, 1.0, v13
	v_rcp_f32_e32 v12, v12
	v_rcp_f32_e32 v13, v13
	v_pk_mul_f32 v[4:5], v[4:5], v[10:11]
	v_add_u32_e32 v32, 0xa0, v155
	v_pk_mul_f32 v[0:1], v[4:5], v[0:1]
	v_cvt_pk_bf16_f32 v27, v16, v17
	v_add_u32_e32 v16, 0xb0, v155
	v_cvt_pk_bf16_f32 v10, v0, v1
	v_pk_mul_f32 v[0:1], v[6:7], v[12:13]
	v_mad_i64_i32 v[156:157], s[56:57], v155, s76, v[148:149]
	v_lshlrev_b64 v[146:147], 1, v[146:147]
	v_mad_i64_i32 v[112:113], s[56:57], v112, s76, v[148:149]
	v_mad_i64_i32 v[96:97], s[56:57], v96, s76, v[148:149]
	v_mad_i64_i32 v[80:81], s[56:57], v80, s76, v[148:149]
	v_mad_i64_i32 v[64:65], s[56:57], v64, s76, v[148:149]
	v_mad_i64_i32 v[48:49], s[56:57], v48, s76, v[148:149]
	v_mad_i64_i32 v[32:33], s[56:57], v32, s76, v[148:149]
	v_mad_i64_i32 v[16:17], s[56:57], v16, s76, v[148:149]
	v_pk_mul_f32 v[0:1], v[0:1], v[2:3]
	v_lshl_add_u64 v[156:157], v[156:157], 0, v[146:147]
	v_lshl_add_u64 v[112:113], v[112:113], 0, v[146:147]
	v_lshl_add_u64 v[96:97], v[96:97], 0, v[146:147]
	v_lshl_add_u64 v[80:81], v[80:81], 0, v[146:147]
	v_lshl_add_u64 v[64:65], v[64:65], 0, v[146:147]
	v_lshl_add_u64 v[48:49], v[48:49], 0, v[146:147]
	v_lshl_add_u64 v[32:33], v[32:33], 0, v[146:147]
	v_lshl_add_u64 v[16:17], v[16:17], 0, v[146:147]
	v_cvt_pk_bf16_f32 v11, v0, v1
	s_andn2_b64 vcc, exec, s[4:5]
	s_mov_b64 s[4:5], -1
	ds_bpermute_b32 v238, v254, v120
	ds_bpermute_b32 v239, v254, v121
	ds_bpermute_b32 v240, v254, v122
	ds_bpermute_b32 v241, v254, v123
	ds_bpermute_b32 v236, v254, v156
	ds_bpermute_b32 v237, v254, v157
	ds_bpermute_b32 v244, v254, v104
	ds_bpermute_b32 v245, v254, v105
	ds_bpermute_b32 v246, v254, v106
	ds_bpermute_b32 v247, v254, v107
	ds_bpermute_b32 v242, v254, v112
	ds_bpermute_b32 v243, v254, v113
	ds_bpermute_b32 v250, v254, v88
	ds_bpermute_b32 v251, v254, v89
	ds_bpermute_b32 v252, v254, v90
	ds_bpermute_b32 v253, v254, v91
	ds_bpermute_b32 v248, v254, v96
	ds_bpermute_b32 v249, v254, v97
	s_waitcnt lgkmcnt(12)
	global_store_dwordx4 v[236:237], v[238:241], off
	s_nop 0
	ds_bpermute_b32 v238, v254, v72
	ds_bpermute_b32 v239, v254, v73
	ds_bpermute_b32 v240, v254, v74
	ds_bpermute_b32 v241, v254, v75
	ds_bpermute_b32 v236, v254, v80
	ds_bpermute_b32 v237, v254, v81
	s_waitcnt lgkmcnt(12)
	global_store_dwordx4 v[242:243], v[244:247], off
	s_nop 0
	ds_bpermute_b32 v244, v254, v56
	ds_bpermute_b32 v245, v254, v57
	ds_bpermute_b32 v246, v254, v58
	ds_bpermute_b32 v247, v254, v59
	ds_bpermute_b32 v242, v254, v64
	ds_bpermute_b32 v243, v254, v65
	s_waitcnt lgkmcnt(12)
	global_store_dwordx4 v[248:249], v[250:253], off
	s_nop 0
	ds_bpermute_b32 v250, v254, v40
	ds_bpermute_b32 v251, v254, v41
	ds_bpermute_b32 v252, v254, v42
	ds_bpermute_b32 v253, v254, v43
	ds_bpermute_b32 v248, v254, v48
	ds_bpermute_b32 v249, v254, v49
	s_waitcnt lgkmcnt(12)
	global_store_dwordx4 v[236:237], v[238:241], off
	s_nop 0
	ds_bpermute_b32 v238, v254, v24
	ds_bpermute_b32 v239, v254, v25
	ds_bpermute_b32 v240, v254, v26
	ds_bpermute_b32 v241, v254, v27
	ds_bpermute_b32 v236, v254, v32
	ds_bpermute_b32 v237, v254, v33
	s_waitcnt lgkmcnt(12)
	global_store_dwordx4 v[242:243], v[244:247], off
	s_nop 0
	ds_bpermute_b32 v244, v254, v8
	ds_bpermute_b32 v245, v254, v9
	ds_bpermute_b32 v246, v254, v10
	ds_bpermute_b32 v247, v254, v11
	ds_bpermute_b32 v242, v254, v16
	ds_bpermute_b32 v243, v254, v17
	s_waitcnt lgkmcnt(12)
	global_store_dwordx4 v[248:249], v[250:253], off
	s_waitcnt lgkmcnt(6)
	global_store_dwordx4 v[236:237], v[238:241], off
	s_waitcnt lgkmcnt(0)
	global_store_dwordx4 v[242:243], v[244:247], off
	s_cbranch_vccnz .LBB0_390
	s_andn2_b64 vcc, exec, s[0:1]
	s_cbranch_vccnz .LBB0_389
	s_barrier
	s_branch .LBB0_389

.LBB0_812:
	v_and_b32_e32 v254, 63, v128
	v_and_b32_e32 v255, 3, v254
	v_lshrrev_b32_e32 v254, 2, v254
	v_lshl_or_b32 v254, v255, 4, v254
	v_lshlrev_b32_e32 v254, 2, v254
	s_add_i32 s13, s28, -6
	v_lshl_add_u32 v172, s30, 8, v129
	s_cmp_gt_u32 s13, 7
	s_mov_b64 s[30:31], -1
	s_cbranch_scc1 .LBB0_815
	s_and_b64 vcc, exec, s[30:31]
	s_cbranch_vccnz .LBB0_896

.LBB0_820:
	v_lshl_or_b32 v152, s28, 8, v167
	v_mov_b64_e32 v[154:155], s[2:3]
	v_ashrrev_i32_e32 v153, 31, v152
	v_mad_i64_i32 v[154:155], s[28:29], v172, s75, v[154:155]
	v_lshl_add_u64 v[154:155], v[152:153], 1, v[154:155]
	v_cvt_pk_bf16_f32 v156, v156, v157
	v_cvt_pk_bf16_f32 v157, v160, v161
	v_cvt_pk_bf16_f32 v158, v158, v159
	v_cvt_pk_bf16_f32 v159, v162, v163
	s_cmp_gt_i32 s15, 1
	s_mov_b64 s[28:29], -1
	ds_bpermute_b32 v238, v254, v156
	ds_bpermute_b32 v239, v254, v157
	ds_bpermute_b32 v240, v254, v158
	ds_bpermute_b32 v241, v254, v159
	ds_bpermute_b32 v236, v254, v154
	ds_bpermute_b32 v237, v254, v155
	s_waitcnt lgkmcnt(0)
	global_store_dwordx4 v[236:237], v[238:241], off
	s_cbranch_scc0 .LBB0_822
	v_mul_f32_e32 v138, 0xbfb8aa3b, v116
	v_exp_f32_e32 v138, v138
	v_mul_f32_e32 v156, 0xbfb8aa3b, v112
	v_exp_f32_e32 v156, v156
	v_mul_f32_e32 v158, 0xbfb8aa3b, v113
	v_add_f32_e32 v138, 1.0, v138
	v_exp_f32_e32 v159, v158
	v_add_f32_e32 v157, 1.0, v156
	v_rcp_f32_e32 v156, v138
	v_mul_f32_e32 v138, 0xbfb8aa3b, v117
	v_exp_f32_e32 v138, v138
	v_rcp_f32_e32 v158, v157
	v_mul_f32_e32 v162, 0xbfb8aa3b, v115
	v_exp_f32_e32 v163, v162
	v_add_f32_e32 v138, 1.0, v138
	v_rcp_f32_e32 v157, v138
	v_add_f32_e32 v138, 1.0, v159
	v_mul_f32_e32 v159, 0xbfb8aa3b, v118
	v_exp_f32_e32 v160, v159
	v_mul_f32_e32 v159, 0xbfb8aa3b, v114
	v_exp_f32_e32 v161, v159
	v_rcp_f32_e32 v159, v138
	v_add_f32_e32 v138, 1.0, v160
	v_rcp_f32_e32 v160, v138
	v_add_f32_e32 v138, 1.0, v161
	v_mul_f32_e32 v161, 0xbfb8aa3b, v119
	v_exp_f32_e32 v161, v161
	v_rcp_f32_e32 v162, v138
	s_mov_b64 s[28:29], 0
	v_add_f32_e32 v138, 1.0, v161
	v_rcp_f32_e32 v161, v138
	v_add_f32_e32 v138, 1.0, v163
	v_rcp_f32_e32 v163, v138

.LBB0_825:
	v_cvt_pk_bf16_f32 v156, v156, v157
	v_cvt_pk_bf16_f32 v157, v160, v161
	v_cvt_pk_bf16_f32 v158, v158, v159
	v_cvt_pk_bf16_f32 v159, v162, v163
	s_cmp_gt_i32 s15, 1
	s_mov_b64 s[28:29], -1
	ds_bpermute_b32 v244, v254, v156
	ds_bpermute_b32 v245, v254, v157
	ds_bpermute_b32 v246, v254, v158
	ds_bpermute_b32 v247, v254, v159
	ds_bpermute_b32 v242, v254, v154
	ds_bpermute_b32 v243, v254, v155
	s_waitcnt lgkmcnt(0)
	global_store_dwordx4 v[242:243], v[244:247], off offset:256
	s_cbranch_scc0 .LBB0_827
	v_mul_f32_e32 v138, 0xbfb8aa3b, v108
	v_exp_f32_e32 v138, v138
	v_mul_f32_e32 v154, 0xbfb8aa3b, v104
	v_exp_f32_e32 v154, v154
	v_mul_f32_e32 v155, 0xbfb8aa3b, v105
	v_add_f32_e32 v138, 1.0, v138
	v_rcp_f32_e32 v156, v138
	v_mul_f32_e32 v138, 0xbfb8aa3b, v109
	v_exp_f32_e32 v138, v138
	v_exp_f32_e32 v155, v155
	v_add_f32_e32 v154, 1.0, v154
	v_rcp_f32_e32 v158, v154
	v_add_f32_e32 v138, 1.0, v138
	v_mul_f32_e32 v154, 0xbfb8aa3b, v110
	v_rcp_f32_e32 v157, v138
	v_add_f32_e32 v138, 1.0, v155
	v_exp_f32_e32 v154, v154
	v_mul_f32_e32 v155, 0xbfb8aa3b, v106
	v_exp_f32_e32 v155, v155
	v_rcp_f32_e32 v159, v138
	v_add_f32_e32 v138, 1.0, v154
	v_mul_f32_e32 v154, 0xbfb8aa3b, v111
	v_rcp_f32_e32 v160, v138
	v_add_f32_e32 v138, 1.0, v155
	v_exp_f32_e32 v154, v154
	v_mul_f32_e32 v155, 0xbfb8aa3b, v107
	v_exp_f32_e32 v155, v155
	v_rcp_f32_e32 v162, v138
	v_add_f32_e32 v138, 1.0, v154
	v_rcp_f32_e32 v161, v138
	v_add_f32_e32 v138, 1.0, v155
	v_rcp_f32_e32 v163, v138
	s_mov_b64 s[28:29], 0

.LBB0_830:
	v_or_b32_e32 v138, 16, v172
	v_mov_b64_e32 v[154:155], s[2:3]
	v_mad_i64_i32 v[154:155], s[28:29], v138, s75, v[154:155]
	v_lshl_add_u64 v[154:155], v[152:153], 1, v[154:155]
	v_cvt_pk_bf16_f32 v156, v156, v157
	v_cvt_pk_bf16_f32 v157, v160, v161
	v_cvt_pk_bf16_f32 v158, v158, v159
	v_cvt_pk_bf16_f32 v159, v162, v163
	s_cmp_gt_i32 s15, 1
	s_mov_b64 s[28:29], -1
	ds_bpermute_b32 v250, v254, v156
	ds_bpermute_b32 v251, v254, v157
	ds_bpermute_b32 v252, v254, v158
	ds_bpermute_b32 v253, v254, v159
	ds_bpermute_b32 v248, v254, v154
	ds_bpermute_b32 v249, v254, v155
	s_waitcnt lgkmcnt(0)
	global_store_dwordx4 v[248:249], v[250:253], off
	s_cbranch_scc0 .LBB0_832
	v_mul_f32_e32 v138, 0xbfb8aa3b, v100
	v_exp_f32_e32 v138, v138
	v_mul_f32_e32 v156, 0xbfb8aa3b, v96
	v_exp_f32_e32 v156, v156
	v_mul_f32_e32 v158, 0xbfb8aa3b, v97
	v_add_f32_e32 v138, 1.0, v138
	v_exp_f32_e32 v159, v158
	v_add_f32_e32 v157, 1.0, v156
	v_rcp_f32_e32 v156, v138
	v_mul_f32_e32 v138, 0xbfb8aa3b, v101
	v_exp_f32_e32 v138, v138
	v_rcp_f32_e32 v158, v157
	v_mul_f32_e32 v162, 0xbfb8aa3b, v99
	v_exp_f32_e32 v163, v162
	v_add_f32_e32 v138, 1.0, v138
	v_rcp_f32_e32 v157, v138
	v_add_f32_e32 v138, 1.0, v159
	v_mul_f32_e32 v159, 0xbfb8aa3b, v102
	v_exp_f32_e32 v160, v159
	v_mul_f32_e32 v159, 0xbfb8aa3b, v98
	v_exp_f32_e32 v161, v159
	v_rcp_f32_e32 v159, v138
	v_add_f32_e32 v138, 1.0, v160
	v_rcp_f32_e32 v160, v138
	v_add_f32_e32 v138, 1.0, v161
	v_mul_f32_e32 v161, 0xbfb8aa3b, v103
	v_exp_f32_e32 v161, v161
	v_rcp_f32_e32 v162, v138
	s_mov_b64 s[28:29], 0
	v_add_f32_e32 v138, 1.0, v161
	v_rcp_f32_e32 v161, v138
	v_add_f32_e32 v138, 1.0, v163
	v_rcp_f32_e32 v163, v138

.LBB0_835:
	v_cvt_pk_bf16_f32 v156, v156, v157
	v_cvt_pk_bf16_f32 v157, v160, v161
	v_cvt_pk_bf16_f32 v158, v158, v159
	v_cvt_pk_bf16_f32 v159, v162, v163
	s_cmp_gt_i32 s15, 1
	s_mov_b64 s[28:29], -1
	ds_bpermute_b32 v238, v254, v156
	ds_bpermute_b32 v239, v254, v157
	ds_bpermute_b32 v240, v254, v158
	ds_bpermute_b32 v241, v254, v159
	ds_bpermute_b32 v236, v254, v154
	ds_bpermute_b32 v237, v254, v155
	s_waitcnt lgkmcnt(0)
	global_store_dwordx4 v[236:237], v[238:241], off offset:256
	s_cbranch_scc0 .LBB0_837
	v_mul_f32_e32 v138, 0xbfb8aa3b, v92
	v_exp_f32_e32 v138, v138
	v_mul_f32_e32 v154, 0xbfb8aa3b, v88
	v_exp_f32_e32 v154, v154
	v_mul_f32_e32 v155, 0xbfb8aa3b, v89
	v_add_f32_e32 v138, 1.0, v138
	v_rcp_f32_e32 v156, v138
	v_mul_f32_e32 v138, 0xbfb8aa3b, v93
	v_exp_f32_e32 v138, v138
	v_exp_f32_e32 v155, v155
	v_add_f32_e32 v154, 1.0, v154
	v_rcp_f32_e32 v158, v154
	v_add_f32_e32 v138, 1.0, v138
	v_mul_f32_e32 v154, 0xbfb8aa3b, v94
	v_rcp_f32_e32 v157, v138
	v_add_f32_e32 v138, 1.0, v155
	v_exp_f32_e32 v154, v154
	v_mul_f32_e32 v155, 0xbfb8aa3b, v90
	v_exp_f32_e32 v155, v155
	v_rcp_f32_e32 v159, v138
	v_add_f32_e32 v138, 1.0, v154
	v_mul_f32_e32 v154, 0xbfb8aa3b, v95
	v_rcp_f32_e32 v160, v138
	v_add_f32_e32 v138, 1.0, v155
	v_exp_f32_e32 v154, v154
	v_mul_f32_e32 v155, 0xbfb8aa3b, v91
	v_exp_f32_e32 v155, v155
	v_rcp_f32_e32 v162, v138
	v_add_f32_e32 v138, 1.0, v154
	v_rcp_f32_e32 v161, v138
	v_add_f32_e32 v138, 1.0, v155
	v_rcp_f32_e32 v163, v138
	s_mov_b64 s[28:29], 0

.LBB0_840:
	v_or_b32_e32 v138, 32, v172
	v_mov_b64_e32 v[154:155], s[2:3]
	v_mad_i64_i32 v[154:155], s[28:29], v138, s75, v[154:155]
	v_lshl_add_u64 v[154:155], v[152:153], 1, v[154:155]
	v_cvt_pk_bf16_f32 v156, v156, v157
	v_cvt_pk_bf16_f32 v157, v160, v161
	v_cvt_pk_bf16_f32 v158, v158, v159
	v_cvt_pk_bf16_f32 v159, v162, v163
	s_cmp_gt_i32 s15, 1
	s_mov_b64 s[28:29], -1
	ds_bpermute_b32 v244, v254, v156
	ds_bpermute_b32 v245, v254, v157
	ds_bpermute_b32 v246, v254, v158
	ds_bpermute_b32 v247, v254, v159
	ds_bpermute_b32 v242, v254, v154
	ds_bpermute_b32 v243, v254, v155
	s_waitcnt lgkmcnt(0)
	global_store_dwordx4 v[242:243], v[244:247], off
	s_cbranch_scc0 .LBB0_842
	v_mul_f32_e32 v138, 0xbfb8aa3b, v84
	v_exp_f32_e32 v138, v138
	v_mul_f32_e32 v156, 0xbfb8aa3b, v80
	v_exp_f32_e32 v156, v156
	v_mul_f32_e32 v158, 0xbfb8aa3b, v81
	v_add_f32_e32 v138, 1.0, v138
	v_exp_f32_e32 v159, v158
	v_add_f32_e32 v157, 1.0, v156
	v_rcp_f32_e32 v156, v138
	v_mul_f32_e32 v138, 0xbfb8aa3b, v85
	v_exp_f32_e32 v138, v138
	v_rcp_f32_e32 v158, v157
	v_mul_f32_e32 v162, 0xbfb8aa3b, v83
	v_exp_f32_e32 v163, v162
	v_add_f32_e32 v138, 1.0, v138
	v_rcp_f32_e32 v157, v138
	v_add_f32_e32 v138, 1.0, v159
	v_mul_f32_e32 v159, 0xbfb8aa3b, v86
	v_exp_f32_e32 v160, v159
	v_mul_f32_e32 v159, 0xbfb8aa3b, v82
	v_exp_f32_e32 v161, v159
	v_rcp_f32_e32 v159, v138
	v_add_f32_e32 v138, 1.0, v160
	v_rcp_f32_e32 v160, v138
	v_add_f32_e32 v138, 1.0, v161
	v_mul_f32_e32 v161, 0xbfb8aa3b, v87
	v_exp_f32_e32 v161, v161
	v_rcp_f32_e32 v162, v138
	s_mov_b64 s[28:29], 0
	v_add_f32_e32 v138, 1.0, v161
	v_rcp_f32_e32 v161, v138
	v_add_f32_e32 v138, 1.0, v163
	v_rcp_f32_e32 v163, v138

.LBB0_845:
	v_cvt_pk_bf16_f32 v156, v156, v157
	v_cvt_pk_bf16_f32 v157, v160, v161
	v_cvt_pk_bf16_f32 v158, v158, v159
	v_cvt_pk_bf16_f32 v159, v162, v163
	s_cmp_gt_i32 s15, 1
	s_mov_b64 s[28:29], -1
	ds_bpermute_b32 v250, v254, v156
	ds_bpermute_b32 v251, v254, v157
	ds_bpermute_b32 v252, v254, v158
	ds_bpermute_b32 v253, v254, v159
	ds_bpermute_b32 v248, v254, v154
	ds_bpermute_b32 v249, v254, v155
	s_waitcnt lgkmcnt(0)
	global_store_dwordx4 v[248:249], v[250:253], off offset:256
	s_cbranch_scc0 .LBB0_847
	v_mul_f32_e32 v138, 0xbfb8aa3b, v76
	v_exp_f32_e32 v138, v138
	v_mul_f32_e32 v154, 0xbfb8aa3b, v72
	v_exp_f32_e32 v154, v154
	v_mul_f32_e32 v155, 0xbfb8aa3b, v73
	v_add_f32_e32 v138, 1.0, v138
	v_rcp_f32_e32 v156, v138
	v_mul_f32_e32 v138, 0xbfb8aa3b, v77
	v_exp_f32_e32 v138, v138
	v_exp_f32_e32 v155, v155
	v_add_f32_e32 v154, 1.0, v154
	v_rcp_f32_e32 v158, v154
	v_add_f32_e32 v138, 1.0, v138
	v_mul_f32_e32 v154, 0xbfb8aa3b, v78
	v_rcp_f32_e32 v157, v138
	v_add_f32_e32 v138, 1.0, v155
	v_exp_f32_e32 v154, v154
	v_mul_f32_e32 v155, 0xbfb8aa3b, v74
	v_exp_f32_e32 v155, v155
	v_rcp_f32_e32 v159, v138
	v_add_f32_e32 v138, 1.0, v154
	v_mul_f32_e32 v154, 0xbfb8aa3b, v79
	v_rcp_f32_e32 v160, v138
	v_add_f32_e32 v138, 1.0, v155
	v_exp_f32_e32 v154, v154
	v_mul_f32_e32 v155, 0xbfb8aa3b, v75
	v_exp_f32_e32 v155, v155
	v_rcp_f32_e32 v162, v138
	v_add_f32_e32 v138, 1.0, v154
	v_rcp_f32_e32 v161, v138
	v_add_f32_e32 v138, 1.0, v155
	v_rcp_f32_e32 v163, v138
	s_mov_b64 s[28:29], 0

.LBB0_850:
	v_or_b32_e32 v138, 48, v172
	v_mov_b64_e32 v[154:155], s[2:3]
	v_mad_i64_i32 v[154:155], s[28:29], v138, s75, v[154:155]
	v_lshl_add_u64 v[154:155], v[152:153], 1, v[154:155]
	v_cvt_pk_bf16_f32 v156, v156, v157
	v_cvt_pk_bf16_f32 v157, v160, v161
	v_cvt_pk_bf16_f32 v158, v158, v159
	v_cvt_pk_bf16_f32 v159, v162, v163
	s_cmp_gt_i32 s15, 1
	s_mov_b64 s[28:29], -1
	ds_bpermute_b32 v238, v254, v156
	ds_bpermute_b32 v239, v254, v157
	ds_bpermute_b32 v240, v254, v158
	ds_bpermute_b32 v241, v254, v159
	ds_bpermute_b32 v236, v254, v154
	ds_bpermute_b32 v237, v254, v155
	s_waitcnt lgkmcnt(0)
	global_store_dwordx4 v[236:237], v[238:241], off
	s_cbranch_scc0 .LBB0_852
	v_mul_f32_e32 v138, 0xbfb8aa3b, v68
	v_exp_f32_e32 v138, v138
	v_mul_f32_e32 v156, 0xbfb8aa3b, v64
	v_exp_f32_e32 v156, v156
	v_mul_f32_e32 v158, 0xbfb8aa3b, v65
	v_add_f32_e32 v138, 1.0, v138
	v_exp_f32_e32 v159, v158
	v_add_f32_e32 v157, 1.0, v156
	v_rcp_f32_e32 v156, v138
	v_mul_f32_e32 v138, 0xbfb8aa3b, v69
	v_exp_f32_e32 v138, v138
	v_rcp_f32_e32 v158, v157
	v_mul_f32_e32 v162, 0xbfb8aa3b, v67
	v_exp_f32_e32 v163, v162
	v_add_f32_e32 v138, 1.0, v138
	v_rcp_f32_e32 v157, v138
	v_add_f32_e32 v138, 1.0, v159
	v_mul_f32_e32 v159, 0xbfb8aa3b, v70
	v_exp_f32_e32 v160, v159
	v_mul_f32_e32 v159, 0xbfb8aa3b, v66
	v_exp_f32_e32 v161, v159
	v_rcp_f32_e32 v159, v138
	v_add_f32_e32 v138, 1.0, v160
	v_rcp_f32_e32 v160, v138
	v_add_f32_e32 v138, 1.0, v161
	v_mul_f32_e32 v161, 0xbfb8aa3b, v71
	v_exp_f32_e32 v161, v161
	v_rcp_f32_e32 v162, v138
	s_mov_b64 s[28:29], 0
	v_add_f32_e32 v138, 1.0, v161
	v_rcp_f32_e32 v161, v138
	v_add_f32_e32 v138, 1.0, v163
	v_rcp_f32_e32 v163, v138

.LBB0_855:
	v_cvt_pk_bf16_f32 v156, v156, v157
	v_cvt_pk_bf16_f32 v157, v160, v161
	v_cvt_pk_bf16_f32 v158, v158, v159
	v_cvt_pk_bf16_f32 v159, v162, v163
	s_cmp_gt_i32 s15, 1
	s_mov_b64 s[28:29], -1
	ds_bpermute_b32 v244, v254, v156
	ds_bpermute_b32 v245, v254, v157
	ds_bpermute_b32 v246, v254, v158
	ds_bpermute_b32 v247, v254, v159
	ds_bpermute_b32 v242, v254, v154
	ds_bpermute_b32 v243, v254, v155
	s_waitcnt lgkmcnt(0)
	global_store_dwordx4 v[242:243], v[244:247], off offset:256
	s_cbranch_scc0 .LBB0_857
	v_mul_f32_e32 v138, 0xbfb8aa3b, v60
	v_exp_f32_e32 v138, v138
	v_mul_f32_e32 v154, 0xbfb8aa3b, v56
	v_exp_f32_e32 v154, v154
	v_mul_f32_e32 v155, 0xbfb8aa3b, v57
	v_add_f32_e32 v138, 1.0, v138
	v_rcp_f32_e32 v156, v138
	v_mul_f32_e32 v138, 0xbfb8aa3b, v61
	v_exp_f32_e32 v138, v138
	v_exp_f32_e32 v155, v155
	v_add_f32_e32 v154, 1.0, v154
	v_rcp_f32_e32 v158, v154
	v_add_f32_e32 v138, 1.0, v138
	v_mul_f32_e32 v154, 0xbfb8aa3b, v62
	v_rcp_f32_e32 v157, v138
	v_add_f32_e32 v138, 1.0, v155
	v_exp_f32_e32 v154, v154
	v_mul_f32_e32 v155, 0xbfb8aa3b, v58
	v_exp_f32_e32 v155, v155
	v_rcp_f32_e32 v159, v138
	v_add_f32_e32 v138, 1.0, v154
	v_mul_f32_e32 v154, 0xbfb8aa3b, v63
	v_rcp_f32_e32 v160, v138
	v_add_f32_e32 v138, 1.0, v155
	v_exp_f32_e32 v154, v154
	v_mul_f32_e32 v155, 0xbfb8aa3b, v59
	v_exp_f32_e32 v155, v155
	v_rcp_f32_e32 v162, v138
	v_add_f32_e32 v138, 1.0, v154
	v_rcp_f32_e32 v161, v138
	v_add_f32_e32 v138, 1.0, v155
	v_rcp_f32_e32 v163, v138
	s_mov_b64 s[28:29], 0

.LBB0_860:
	v_add_u32_e32 v138, 0x80, v172
	v_mov_b64_e32 v[154:155], s[2:3]
	v_mad_i64_i32 v[154:155], s[28:29], v138, s75, v[154:155]
	v_lshl_add_u64 v[154:155], v[152:153], 1, v[154:155]
	v_cvt_pk_bf16_f32 v156, v156, v157
	v_cvt_pk_bf16_f32 v157, v160, v161
	v_cvt_pk_bf16_f32 v158, v158, v159
	v_cvt_pk_bf16_f32 v159, v162, v163
	s_cmp_gt_i32 s15, 1
	s_mov_b64 s[28:29], -1
	ds_bpermute_b32 v250, v254, v156
	ds_bpermute_b32 v251, v254, v157
	ds_bpermute_b32 v252, v254, v158
	ds_bpermute_b32 v253, v254, v159
	ds_bpermute_b32 v248, v254, v154
	ds_bpermute_b32 v249, v254, v155
	s_waitcnt lgkmcnt(0)
	global_store_dwordx4 v[248:249], v[250:253], off
	s_cbranch_scc0 .LBB0_862
	v_mul_f32_e32 v138, 0xbfb8aa3b, v52
	v_exp_f32_e32 v138, v138
	v_mul_f32_e32 v156, 0xbfb8aa3b, v48
	v_exp_f32_e32 v156, v156
	v_mul_f32_e32 v158, 0xbfb8aa3b, v49
	v_add_f32_e32 v138, 1.0, v138
	v_exp_f32_e32 v159, v158
	v_add_f32_e32 v157, 1.0, v156
	v_rcp_f32_e32 v156, v138
	v_mul_f32_e32 v138, 0xbfb8aa3b, v53
	v_exp_f32_e32 v138, v138
	v_rcp_f32_e32 v158, v157
	v_mul_f32_e32 v162, 0xbfb8aa3b, v51
	v_exp_f32_e32 v163, v162
	v_add_f32_e32 v138, 1.0, v138
	v_rcp_f32_e32 v157, v138
	v_add_f32_e32 v138, 1.0, v159
	v_mul_f32_e32 v159, 0xbfb8aa3b, v54
	v_exp_f32_e32 v160, v159
	v_mul_f32_e32 v159, 0xbfb8aa3b, v50
	v_exp_f32_e32 v161, v159
	v_rcp_f32_e32 v159, v138
	v_add_f32_e32 v138, 1.0, v160
	v_rcp_f32_e32 v160, v138
	v_add_f32_e32 v138, 1.0, v161
	v_mul_f32_e32 v161, 0xbfb8aa3b, v55
	v_exp_f32_e32 v161, v161
	v_rcp_f32_e32 v162, v138
	s_mov_b64 s[28:29], 0
	v_add_f32_e32 v138, 1.0, v161
	v_rcp_f32_e32 v161, v138
	v_add_f32_e32 v138, 1.0, v163
	v_rcp_f32_e32 v163, v138

.LBB0_865:
	v_cvt_pk_bf16_f32 v156, v156, v157
	v_cvt_pk_bf16_f32 v157, v160, v161
	v_cvt_pk_bf16_f32 v158, v158, v159
	v_cvt_pk_bf16_f32 v159, v162, v163
	s_cmp_gt_i32 s15, 1
	s_mov_b64 s[28:29], -1
	ds_bpermute_b32 v238, v254, v156
	ds_bpermute_b32 v239, v254, v157
	ds_bpermute_b32 v240, v254, v158
	ds_bpermute_b32 v241, v254, v159
	ds_bpermute_b32 v236, v254, v154
	ds_bpermute_b32 v237, v254, v155
	s_waitcnt lgkmcnt(0)
	global_store_dwordx4 v[236:237], v[238:241], off offset:256
	s_cbranch_scc0 .LBB0_867
	v_mul_f32_e32 v138, 0xbfb8aa3b, v44
	v_exp_f32_e32 v138, v138
	v_mul_f32_e32 v154, 0xbfb8aa3b, v40
	v_exp_f32_e32 v154, v154
	v_mul_f32_e32 v155, 0xbfb8aa3b, v41
	v_add_f32_e32 v138, 1.0, v138
	v_rcp_f32_e32 v156, v138
	v_mul_f32_e32 v138, 0xbfb8aa3b, v45
	v_exp_f32_e32 v138, v138
	v_exp_f32_e32 v155, v155
	v_add_f32_e32 v154, 1.0, v154
	v_rcp_f32_e32 v158, v154
	v_add_f32_e32 v138, 1.0, v138
	v_mul_f32_e32 v154, 0xbfb8aa3b, v46
	v_rcp_f32_e32 v157, v138
	v_add_f32_e32 v138, 1.0, v155
	v_exp_f32_e32 v154, v154
	v_mul_f32_e32 v155, 0xbfb8aa3b, v42
	v_exp_f32_e32 v155, v155
	v_rcp_f32_e32 v159, v138
	v_add_f32_e32 v138, 1.0, v154
	v_mul_f32_e32 v154, 0xbfb8aa3b, v47
	v_rcp_f32_e32 v160, v138
	v_add_f32_e32 v138, 1.0, v155
	v_exp_f32_e32 v154, v154
	v_mul_f32_e32 v155, 0xbfb8aa3b, v43
	v_exp_f32_e32 v155, v155
	v_rcp_f32_e32 v162, v138
	v_add_f32_e32 v138, 1.0, v154
	v_rcp_f32_e32 v161, v138
	v_add_f32_e32 v138, 1.0, v155
	v_rcp_f32_e32 v163, v138
	s_mov_b64 s[28:29], 0

.LBB0_870:
	v_add_u32_e32 v138, 0x90, v172
	v_mov_b64_e32 v[154:155], s[2:3]
	v_mad_i64_i32 v[154:155], s[28:29], v138, s75, v[154:155]
	v_lshl_add_u64 v[154:155], v[152:153], 1, v[154:155]
	v_cvt_pk_bf16_f32 v156, v156, v157
	v_cvt_pk_bf16_f32 v157, v160, v161
	v_cvt_pk_bf16_f32 v158, v158, v159
	v_cvt_pk_bf16_f32 v159, v162, v163
	s_cmp_gt_i32 s15, 1
	s_mov_b64 s[28:29], -1
	ds_bpermute_b32 v244, v254, v156
	ds_bpermute_b32 v245, v254, v157
	ds_bpermute_b32 v246, v254, v158
	ds_bpermute_b32 v247, v254, v159
	ds_bpermute_b32 v242, v254, v154
	ds_bpermute_b32 v243, v254, v155
	s_waitcnt lgkmcnt(0)
	global_store_dwordx4 v[242:243], v[244:247], off
	s_cbranch_scc0 .LBB0_872
	v_mul_f32_e32 v138, 0xbfb8aa3b, v36
	v_exp_f32_e32 v138, v138
	v_mul_f32_e32 v156, 0xbfb8aa3b, v32
	v_exp_f32_e32 v156, v156
	v_mul_f32_e32 v158, 0xbfb8aa3b, v33
	v_add_f32_e32 v138, 1.0, v138
	v_exp_f32_e32 v159, v158
	v_add_f32_e32 v157, 1.0, v156
	v_rcp_f32_e32 v156, v138
	v_mul_f32_e32 v138, 0xbfb8aa3b, v37
	v_exp_f32_e32 v138, v138
	v_rcp_f32_e32 v158, v157
	v_mul_f32_e32 v162, 0xbfb8aa3b, v35
	v_exp_f32_e32 v163, v162
	v_add_f32_e32 v138, 1.0, v138
	v_rcp_f32_e32 v157, v138
	v_add_f32_e32 v138, 1.0, v159
	v_mul_f32_e32 v159, 0xbfb8aa3b, v38
	v_exp_f32_e32 v160, v159
	v_mul_f32_e32 v159, 0xbfb8aa3b, v34
	v_exp_f32_e32 v161, v159
	v_rcp_f32_e32 v159, v138
	v_add_f32_e32 v138, 1.0, v160
	v_rcp_f32_e32 v160, v138
	v_add_f32_e32 v138, 1.0, v161
	v_mul_f32_e32 v161, 0xbfb8aa3b, v39
	v_exp_f32_e32 v161, v161
	v_rcp_f32_e32 v162, v138
	s_mov_b64 s[28:29], 0
	v_add_f32_e32 v138, 1.0, v161
	v_rcp_f32_e32 v161, v138
	v_add_f32_e32 v138, 1.0, v163
	v_rcp_f32_e32 v163, v138

.LBB0_875:
	v_cvt_pk_bf16_f32 v156, v156, v157
	v_cvt_pk_bf16_f32 v157, v160, v161
	v_cvt_pk_bf16_f32 v158, v158, v159
	v_cvt_pk_bf16_f32 v159, v162, v163
	s_cmp_gt_i32 s15, 1
	s_mov_b64 s[28:29], -1
	ds_bpermute_b32 v250, v254, v156
	ds_bpermute_b32 v251, v254, v157
	ds_bpermute_b32 v252, v254, v158
	ds_bpermute_b32 v253, v254, v159
	ds_bpermute_b32 v248, v254, v154
	ds_bpermute_b32 v249, v254, v155
	s_waitcnt lgkmcnt(0)
	global_store_dwordx4 v[248:249], v[250:253], off offset:256
	s_cbranch_scc0 .LBB0_877
	v_mul_f32_e32 v138, 0xbfb8aa3b, v28
	v_exp_f32_e32 v138, v138
	v_mul_f32_e32 v154, 0xbfb8aa3b, v24
	v_exp_f32_e32 v154, v154
	v_mul_f32_e32 v155, 0xbfb8aa3b, v25
	v_add_f32_e32 v138, 1.0, v138
	v_rcp_f32_e32 v156, v138
	v_mul_f32_e32 v138, 0xbfb8aa3b, v29
	v_exp_f32_e32 v138, v138
	v_exp_f32_e32 v155, v155
	v_add_f32_e32 v154, 1.0, v154
	v_rcp_f32_e32 v158, v154
	v_add_f32_e32 v138, 1.0, v138
	v_mul_f32_e32 v154, 0xbfb8aa3b, v30
	v_rcp_f32_e32 v157, v138
	v_add_f32_e32 v138, 1.0, v155
	v_exp_f32_e32 v154, v154
	v_mul_f32_e32 v155, 0xbfb8aa3b, v26
	v_exp_f32_e32 v155, v155
	v_rcp_f32_e32 v159, v138
	v_add_f32_e32 v138, 1.0, v154
	v_mul_f32_e32 v154, 0xbfb8aa3b, v31
	v_rcp_f32_e32 v160, v138
	v_add_f32_e32 v138, 1.0, v155
	v_exp_f32_e32 v154, v154
	v_mul_f32_e32 v155, 0xbfb8aa3b, v27
	v_exp_f32_e32 v155, v155
	v_rcp_f32_e32 v162, v138
	v_add_f32_e32 v138, 1.0, v154
	v_rcp_f32_e32 v161, v138
	v_add_f32_e32 v138, 1.0, v155
	v_rcp_f32_e32 v163, v138
	s_mov_b64 s[28:29], 0

.LBB0_880:
	v_add_u32_e32 v138, 0xa0, v172
	v_mov_b64_e32 v[154:155], s[2:3]
	v_mad_i64_i32 v[154:155], s[28:29], v138, s75, v[154:155]
	v_lshl_add_u64 v[154:155], v[152:153], 1, v[154:155]
	v_cvt_pk_bf16_f32 v156, v156, v157
	v_cvt_pk_bf16_f32 v157, v160, v161
	v_cvt_pk_bf16_f32 v158, v158, v159
	v_cvt_pk_bf16_f32 v159, v162, v163
	s_cmp_gt_i32 s15, 1
	s_mov_b64 s[28:29], -1
	ds_bpermute_b32 v238, v254, v156
	ds_bpermute_b32 v239, v254, v157
	ds_bpermute_b32 v240, v254, v158
	ds_bpermute_b32 v241, v254, v159
	ds_bpermute_b32 v236, v254, v154
	ds_bpermute_b32 v237, v254, v155
	s_waitcnt lgkmcnt(0)
	global_store_dwordx4 v[236:237], v[238:241], off
	s_cbranch_scc0 .LBB0_882
	v_mul_f32_e32 v138, 0xbfb8aa3b, v20
	v_exp_f32_e32 v138, v138
	v_mul_f32_e32 v156, 0xbfb8aa3b, v16
	v_exp_f32_e32 v156, v156
	v_mul_f32_e32 v158, 0xbfb8aa3b, v17
	v_add_f32_e32 v138, 1.0, v138
	v_exp_f32_e32 v159, v158
	v_add_f32_e32 v157, 1.0, v156
	v_rcp_f32_e32 v156, v138
	v_mul_f32_e32 v138, 0xbfb8aa3b, v21
	v_exp_f32_e32 v138, v138
	v_rcp_f32_e32 v158, v157
	v_mul_f32_e32 v162, 0xbfb8aa3b, v19
	v_exp_f32_e32 v163, v162
	v_add_f32_e32 v138, 1.0, v138
	v_rcp_f32_e32 v157, v138
	v_add_f32_e32 v138, 1.0, v159
	v_mul_f32_e32 v159, 0xbfb8aa3b, v22
	v_exp_f32_e32 v160, v159
	v_mul_f32_e32 v159, 0xbfb8aa3b, v18
	v_exp_f32_e32 v161, v159
	v_rcp_f32_e32 v159, v138
	v_add_f32_e32 v138, 1.0, v160
	v_rcp_f32_e32 v160, v138
	v_add_f32_e32 v138, 1.0, v161
	v_mul_f32_e32 v161, 0xbfb8aa3b, v23
	v_exp_f32_e32 v161, v161
	v_rcp_f32_e32 v162, v138
	s_mov_b64 s[28:29], 0
	v_add_f32_e32 v138, 1.0, v161
	v_rcp_f32_e32 v161, v138
	v_add_f32_e32 v138, 1.0, v163
	v_rcp_f32_e32 v163, v138

.LBB0_885:
	v_cvt_pk_bf16_f32 v156, v156, v157
	v_cvt_pk_bf16_f32 v157, v160, v161
	v_cvt_pk_bf16_f32 v158, v158, v159
	v_cvt_pk_bf16_f32 v159, v162, v163
	s_cmp_gt_i32 s15, 1
	s_mov_b64 s[28:29], -1
	ds_bpermute_b32 v244, v254, v156
	ds_bpermute_b32 v245, v254, v157
	ds_bpermute_b32 v246, v254, v158
	ds_bpermute_b32 v247, v254, v159
	ds_bpermute_b32 v242, v254, v154
	ds_bpermute_b32 v243, v254, v155
	s_waitcnt lgkmcnt(0)
	global_store_dwordx4 v[242:243], v[244:247], off offset:256
	s_cbranch_scc0 .LBB0_887
	v_mul_f32_e32 v138, 0xbfb8aa3b, v12
	v_exp_f32_e32 v138, v138
	v_mul_f32_e32 v154, 0xbfb8aa3b, v8
	v_exp_f32_e32 v154, v154
	v_mul_f32_e32 v156, 0xbfb8aa3b, v9
	v_add_f32_e32 v138, 1.0, v138
	v_exp_f32_e32 v157, v156
	v_add_f32_e32 v155, 1.0, v154
	v_rcp_f32_e32 v154, v138
	v_mul_f32_e32 v138, 0xbfb8aa3b, v13
	v_exp_f32_e32 v138, v138
	v_rcp_f32_e32 v156, v155
	v_mul_f32_e32 v160, 0xbfb8aa3b, v11
	v_exp_f32_e32 v161, v160
	v_add_f32_e32 v138, 1.0, v138
	v_rcp_f32_e32 v155, v138
	v_add_f32_e32 v138, 1.0, v157
	v_mul_f32_e32 v157, 0xbfb8aa3b, v14
	v_exp_f32_e32 v158, v157
	v_mul_f32_e32 v157, 0xbfb8aa3b, v10
	v_exp_f32_e32 v159, v157
	v_rcp_f32_e32 v157, v138
	v_add_f32_e32 v138, 1.0, v158
	v_rcp_f32_e32 v158, v138
	v_add_f32_e32 v138, 1.0, v159
	v_mul_f32_e32 v159, 0xbfb8aa3b, v15
	v_exp_f32_e32 v159, v159
	v_rcp_f32_e32 v160, v138
	s_mov_b64 s[28:29], 0
	v_add_f32_e32 v138, 1.0, v159
	v_rcp_f32_e32 v159, v138
	v_add_f32_e32 v138, 1.0, v161
	v_rcp_f32_e32 v161, v138

.LBB0_890:
	v_add_u32_e32 v138, 0xb0, v172
	v_mov_b64_e32 v[162:163], s[2:3]
	v_mad_i64_i32 v[162:163], s[28:29], v138, s75, v[162:163]
	v_lshl_add_u64 v[152:153], v[152:153], 1, v[162:163]
	v_cvt_pk_bf16_f32 v154, v154, v155
	v_cvt_pk_bf16_f32 v155, v158, v159
	v_cvt_pk_bf16_f32 v156, v156, v157
	v_cvt_pk_bf16_f32 v157, v160, v161
	s_cmp_gt_i32 s15, 1
	s_mov_b64 s[28:29], -1
	ds_bpermute_b32 v250, v254, v154
	ds_bpermute_b32 v251, v254, v155
	ds_bpermute_b32 v252, v254, v156
	ds_bpermute_b32 v253, v254, v157
	ds_bpermute_b32 v248, v254, v152
	ds_bpermute_b32 v249, v254, v153
	s_waitcnt lgkmcnt(0)
	global_store_dwordx4 v[248:249], v[250:253], off
	s_cbranch_scc0 .LBB0_892
	v_mul_f32_e32 v138, 0xbfb8aa3b, v4
	v_exp_f32_e32 v138, v138
	v_mul_f32_e32 v154, 0xbfb8aa3b, v0
	v_exp_f32_e32 v154, v154
	v_mul_f32_e32 v156, 0xbfb8aa3b, v1
	v_add_f32_e32 v138, 1.0, v138
	v_exp_f32_e32 v157, v156
	v_add_f32_e32 v155, 1.0, v154
	v_rcp_f32_e32 v154, v138
	v_mul_f32_e32 v138, 0xbfb8aa3b, v5
	v_exp_f32_e32 v138, v138
	v_rcp_f32_e32 v156, v155
	v_mul_f32_e32 v160, 0xbfb8aa3b, v3
	v_exp_f32_e32 v161, v160
	v_add_f32_e32 v138, 1.0, v138
	v_rcp_f32_e32 v155, v138
	v_add_f32_e32 v138, 1.0, v157
	v_mul_f32_e32 v157, 0xbfb8aa3b, v6
	v_exp_f32_e32 v158, v157
	v_mul_f32_e32 v157, 0xbfb8aa3b, v2
	v_exp_f32_e32 v159, v157
	v_rcp_f32_e32 v157, v138
	v_add_f32_e32 v138, 1.0, v158
	v_rcp_f32_e32 v158, v138
	v_add_f32_e32 v138, 1.0, v159
	v_mul_f32_e32 v159, 0xbfb8aa3b, v7
	v_exp_f32_e32 v159, v159
	v_rcp_f32_e32 v160, v138
	s_mov_b64 s[28:29], 0
	v_add_f32_e32 v138, 1.0, v159
	v_rcp_f32_e32 v159, v138
	v_add_f32_e32 v138, 1.0, v161
	v_rcp_f32_e32 v161, v138

.LBB0_895:
	v_cvt_pk_bf16_f32 v154, v154, v155
	v_cvt_pk_bf16_f32 v155, v158, v159
	v_cvt_pk_bf16_f32 v156, v156, v157
	v_cvt_pk_bf16_f32 v157, v160, v161
	ds_bpermute_b32 v238, v254, v154
	ds_bpermute_b32 v239, v254, v155
	ds_bpermute_b32 v240, v254, v156
	ds_bpermute_b32 v241, v254, v157
	ds_bpermute_b32 v236, v254, v152
	ds_bpermute_b32 v237, v254, v153
	s_waitcnt lgkmcnt(0)
	global_store_dwordx4 v[236:237], v[238:241], off offset:256
	s_branch .LBB0_814
.LBB0_896:
	v_and_b32_e32 v138, 0xfcf, v172
	v_cmp_gt_i32_e32 vcc, s65, v172
	s_lshl_b32 s15, s13, 1
	s_lshl_b32 s17, s13, 8
	v_cndmask_b32_e32 v138, v166, v138, vcc
	v_lshlrev_b32_e32 v138, 8, v138
	v_lshl_add_u64 v[152:153], v[142:143], 0, v[138:139]
	global_load_dwordx4 v[156:159], v[152:153], off
	global_load_dwordx4 v[160:163], v[152:153], off offset:16
	v_lshl_add_u64 v[152:153], v[140:141], 0, v[138:139]
	global_load_dwordx4 v[174:177], v[152:153], off
	global_load_dwordx4 v[178:181], v[152:153], off offset:16
	s_and_b32 s15, s15, 6
	v_mov_b64_e32 v[152:153], s[2:3]
	v_or_b32_e32 v155, 16, v172
	s_movk_i32 s28, 0xfdf
	s_and_b32 s17, s17, 0x400
	s_or_b32 s15, s15, s70
	v_bitop3_b32 v138, v172, s28, 16 bitop3:0xc8
	v_mad_i64_i32 v[184:185], s[28:29], v172, s75, v[152:153]
	v_cmp_gt_i32_e32 vcc, s65, v155
	s_cmp_lt_u32 s13, 4
	v_or_b32_e32 v154, s17, v165
	v_cndmask_b32_e32 v138, v166, v138, vcc
	s_cselect_b64 s[28:29], -1, 0
	v_lshlrev_b32_e32 v182, 8, v138
	v_lshlrev_b32_e32 v138, 1, v154
	v_cndmask_b32_e64 v154, v171, 1.0, s[28:29]
	v_pk_mul_f32 v[118:119], v[154:155], v[118:119] op_sel_hi:[0,1]
	v_pk_mul_f32 v[116:117], v[154:155], v[116:117] op_sel_hi:[0,1]
	v_pk_mul_f32 v[114:115], v[154:155], v[114:115] op_sel_hi:[0,1]
	v_pk_mul_f32 v[112:113], v[154:155], v[112:113] op_sel_hi:[0,1]
	v_pk_mul_f32 v[126:127], v[154:155], v[126:127] op_sel_hi:[0,1]
	v_pk_mul_f32 v[124:125], v[154:155], v[124:125] op_sel_hi:[0,1]
	v_pk_mul_f32 v[122:123], v[154:155], v[122:123] op_sel_hi:[0,1]
	v_pk_mul_f32 v[120:121], v[154:155], v[120:121] op_sel_hi:[0,1]
	v_lshl_or_b32 v138, s15, 8, v138
	v_mov_b32_e32 v183, v139
	v_lshl_add_u64 v[184:185], v[184:185], 0, v[138:139]
	v_lshl_add_u64 v[186:187], v[142:143], 0, v[182:183]
	v_or_b32_e32 v173, 32, v172
	s_movk_i32 s13, 0xfef
	v_cmp_gt_i32_e32 vcc, s65, v173
	s_waitcnt vmcnt(0)
	v_pk_mul_f32 v[188:189], v[118:119], v[158:159]
	v_pk_mul_f32 v[190:191], v[116:117], v[156:157]
	v_pk_mul_f32 v[192:193], v[114:115], v[162:163]
	v_pk_mul_f32 v[194:195], v[112:113], v[160:161]
	v_pk_mul_f32 v[158:159], v[126:127], v[158:159]
	v_pk_mul_f32 v[156:157], v[124:125], v[156:157]
	v_pk_mul_f32 v[162:163], v[122:123], v[162:163]
	v_pk_mul_f32 v[160:161], v[120:121], v[160:161]
	v_pk_fma_f32 v[126:127], v[126:127], v[176:177], v[188:189] neg_lo:[0,0,1] neg_hi:[0,0,1]
	v_pk_fma_f32 v[124:125], v[124:125], v[174:175], v[190:191] neg_lo:[0,0,1] neg_hi:[0,0,1]
	v_pk_fma_f32 v[122:123], v[122:123], v[180:181], v[192:193] neg_lo:[0,0,1] neg_hi:[0,0,1]
	v_pk_fma_f32 v[120:121], v[120:121], v[178:179], v[194:195] neg_lo:[0,0,1] neg_hi:[0,0,1]
	v_pk_fma_f32 v[118:119], v[118:119], v[176:177], v[158:159]
	v_pk_fma_f32 v[116:117], v[116:117], v[174:175], v[156:157]
	v_pk_fma_f32 v[156:157], v[114:115], v[180:181], v[162:163]
	v_pk_fma_f32 v[158:159], v[112:113], v[178:179], v[160:161]
	v_cvt_pk_bf16_f32 v112, v124, v125
	v_cvt_pk_bf16_f32 v113, v126, v127
	v_cvt_pk_bf16_f32 v114, v120, v121
	v_cvt_pk_bf16_f32 v115, v122, v123
	v_cvt_pk_bf16_f32 v116, v116, v117
	v_cvt_pk_bf16_f32 v117, v118, v119
	v_cvt_pk_bf16_f32 v118, v158, v159
	v_cvt_pk_bf16_f32 v119, v156, v157
	ds_bpermute_b32 v244, v254, v112
	ds_bpermute_b32 v245, v254, v113
	ds_bpermute_b32 v246, v254, v114
	ds_bpermute_b32 v247, v254, v115
	ds_bpermute_b32 v242, v254, v184
	ds_bpermute_b32 v243, v254, v185
	ds_bpermute_b32 v250, v254, v116
	ds_bpermute_b32 v251, v254, v117
	ds_bpermute_b32 v252, v254, v118
	ds_bpermute_b32 v253, v254, v119
	ds_bpermute_b32 v248, v254, v184
	ds_bpermute_b32 v249, v254, v185
	global_load_dwordx4 v[112:115], v[186:187], off
	s_nop 0
	global_load_dwordx4 v[116:119], v[186:187], off offset:16
	v_lshl_add_u64 v[124:125], v[140:141], 0, v[182:183]
	global_load_dwordx4 v[120:123], v[124:125], off
	s_nop 0
	global_load_dwordx4 v[124:127], v[124:125], off offset:16
	v_bitop3_b32 v156, v172, s13, 32 bitop3:0xc8
	v_mad_i64_i32 v[158:159], s[28:29], v155, s75, v[152:153]
	v_cndmask_b32_e32 v155, v166, v156, vcc
	v_pk_mul_f32 v[102:103], v[154:155], v[102:103] op_sel_hi:[0,1]
	v_pk_mul_f32 v[100:101], v[154:155], v[100:101] op_sel_hi:[0,1]
	v_pk_mul_f32 v[98:99], v[154:155], v[98:99] op_sel_hi:[0,1]
	v_pk_mul_f32 v[96:97], v[154:155], v[96:97] op_sel_hi:[0,1]
	v_pk_mul_f32 v[110:111], v[154:155], v[110:111] op_sel_hi:[0,1]
	v_pk_mul_f32 v[108:109], v[154:155], v[108:109] op_sel_hi:[0,1]
	v_pk_mul_f32 v[106:107], v[154:155], v[106:107] op_sel_hi:[0,1]
	v_pk_mul_f32 v[104:105], v[154:155], v[104:105] op_sel_hi:[0,1]
	v_mov_b32_e32 v157, v139
	v_lshlrev_b32_e32 v156, 8, v155
	v_lshl_add_u64 v[158:159], v[158:159], 0, v[138:139]
	v_lshl_add_u64 v[160:161], v[142:143], 0, v[156:157]
	s_movk_i32 s13, 0xfff
	v_pk_mul_f32 v[86:87], v[154:155], v[86:87] op_sel_hi:[0,1]
	v_pk_mul_f32 v[84:85], v[154:155], v[84:85] op_sel_hi:[0,1]
	v_pk_mul_f32 v[82:83], v[154:155], v[82:83] op_sel_hi:[0,1]
	v_pk_mul_f32 v[80:81], v[154:155], v[80:81] op_sel_hi:[0,1]
	v_pk_mul_f32 v[94:95], v[154:155], v[94:95] op_sel_hi:[0,1]
	v_pk_mul_f32 v[92:93], v[154:155], v[92:93] op_sel_hi:[0,1]
	v_pk_mul_f32 v[90:91], v[154:155], v[90:91] op_sel_hi:[0,1]
	v_pk_mul_f32 v[88:89], v[154:155], v[88:89] op_sel_hi:[0,1]
	v_pk_mul_f32 v[70:71], v[154:155], v[70:71] op_sel_hi:[0,1]
	v_pk_mul_f32 v[68:69], v[154:155], v[68:69] op_sel_hi:[0,1]
	v_pk_mul_f32 v[66:67], v[154:155], v[66:67] op_sel_hi:[0,1]
	v_pk_mul_f32 v[64:65], v[154:155], v[64:65] op_sel_hi:[0,1]
	v_pk_mul_f32 v[78:79], v[154:155], v[78:79] op_sel_hi:[0,1]
	v_pk_mul_f32 v[76:77], v[154:155], v[76:77] op_sel_hi:[0,1]
	v_pk_mul_f32 v[74:75], v[154:155], v[74:75] op_sel_hi:[0,1]
	v_pk_mul_f32 v[72:73], v[154:155], v[72:73] op_sel_hi:[0,1]
	v_pk_mul_f32 v[54:55], v[154:155], v[54:55] op_sel_hi:[0,1]
	v_pk_mul_f32 v[52:53], v[154:155], v[52:53] op_sel_hi:[0,1]
	v_pk_mul_f32 v[50:51], v[154:155], v[50:51] op_sel_hi:[0,1]
	v_pk_mul_f32 v[48:49], v[154:155], v[48:49] op_sel_hi:[0,1]
	v_pk_mul_f32 v[62:63], v[154:155], v[62:63] op_sel_hi:[0,1]
	v_pk_mul_f32 v[60:61], v[154:155], v[60:61] op_sel_hi:[0,1]
	v_pk_mul_f32 v[58:59], v[154:155], v[58:59] op_sel_hi:[0,1]
	v_pk_mul_f32 v[56:57], v[154:155], v[56:57] op_sel_hi:[0,1]
	v_pk_mul_f32 v[38:39], v[154:155], v[38:39] op_sel_hi:[0,1]
	v_pk_mul_f32 v[36:37], v[154:155], v[36:37] op_sel_hi:[0,1]
	v_pk_mul_f32 v[34:35], v[154:155], v[34:35] op_sel_hi:[0,1]
	v_pk_mul_f32 v[32:33], v[154:155], v[32:33] op_sel_hi:[0,1]
	v_pk_mul_f32 v[46:47], v[154:155], v[46:47] op_sel_hi:[0,1]
	v_pk_mul_f32 v[44:45], v[154:155], v[44:45] op_sel_hi:[0,1]
	v_pk_mul_f32 v[42:43], v[154:155], v[42:43] op_sel_hi:[0,1]
	v_pk_mul_f32 v[40:41], v[154:155], v[40:41] op_sel_hi:[0,1]
	v_pk_mul_f32 v[22:23], v[154:155], v[22:23] op_sel_hi:[0,1]
	v_pk_mul_f32 v[20:21], v[154:155], v[20:21] op_sel_hi:[0,1]
	v_pk_mul_f32 v[18:19], v[154:155], v[18:19] op_sel_hi:[0,1]
	v_pk_mul_f32 v[16:17], v[154:155], v[16:17] op_sel_hi:[0,1]
	v_pk_mul_f32 v[30:31], v[154:155], v[30:31] op_sel_hi:[0,1]
	v_pk_mul_f32 v[28:29], v[154:155], v[28:29] op_sel_hi:[0,1]
	v_pk_mul_f32 v[26:27], v[154:155], v[26:27] op_sel_hi:[0,1]
	v_pk_mul_f32 v[24:25], v[154:155], v[24:25] op_sel_hi:[0,1]
	v_pk_mul_f32 v[6:7], v[154:155], v[6:7] op_sel_hi:[0,1]
	v_pk_mul_f32 v[4:5], v[154:155], v[4:5] op_sel_hi:[0,1]
	v_pk_mul_f32 v[2:3], v[154:155], v[2:3] op_sel_hi:[0,1]
	v_pk_mul_f32 v[0:1], v[154:155], v[0:1] op_sel_hi:[0,1]
	v_pk_mul_f32 v[14:15], v[154:155], v[14:15] op_sel_hi:[0,1]
	v_pk_mul_f32 v[12:13], v[154:155], v[12:13] op_sel_hi:[0,1]
	v_pk_mul_f32 v[10:11], v[154:155], v[10:11] op_sel_hi:[0,1]
	v_pk_mul_f32 v[8:9], v[154:155], v[8:9] op_sel_hi:[0,1]
	s_waitcnt lgkmcnt(6)
	global_store_dwordx4 v[242:243], v[244:247], off offset:3072
	s_waitcnt lgkmcnt(0)
	global_store_dwordx4 v[248:249], v[250:253], off offset:3200
	s_waitcnt vmcnt(3)
	v_pk_mul_f32 v[162:163], v[102:103], v[114:115]
	v_pk_mul_f32 v[174:175], v[100:101], v[112:113]
	s_waitcnt vmcnt(2)
	v_pk_mul_f32 v[176:177], v[98:99], v[118:119]
	v_pk_mul_f32 v[178:179], v[96:97], v[116:117]
	v_pk_mul_f32 v[114:115], v[110:111], v[114:115]
	v_pk_mul_f32 v[112:113], v[108:109], v[112:113]
	v_pk_mul_f32 v[118:119], v[106:107], v[118:119]
	v_pk_mul_f32 v[116:117], v[104:105], v[116:117]
	s_waitcnt vmcnt(1)
	v_pk_fma_f32 v[110:111], v[110:111], v[122:123], v[162:163] neg_lo:[0,0,1] neg_hi:[0,0,1]
	v_pk_fma_f32 v[108:109], v[108:109], v[120:121], v[174:175] neg_lo:[0,0,1] neg_hi:[0,0,1]
	s_waitcnt vmcnt(0)
	v_pk_fma_f32 v[106:107], v[106:107], v[126:127], v[176:177] neg_lo:[0,0,1] neg_hi:[0,0,1]
	v_pk_fma_f32 v[104:105], v[104:105], v[124:125], v[178:179] neg_lo:[0,0,1] neg_hi:[0,0,1]
	v_pk_fma_f32 v[102:103], v[102:103], v[122:123], v[114:115]
	v_pk_fma_f32 v[100:101], v[100:101], v[120:121], v[112:113]
	v_pk_fma_f32 v[112:113], v[98:99], v[126:127], v[118:119]
	v_pk_fma_f32 v[114:115], v[96:97], v[124:125], v[116:117]
	v_cvt_pk_bf16_f32 v96, v108, v109
	v_cvt_pk_bf16_f32 v97, v110, v111
	v_cvt_pk_bf16_f32 v98, v104, v105
	v_cvt_pk_bf16_f32 v99, v106, v107
	v_cvt_pk_bf16_f32 v100, v100, v101
	v_cvt_pk_bf16_f32 v101, v102, v103
	v_cvt_pk_bf16_f32 v102, v114, v115
	v_cvt_pk_bf16_f32 v103, v112, v113
	ds_bpermute_b32 v238, v254, v96
	ds_bpermute_b32 v239, v254, v97
	ds_bpermute_b32 v240, v254, v98
	ds_bpermute_b32 v241, v254, v99
	ds_bpermute_b32 v236, v254, v158
	ds_bpermute_b32 v237, v254, v159
	ds_bpermute_b32 v244, v254, v100
	ds_bpermute_b32 v245, v254, v101
	ds_bpermute_b32 v246, v254, v102
	ds_bpermute_b32 v247, v254, v103
	ds_bpermute_b32 v242, v254, v158
	ds_bpermute_b32 v243, v254, v159
	global_load_dwordx4 v[96:99], v[160:161], off
	s_nop 0
	global_load_dwordx4 v[100:103], v[160:161], off offset:16
	v_lshl_add_u64 v[108:109], v[140:141], 0, v[156:157]
	global_load_dwordx4 v[104:107], v[108:109], off
	s_nop 0
	global_load_dwordx4 v[108:111], v[108:109], off offset:16
	v_or_b32_e32 v126, 48, v172
	v_bitop3_b32 v112, v172, s13, 48 bitop3:0xc8
	v_cmp_gt_i32_e32 vcc, s65, v126
	v_mad_i64_i32 v[114:115], s[28:29], v173, s75, v[152:153]
	s_nop 0
	v_cndmask_b32_e32 v112, v166, v112, vcc
	v_mov_b32_e32 v113, v139
	v_lshlrev_b32_e32 v112, 8, v112
	v_lshl_add_u64 v[114:115], v[114:115], 0, v[138:139]
	v_lshl_add_u64 v[116:117], v[142:143], 0, v[112:113]
	v_cmp_gt_i32_e32 vcc, s76, v172
	s_waitcnt lgkmcnt(6)
	global_store_dwordx4 v[236:237], v[238:241], off offset:3072
	s_waitcnt lgkmcnt(0)
	global_store_dwordx4 v[242:243], v[244:247], off offset:3200
	s_waitcnt vmcnt(3)
	v_pk_mul_f32 v[118:119], v[86:87], v[98:99]
	v_pk_mul_f32 v[120:121], v[84:85], v[96:97]
	s_waitcnt vmcnt(2)
	v_pk_mul_f32 v[122:123], v[82:83], v[102:103]
	v_pk_mul_f32 v[124:125], v[80:81], v[100:101]
	v_pk_mul_f32 v[98:99], v[94:95], v[98:99]
	v_pk_mul_f32 v[96:97], v[92:93], v[96:97]
	v_pk_mul_f32 v[102:103], v[90:91], v[102:103]
	v_pk_mul_f32 v[100:101], v[88:89], v[100:101]
	s_waitcnt vmcnt(1)
	v_pk_fma_f32 v[94:95], v[94:95], v[106:107], v[118:119] neg_lo:[0,0,1] neg_hi:[0,0,1]
	v_pk_fma_f32 v[92:93], v[92:93], v[104:105], v[120:121] neg_lo:[0,0,1] neg_hi:[0,0,1]
	s_waitcnt vmcnt(0)
	v_pk_fma_f32 v[90:91], v[90:91], v[110:111], v[122:123] neg_lo:[0,0,1] neg_hi:[0,0,1]
	v_pk_fma_f32 v[88:89], v[88:89], v[108:109], v[124:125] neg_lo:[0,0,1] neg_hi:[0,0,1]
	v_pk_fma_f32 v[86:87], v[86:87], v[106:107], v[98:99]
	v_pk_fma_f32 v[84:85], v[84:85], v[104:105], v[96:97]
	v_pk_fma_f32 v[96:97], v[82:83], v[110:111], v[102:103]
	v_pk_fma_f32 v[98:99], v[80:81], v[108:109], v[100:101]
	v_cvt_pk_bf16_f32 v80, v92, v93
	v_cvt_pk_bf16_f32 v81, v94, v95
	v_cvt_pk_bf16_f32 v82, v88, v89
	v_cvt_pk_bf16_f32 v83, v90, v91
	v_cvt_pk_bf16_f32 v84, v84, v85
	v_cvt_pk_bf16_f32 v85, v86, v87
	v_cvt_pk_bf16_f32 v86, v98, v99
	v_cvt_pk_bf16_f32 v87, v96, v97
	ds_bpermute_b32 v250, v254, v80
	ds_bpermute_b32 v251, v254, v81
	ds_bpermute_b32 v252, v254, v82
	ds_bpermute_b32 v253, v254, v83
	ds_bpermute_b32 v248, v254, v114
	ds_bpermute_b32 v249, v254, v115
	ds_bpermute_b32 v238, v254, v84
	ds_bpermute_b32 v239, v254, v85
	ds_bpermute_b32 v240, v254, v86
	ds_bpermute_b32 v241, v254, v87
	ds_bpermute_b32 v236, v254, v114
	ds_bpermute_b32 v237, v254, v115
	global_load_dwordx4 v[80:83], v[116:117], off
	s_nop 0
	global_load_dwordx4 v[84:87], v[116:117], off offset:16
	v_lshl_add_u64 v[92:93], v[140:141], 0, v[112:113]
	global_load_dwordx4 v[88:91], v[92:93], off
	s_nop 0
	global_load_dwordx4 v[92:95], v[92:93], off offset:16
	v_add_u32_e32 v110, 0x80, v172
	v_and_b32_e32 v96, 0xfcf, v110
	v_mad_i64_i32 v[98:99], s[28:29], v126, s75, v[152:153]
	v_cndmask_b32_e32 v96, v166, v96, vcc
	v_mov_b32_e32 v97, v139
	v_lshlrev_b32_e32 v96, 8, v96
	v_lshl_add_u64 v[98:99], v[98:99], 0, v[138:139]
	v_lshl_add_u64 v[100:101], v[142:143], 0, v[96:97]
	v_cmp_gt_i32_e32 vcc, s77, v172
	s_waitcnt lgkmcnt(6)
	global_store_dwordx4 v[248:249], v[250:253], off offset:3072
	s_waitcnt lgkmcnt(0)
	global_store_dwordx4 v[236:237], v[238:241], off offset:3200
	s_waitcnt vmcnt(3)
	v_pk_mul_f32 v[102:103], v[70:71], v[82:83]
	v_pk_mul_f32 v[104:105], v[68:69], v[80:81]
	s_waitcnt vmcnt(2)
	v_pk_mul_f32 v[106:107], v[66:67], v[86:87]
	v_pk_mul_f32 v[108:109], v[64:65], v[84:85]
	v_pk_mul_f32 v[82:83], v[78:79], v[82:83]
	v_pk_mul_f32 v[80:81], v[76:77], v[80:81]
	v_pk_mul_f32 v[86:87], v[74:75], v[86:87]
	v_pk_mul_f32 v[84:85], v[72:73], v[84:85]
	s_waitcnt vmcnt(1)
	v_pk_fma_f32 v[78:79], v[78:79], v[90:91], v[102:103] neg_lo:[0,0,1] neg_hi:[0,0,1]
	v_pk_fma_f32 v[76:77], v[76:77], v[88:89], v[104:105] neg_lo:[0,0,1] neg_hi:[0,0,1]
	s_waitcnt vmcnt(0)
	v_pk_fma_f32 v[74:75], v[74:75], v[94:95], v[106:107] neg_lo:[0,0,1] neg_hi:[0,0,1]
	v_pk_fma_f32 v[72:73], v[72:73], v[92:93], v[108:109] neg_lo:[0,0,1] neg_hi:[0,0,1]
	v_pk_fma_f32 v[70:71], v[70:71], v[90:91], v[82:83]
	v_pk_fma_f32 v[68:69], v[68:69], v[88:89], v[80:81]
	v_pk_fma_f32 v[80:81], v[66:67], v[94:95], v[86:87]
	v_pk_fma_f32 v[82:83], v[64:65], v[92:93], v[84:85]
	v_cvt_pk_bf16_f32 v64, v76, v77
	v_cvt_pk_bf16_f32 v65, v78, v79
	v_cvt_pk_bf16_f32 v66, v72, v73
	v_cvt_pk_bf16_f32 v67, v74, v75
	v_cvt_pk_bf16_f32 v68, v68, v69
	v_cvt_pk_bf16_f32 v69, v70, v71
	v_cvt_pk_bf16_f32 v70, v82, v83
	v_cvt_pk_bf16_f32 v71, v80, v81
	ds_bpermute_b32 v244, v254, v64
	ds_bpermute_b32 v245, v254, v65
	ds_bpermute_b32 v246, v254, v66
	ds_bpermute_b32 v247, v254, v67
	ds_bpermute_b32 v242, v254, v98
	ds_bpermute_b32 v243, v254, v99
	ds_bpermute_b32 v250, v254, v68
	ds_bpermute_b32 v251, v254, v69
	ds_bpermute_b32 v252, v254, v70
	ds_bpermute_b32 v253, v254, v71
	ds_bpermute_b32 v248, v254, v98
	ds_bpermute_b32 v249, v254, v99
	global_load_dwordx4 v[64:67], v[100:101], off
	s_nop 0
	global_load_dwordx4 v[68:71], v[100:101], off offset:16
	v_lshl_add_u64 v[76:77], v[140:141], 0, v[96:97]
	global_load_dwordx4 v[72:75], v[76:77], off
	s_nop 0
	global_load_dwordx4 v[76:79], v[76:77], off offset:16
	v_add_u32_e32 v94, 0x90, v172
	v_and_b32_e32 v80, 0xfdf, v94
	v_mad_i64_i32 v[82:83], s[28:29], v110, s75, v[152:153]
	v_cndmask_b32_e32 v80, v166, v80, vcc
	v_mov_b32_e32 v81, v139
	v_lshlrev_b32_e32 v80, 8, v80
	v_lshl_add_u64 v[82:83], v[82:83], 0, v[138:139]
	v_lshl_add_u64 v[84:85], v[142:143], 0, v[80:81]
	v_cmp_gt_i32_e32 vcc, s78, v172
	s_waitcnt lgkmcnt(6)
	global_store_dwordx4 v[242:243], v[244:247], off offset:3072
	s_waitcnt lgkmcnt(0)
	global_store_dwordx4 v[248:249], v[250:253], off offset:3200
	s_waitcnt vmcnt(3)
	v_pk_mul_f32 v[86:87], v[54:55], v[66:67]
	v_pk_mul_f32 v[88:89], v[52:53], v[64:65]
	s_waitcnt vmcnt(2)
	v_pk_mul_f32 v[90:91], v[50:51], v[70:71]
	v_pk_mul_f32 v[92:93], v[48:49], v[68:69]
	v_pk_mul_f32 v[66:67], v[62:63], v[66:67]
	v_pk_mul_f32 v[64:65], v[60:61], v[64:65]
	v_pk_mul_f32 v[70:71], v[58:59], v[70:71]
	v_pk_mul_f32 v[68:69], v[56:57], v[68:69]
	s_waitcnt vmcnt(1)
	v_pk_fma_f32 v[62:63], v[62:63], v[74:75], v[86:87] neg_lo:[0,0,1] neg_hi:[0,0,1]
	v_pk_fma_f32 v[60:61], v[60:61], v[72:73], v[88:89] neg_lo:[0,0,1] neg_hi:[0,0,1]
	s_waitcnt vmcnt(0)
	v_pk_fma_f32 v[58:59], v[58:59], v[78:79], v[90:91] neg_lo:[0,0,1] neg_hi:[0,0,1]
	v_pk_fma_f32 v[56:57], v[56:57], v[76:77], v[92:93] neg_lo:[0,0,1] neg_hi:[0,0,1]
	v_pk_fma_f32 v[54:55], v[54:55], v[74:75], v[66:67]
	v_pk_fma_f32 v[52:53], v[52:53], v[72:73], v[64:65]
	v_pk_fma_f32 v[64:65], v[50:51], v[78:79], v[70:71]
	v_pk_fma_f32 v[66:67], v[48:49], v[76:77], v[68:69]
	v_cvt_pk_bf16_f32 v48, v60, v61
	v_cvt_pk_bf16_f32 v49, v62, v63
	v_cvt_pk_bf16_f32 v50, v56, v57
	v_cvt_pk_bf16_f32 v51, v58, v59
	v_cvt_pk_bf16_f32 v52, v52, v53
	v_cvt_pk_bf16_f32 v53, v54, v55
	v_cvt_pk_bf16_f32 v54, v66, v67
	v_cvt_pk_bf16_f32 v55, v64, v65
	ds_bpermute_b32 v238, v254, v48
	ds_bpermute_b32 v239, v254, v49
	ds_bpermute_b32 v240, v254, v50
	ds_bpermute_b32 v241, v254, v51
	ds_bpermute_b32 v236, v254, v82
	ds_bpermute_b32 v237, v254, v83
	ds_bpermute_b32 v244, v254, v52
	ds_bpermute_b32 v245, v254, v53
	ds_bpermute_b32 v246, v254, v54
	ds_bpermute_b32 v247, v254, v55
	ds_bpermute_b32 v242, v254, v82
	ds_bpermute_b32 v243, v254, v83
	global_load_dwordx4 v[48:51], v[84:85], off
	s_nop 0
	global_load_dwordx4 v[52:55], v[84:85], off offset:16
	v_lshl_add_u64 v[60:61], v[140:141], 0, v[80:81]
	global_load_dwordx4 v[56:59], v[60:61], off
	s_nop 0
	global_load_dwordx4 v[60:63], v[60:61], off offset:16
	v_add_u32_e32 v78, 0xa0, v172
	v_and_b32_e32 v64, 0xfef, v78
	v_mad_i64_i32 v[66:67], s[28:29], v94, s75, v[152:153]
	v_cndmask_b32_e32 v64, v166, v64, vcc
	v_mov_b32_e32 v65, v139
	v_lshlrev_b32_e32 v64, 8, v64
	v_lshl_add_u64 v[66:67], v[66:67], 0, v[138:139]
	v_lshl_add_u64 v[68:69], v[142:143], 0, v[64:65]
	v_cmp_gt_i32_e32 vcc, s79, v172
	s_waitcnt lgkmcnt(6)
	global_store_dwordx4 v[236:237], v[238:241], off offset:3072
	s_waitcnt lgkmcnt(0)
	global_store_dwordx4 v[242:243], v[244:247], off offset:3200
	s_waitcnt vmcnt(3)
	v_pk_mul_f32 v[70:71], v[38:39], v[50:51]
	v_pk_mul_f32 v[72:73], v[36:37], v[48:49]
	s_waitcnt vmcnt(2)
	v_pk_mul_f32 v[74:75], v[34:35], v[54:55]
	v_pk_mul_f32 v[76:77], v[32:33], v[52:53]
	v_pk_mul_f32 v[50:51], v[46:47], v[50:51]
	v_pk_mul_f32 v[48:49], v[44:45], v[48:49]
	v_pk_mul_f32 v[54:55], v[42:43], v[54:55]
	v_pk_mul_f32 v[52:53], v[40:41], v[52:53]
	s_waitcnt vmcnt(1)
	v_pk_fma_f32 v[46:47], v[46:47], v[58:59], v[70:71] neg_lo:[0,0,1] neg_hi:[0,0,1]
	v_pk_fma_f32 v[44:45], v[44:45], v[56:57], v[72:73] neg_lo:[0,0,1] neg_hi:[0,0,1]
	s_waitcnt vmcnt(0)
	v_pk_fma_f32 v[42:43], v[42:43], v[62:63], v[74:75] neg_lo:[0,0,1] neg_hi:[0,0,1]
	v_pk_fma_f32 v[40:41], v[40:41], v[60:61], v[76:77] neg_lo:[0,0,1] neg_hi:[0,0,1]
	v_pk_fma_f32 v[38:39], v[38:39], v[58:59], v[50:51]
	v_pk_fma_f32 v[36:37], v[36:37], v[56:57], v[48:49]
	v_pk_fma_f32 v[48:49], v[34:35], v[62:63], v[54:55]
	v_pk_fma_f32 v[50:51], v[32:33], v[60:61], v[52:53]
	v_cvt_pk_bf16_f32 v32, v44, v45
	v_cvt_pk_bf16_f32 v33, v46, v47
	v_cvt_pk_bf16_f32 v34, v40, v41
	v_cvt_pk_bf16_f32 v35, v42, v43
	v_cvt_pk_bf16_f32 v36, v36, v37
	v_cvt_pk_bf16_f32 v37, v38, v39
	v_cvt_pk_bf16_f32 v38, v50, v51
	v_cvt_pk_bf16_f32 v39, v48, v49
	ds_bpermute_b32 v250, v254, v32
	ds_bpermute_b32 v251, v254, v33
	ds_bpermute_b32 v252, v254, v34
	ds_bpermute_b32 v253, v254, v35
	ds_bpermute_b32 v248, v254, v66
	ds_bpermute_b32 v249, v254, v67
	ds_bpermute_b32 v238, v254, v36
	ds_bpermute_b32 v239, v254, v37
	ds_bpermute_b32 v240, v254, v38
	ds_bpermute_b32 v241, v254, v39
	ds_bpermute_b32 v236, v254, v66
	ds_bpermute_b32 v237, v254, v67
	global_load_dwordx4 v[32:35], v[68:69], off
	s_nop 0
	global_load_dwordx4 v[36:39], v[68:69], off offset:16
	v_lshl_add_u64 v[44:45], v[140:141], 0, v[64:65]
	global_load_dwordx4 v[40:43], v[44:45], off
	s_nop 0
	global_load_dwordx4 v[44:47], v[44:45], off offset:16
	v_add_u32_e32 v62, 0xb0, v172
	v_and_b32_e32 v48, 0xfff, v62
	v_mad_i64_i32 v[50:51], s[28:29], v78, s75, v[152:153]
	v_cndmask_b32_e32 v48, v166, v48, vcc
	v_mov_b32_e32 v49, v139
	v_lshlrev_b32_e32 v48, 8, v48
	v_lshl_add_u64 v[50:51], v[50:51], 0, v[138:139]
	v_lshl_add_u64 v[52:53], v[142:143], 0, v[48:49]
	s_waitcnt lgkmcnt(6)
	global_store_dwordx4 v[248:249], v[250:253], off offset:3072
	s_waitcnt lgkmcnt(0)
	global_store_dwordx4 v[236:237], v[238:241], off offset:3200
	s_waitcnt vmcnt(3)
	v_pk_mul_f32 v[54:55], v[22:23], v[34:35]
	v_pk_mul_f32 v[56:57], v[20:21], v[32:33]
	s_waitcnt vmcnt(2)
	v_pk_mul_f32 v[58:59], v[18:19], v[38:39]
	v_pk_mul_f32 v[60:61], v[16:17], v[36:37]
	v_pk_mul_f32 v[34:35], v[30:31], v[34:35]
	v_pk_mul_f32 v[32:33], v[28:29], v[32:33]
	v_pk_mul_f32 v[38:39], v[26:27], v[38:39]
	v_pk_mul_f32 v[36:37], v[24:25], v[36:37]
	s_waitcnt vmcnt(1)
	v_pk_fma_f32 v[30:31], v[30:31], v[42:43], v[54:55] neg_lo:[0,0,1] neg_hi:[0,0,1]
	v_pk_fma_f32 v[28:29], v[28:29], v[40:41], v[56:57] neg_lo:[0,0,1] neg_hi:[0,0,1]
	s_waitcnt vmcnt(0)
	v_pk_fma_f32 v[26:27], v[26:27], v[46:47], v[58:59] neg_lo:[0,0,1] neg_hi:[0,0,1]
	v_pk_fma_f32 v[24:25], v[24:25], v[44:45], v[60:61] neg_lo:[0,0,1] neg_hi:[0,0,1]
	v_pk_fma_f32 v[22:23], v[22:23], v[42:43], v[34:35]
	v_pk_fma_f32 v[20:21], v[20:21], v[40:41], v[32:33]
	v_pk_fma_f32 v[32:33], v[18:19], v[46:47], v[38:39]
	v_pk_fma_f32 v[34:35], v[16:17], v[44:45], v[36:37]
	v_cvt_pk_bf16_f32 v16, v28, v29
	v_cvt_pk_bf16_f32 v17, v30, v31
	v_cvt_pk_bf16_f32 v18, v24, v25
	v_cvt_pk_bf16_f32 v19, v26, v27
	v_cvt_pk_bf16_f32 v20, v20, v21
	v_cvt_pk_bf16_f32 v21, v22, v23
	v_cvt_pk_bf16_f32 v22, v34, v35
	v_cvt_pk_bf16_f32 v23, v32, v33
	ds_bpermute_b32 v244, v254, v16
	ds_bpermute_b32 v245, v254, v17
	ds_bpermute_b32 v246, v254, v18
	ds_bpermute_b32 v247, v254, v19
	ds_bpermute_b32 v242, v254, v50
	ds_bpermute_b32 v243, v254, v51
	ds_bpermute_b32 v250, v254, v20
	ds_bpermute_b32 v251, v254, v21
	ds_bpermute_b32 v252, v254, v22
	ds_bpermute_b32 v253, v254, v23
	ds_bpermute_b32 v248, v254, v50
	ds_bpermute_b32 v249, v254, v51
	global_load_dwordx4 v[16:19], v[52:53], off
	s_nop 0
	global_load_dwordx4 v[20:23], v[52:53], off offset:16
	v_lshl_add_u64 v[28:29], v[140:141], 0, v[48:49]
	global_load_dwordx4 v[24:27], v[28:29], off
	s_nop 0
	global_load_dwordx4 v[28:31], v[28:29], off offset:16
	v_mad_i64_i32 v[32:33], s[28:29], v62, s75, v[152:153]
	v_lshl_add_u64 v[32:33], v[32:33], 0, v[138:139]
	s_waitcnt lgkmcnt(6)
	global_store_dwordx4 v[242:243], v[244:247], off offset:3072
	s_waitcnt lgkmcnt(0)
	global_store_dwordx4 v[248:249], v[250:253], off offset:3200
	s_waitcnt vmcnt(3)
	v_pk_mul_f32 v[34:35], v[6:7], v[18:19]
	v_pk_mul_f32 v[36:37], v[4:5], v[16:17]
	s_waitcnt vmcnt(2)
	v_pk_mul_f32 v[38:39], v[2:3], v[22:23]
	v_pk_mul_f32 v[40:41], v[0:1], v[20:21]
	v_pk_mul_f32 v[18:19], v[14:15], v[18:19]
	v_pk_mul_f32 v[16:17], v[12:13], v[16:17]
	v_pk_mul_f32 v[22:23], v[10:11], v[22:23]
	v_pk_mul_f32 v[20:21], v[8:9], v[20:21]
	s_waitcnt vmcnt(1)
	v_pk_fma_f32 v[14:15], v[14:15], v[26:27], v[34:35] neg_lo:[0,0,1] neg_hi:[0,0,1]
	v_pk_fma_f32 v[12:13], v[12:13], v[24:25], v[36:37] neg_lo:[0,0,1] neg_hi:[0,0,1]
	s_waitcnt vmcnt(0)
	v_pk_fma_f32 v[10:11], v[10:11], v[30:31], v[38:39] neg_lo:[0,0,1] neg_hi:[0,0,1]
	v_pk_fma_f32 v[8:9], v[8:9], v[28:29], v[40:41] neg_lo:[0,0,1] neg_hi:[0,0,1]
	v_pk_fma_f32 v[6:7], v[6:7], v[26:27], v[18:19]
	v_pk_fma_f32 v[4:5], v[4:5], v[24:25], v[16:17]
	v_pk_fma_f32 v[16:17], v[2:3], v[30:31], v[22:23]
	v_pk_fma_f32 v[18:19], v[0:1], v[28:29], v[20:21]
	v_cvt_pk_bf16_f32 v0, v12, v13
	v_cvt_pk_bf16_f32 v1, v14, v15
	v_cvt_pk_bf16_f32 v2, v8, v9
	v_cvt_pk_bf16_f32 v3, v10, v11
	v_cvt_pk_bf16_f32 v4, v4, v5
	v_cvt_pk_bf16_f32 v5, v6, v7
	v_cvt_pk_bf16_f32 v6, v18, v19
	v_cvt_pk_bf16_f32 v7, v16, v17
	ds_bpermute_b32 v238, v254, v0
	ds_bpermute_b32 v239, v254, v1
	ds_bpermute_b32 v240, v254, v2
	ds_bpermute_b32 v241, v254, v3
	ds_bpermute_b32 v236, v254, v32
	ds_bpermute_b32 v237, v254, v33
	ds_bpermute_b32 v244, v254, v4
	ds_bpermute_b32 v245, v254, v5
	ds_bpermute_b32 v246, v254, v6
	ds_bpermute_b32 v247, v254, v7
	ds_bpermute_b32 v242, v254, v32
	ds_bpermute_b32 v243, v254, v33
	s_andn2_b64 vcc, exec, s[4:5]
	s_mov_b64 s[4:5], -1
	s_waitcnt lgkmcnt(6)
	global_store_dwordx4 v[236:237], v[238:241], off offset:3072
	s_waitcnt lgkmcnt(0)
	global_store_dwordx4 v[242:243], v[244:247], off offset:3200
	s_cbranch_vccnz .LBB0_805

.LBB0_1393:
	v_and_b32_e32 v254, 63, v128
	v_and_b32_e32 v255, 3, v254
	v_lshrrev_b32_e32 v254, 2, v254
	v_lshl_or_b32 v254, v255, 4, v254
	v_lshlrev_b32_e32 v254, 2, v254
	v_lshl_or_b32 v146, s30, 8, v157
	v_lshl_add_u32 v148, s52, 8, v129
	v_ashrrev_i32_e32 v147, 31, v146
	v_mov_b64_e32 v[150:151], s[8:9]
	v_mad_i64_i32 v[154:155], s[54:55], v148, s71, v[150:151]
	v_lshlrev_b64 v[152:153], 1, v[146:147]
	v_lshl_add_u64 v[154:155], v[154:155], 0, v[152:153]
	v_add_co_u32_e32 v162, vcc, 0x3000, v154
	v_or_b32_e32 v182, 16, v148
	s_nop 0
	v_addc_co_u32_e32 v163, vcc, 0, v155, vcc
	v_lshl_add_u64 v[154:155], v[154:155], 0, s[18:19]
	global_load_dwordx4 v[162:165], v[162:163], off offset:3072
	v_or_b32_e32 v194, 32, v148
	global_load_dwordx4 v[166:169], v[154:155], off offset:256
	v_mad_i64_i32 v[154:155], s[54:55], v182, s71, v[150:151]
	v_lshl_add_u64 v[154:155], v[154:155], 0, v[152:153]
	v_add_co_u32_e32 v170, vcc, s72, v154
	v_mad_i64_i32 v[178:179], s[54:55], v194, s71, v[150:151]
	s_nop 0
	v_addc_co_u32_e32 v171, vcc, 0, v155, vcc
	global_load_dwordx4 v[170:173], v[170:171], off offset:3072
	v_lshl_add_u64 v[154:155], v[154:155], 0, s[18:19]
	global_load_dwordx4 v[174:177], v[154:155], off offset:256
	v_lshl_add_u64 v[184:185], v[178:179], 0, v[152:153]
	v_add_co_u32_e32 v178, vcc, s72, v184
	v_ashrrev_i32_e32 v183, 31, v182
	s_nop 0
	v_addc_co_u32_e32 v179, vcc, 0, v185, vcc
	global_load_dwordx4 v[178:181], v[178:179], off offset:3072
	v_lshlrev_b64 v[196:197], 13, v[182:183]
	v_lshl_add_u64 v[182:183], v[184:185], 0, s[18:19]
	v_or_b32_e32 v154, 48, v148
	global_load_dwordx4 v[182:185], v[182:183], off offset:256
	v_mad_i64_i32 v[186:187], s[54:55], v154, s71, v[150:151]
	v_ashrrev_i32_e32 v149, 31, v148
	v_lshl_add_u64 v[186:187], v[186:187], 0, v[152:153]
	v_lshlrev_b64 v[188:189], 13, v[148:149]
	v_lshl_add_u64 v[190:191], v[186:187], 0, s[18:19]
	v_add_co_u32_e32 v186, vcc, s72, v186
	v_lshlrev_b64 v[146:147], 2, v[146:147]
	v_lshl_add_u64 v[188:189], s[6:7], 0, v[188:189]
	v_addc_co_u32_e32 v187, vcc, 0, v187, vcc
	v_lshl_add_u64 v[198:199], v[188:189], 0, v[146:147]
	global_load_dwordx4 v[186:189], v[186:187], off offset:3072
	s_nop 0
	global_load_dwordx4 v[190:193], v[190:191], off offset:256
	v_ashrrev_i32_e32 v195, 31, v194
	v_ashrrev_i32_e32 v155, 31, v154
	s_waitcnt vmcnt(0)
	v_lshlrev_b32_e32 v200, 16, v162
	v_and_b32_e32 v201, 0xffff0000, v162
	v_lshlrev_b32_e32 v162, 16, v163
	v_and_b32_e32 v163, 0xffff0000, v163
	v_lshlrev_b32_e32 v204, 16, v166
	v_and_b32_e32 v205, 0xffff0000, v166
	v_lshlrev_b32_e32 v202, 16, v164
	v_and_b32_e32 v203, 0xffff0000, v164
	v_lshlrev_b32_e32 v164, 16, v165
	v_and_b32_e32 v165, 0xffff0000, v165
	v_lshlrev_b32_e32 v166, 16, v167
	v_and_b32_e32 v167, 0xffff0000, v167
	v_lshlrev_b32_e32 v206, 16, v168
	v_and_b32_e32 v207, 0xffff0000, v168
	v_lshlrev_b32_e32 v168, 16, v169
	v_and_b32_e32 v169, 0xffff0000, v169
	v_pk_mul_f32 v[124:125], v[124:125], v[200:201]
	v_pk_mul_f32 v[126:127], v[126:127], v[162:163]
	v_pk_mul_f32 v[112:113], v[112:113], v[204:205]
	v_pk_mul_f32 v[120:121], v[120:121], v[202:203]
	v_pk_mul_f32 v[122:123], v[122:123], v[164:165]
	v_pk_mul_f32 v[114:115], v[114:115], v[166:167]
	v_pk_mul_f32 v[108:109], v[108:109], v[206:207]
	v_pk_mul_f32 v[110:111], v[110:111], v[168:169]
	ds_bpermute_b32 v238, v254, v124
	ds_bpermute_b32 v239, v254, v125
	ds_bpermute_b32 v240, v254, v126
	ds_bpermute_b32 v241, v254, v127
	ds_bpermute_b32 v236, v254, v198
	ds_bpermute_b32 v237, v254, v199
	ds_bpermute_b32 v244, v254, v120
	ds_bpermute_b32 v245, v254, v121
	ds_bpermute_b32 v246, v254, v122
	ds_bpermute_b32 v247, v254, v123
	ds_bpermute_b32 v242, v254, v198
	ds_bpermute_b32 v243, v254, v199
	ds_bpermute_b32 v250, v254, v112
	ds_bpermute_b32 v251, v254, v113
	ds_bpermute_b32 v252, v254, v114
	ds_bpermute_b32 v253, v254, v115
	ds_bpermute_b32 v248, v254, v198
	ds_bpermute_b32 v249, v254, v199
	s_waitcnt lgkmcnt(12)
	global_store_dwordx4 v[236:237], v[238:241], off
	s_nop 0
	ds_bpermute_b32 v238, v254, v108
	ds_bpermute_b32 v239, v254, v109
	ds_bpermute_b32 v240, v254, v110
	ds_bpermute_b32 v241, v254, v111
	ds_bpermute_b32 v236, v254, v198
	ds_bpermute_b32 v237, v254, v199
	s_nop 0
	v_lshlrev_b32_e32 v112, 16, v172
	v_and_b32_e32 v113, 0xffff0000, v172
	v_pk_mul_f32 v[104:105], v[104:105], v[112:113]
	v_lshlrev_b32_e32 v112, 16, v173
	v_and_b32_e32 v113, 0xffff0000, v173
	v_lshlrev_b32_e32 v108, 16, v170
	v_and_b32_e32 v109, 0xffff0000, v170
	v_lshlrev_b32_e32 v110, 16, v171
	v_and_b32_e32 v111, 0xffff0000, v171
	v_pk_mul_f32 v[106:107], v[106:107], v[112:113]
	v_lshl_add_u64 v[112:113], s[6:7], 0, v[196:197]
	v_pk_mul_f32 v[108:109], v[116:117], v[108:109]
	v_pk_mul_f32 v[110:111], v[118:119], v[110:111]
	v_lshl_add_u64 v[112:113], v[112:113], 0, v[146:147]
	s_waitcnt lgkmcnt(12)
	global_store_dwordx4 v[242:243], v[244:247], off offset:16
	s_nop 0
	ds_bpermute_b32 v244, v254, v108
	ds_bpermute_b32 v245, v254, v109
	ds_bpermute_b32 v246, v254, v110
	ds_bpermute_b32 v247, v254, v111
	ds_bpermute_b32 v242, v254, v112
	ds_bpermute_b32 v243, v254, v113
	s_waitcnt lgkmcnt(12)
	global_store_dwordx4 v[248:249], v[250:253], off offset:512
	s_nop 0
	ds_bpermute_b32 v250, v254, v104
	ds_bpermute_b32 v251, v254, v105
	ds_bpermute_b32 v252, v254, v106
	ds_bpermute_b32 v253, v254, v107
	ds_bpermute_b32 v248, v254, v112
	ds_bpermute_b32 v249, v254, v113
	s_nop 1
	v_lshlrev_b32_e32 v104, 16, v174
	v_and_b32_e32 v105, 0xffff0000, v174
	v_pk_mul_f32 v[100:101], v[100:101], v[104:105]
	v_lshlrev_b32_e32 v104, 16, v175
	v_and_b32_e32 v105, 0xffff0000, v175
	v_pk_mul_f32 v[102:103], v[102:103], v[104:105]
	v_lshlrev_b32_e32 v104, 16, v176
	v_and_b32_e32 v105, 0xffff0000, v176
	v_pk_mul_f32 v[92:93], v[92:93], v[104:105]
	v_lshlrev_b32_e32 v104, 16, v177
	v_and_b32_e32 v105, 0xffff0000, v177
	v_pk_mul_f32 v[94:95], v[94:95], v[104:105]
	s_waitcnt lgkmcnt(12)
	global_store_dwordx4 v[236:237], v[238:241], off offset:528
	s_nop 0
	ds_bpermute_b32 v238, v254, v100
	ds_bpermute_b32 v239, v254, v101
	ds_bpermute_b32 v240, v254, v102
	ds_bpermute_b32 v241, v254, v103
	ds_bpermute_b32 v236, v254, v112
	ds_bpermute_b32 v237, v254, v113
	s_waitcnt lgkmcnt(12)
	global_store_dwordx4 v[242:243], v[244:247], off
	s_nop 0
	ds_bpermute_b32 v244, v254, v92
	ds_bpermute_b32 v245, v254, v93
	ds_bpermute_b32 v246, v254, v94
	ds_bpermute_b32 v247, v254, v95
	ds_bpermute_b32 v242, v254, v112
	ds_bpermute_b32 v243, v254, v113
	s_nop 0
	v_lshlrev_b64 v[100:101], 13, v[194:195]
	v_lshlrev_b32_e32 v92, 16, v178
	v_and_b32_e32 v93, 0xffff0000, v178
	v_pk_mul_f32 v[92:93], v[96:97], v[92:93]
	v_lshlrev_b32_e32 v96, 16, v180
	v_and_b32_e32 v97, 0xffff0000, v180
	v_pk_mul_f32 v[88:89], v[88:89], v[96:97]
	v_lshlrev_b32_e32 v96, 16, v181
	v_and_b32_e32 v97, 0xffff0000, v181
	v_lshlrev_b32_e32 v94, 16, v179
	v_and_b32_e32 v95, 0xffff0000, v179
	v_pk_mul_f32 v[90:91], v[90:91], v[96:97]
	v_lshl_add_u64 v[96:97], s[6:7], 0, v[100:101]
	v_pk_mul_f32 v[94:95], v[98:99], v[94:95]
	v_lshl_add_u64 v[96:97], v[96:97], 0, v[146:147]
	s_waitcnt lgkmcnt(12)
	global_store_dwordx4 v[248:249], v[250:253], off offset:16
	s_nop 0
	ds_bpermute_b32 v250, v254, v92
	ds_bpermute_b32 v251, v254, v93
	ds_bpermute_b32 v252, v254, v94
	ds_bpermute_b32 v253, v254, v95
	ds_bpermute_b32 v248, v254, v96
	ds_bpermute_b32 v249, v254, v97
	s_waitcnt lgkmcnt(12)
	global_store_dwordx4 v[236:237], v[238:241], off offset:512
	s_nop 0
	ds_bpermute_b32 v238, v254, v88
	ds_bpermute_b32 v239, v254, v89
	ds_bpermute_b32 v240, v254, v90
	ds_bpermute_b32 v241, v254, v91
	ds_bpermute_b32 v236, v254, v96
	ds_bpermute_b32 v237, v254, v97
	v_add_u32_e32 v98, 0x90, v148
	v_add_u32_e32 v100, 0xa0, v148
	v_lshlrev_b32_e32 v88, 16, v182
	v_and_b32_e32 v89, 0xffff0000, v182
	v_pk_mul_f32 v[84:85], v[84:85], v[88:89]
	v_lshlrev_b32_e32 v88, 16, v183
	v_and_b32_e32 v89, 0xffff0000, v183
	v_pk_mul_f32 v[86:87], v[86:87], v[88:89]
	v_lshlrev_b32_e32 v88, 16, v184
	v_and_b32_e32 v89, 0xffff0000, v184
	v_pk_mul_f32 v[76:77], v[76:77], v[88:89]
	v_lshlrev_b32_e32 v88, 16, v185
	v_and_b32_e32 v89, 0xffff0000, v185
	v_pk_mul_f32 v[78:79], v[78:79], v[88:89]
	s_waitcnt lgkmcnt(12)
	global_store_dwordx4 v[242:243], v[244:247], off offset:528
	s_nop 0
	ds_bpermute_b32 v244, v254, v84
	ds_bpermute_b32 v245, v254, v85
	ds_bpermute_b32 v246, v254, v86
	ds_bpermute_b32 v247, v254, v87
	ds_bpermute_b32 v242, v254, v96
	ds_bpermute_b32 v243, v254, v97
	s_waitcnt lgkmcnt(12)
	global_store_dwordx4 v[248:249], v[250:253], off
	s_nop 0
	ds_bpermute_b32 v250, v254, v76
	ds_bpermute_b32 v251, v254, v77
	ds_bpermute_b32 v252, v254, v78
	ds_bpermute_b32 v253, v254, v79
	ds_bpermute_b32 v248, v254, v96
	ds_bpermute_b32 v249, v254, v97
	v_add_u32_e32 v96, 0x80, v148
	v_lshlrev_b64 v[84:85], 13, v[154:155]
	v_lshlrev_b32_e32 v76, 16, v186
	v_and_b32_e32 v77, 0xffff0000, v186
	v_pk_mul_f32 v[76:77], v[80:81], v[76:77]
	v_lshlrev_b32_e32 v80, 16, v188
	v_and_b32_e32 v81, 0xffff0000, v188
	v_pk_mul_f32 v[72:73], v[72:73], v[80:81]
	v_lshlrev_b32_e32 v80, 16, v189
	v_and_b32_e32 v81, 0xffff0000, v189
	v_lshlrev_b32_e32 v78, 16, v187
	v_and_b32_e32 v79, 0xffff0000, v187
	v_pk_mul_f32 v[74:75], v[74:75], v[80:81]
	v_lshl_add_u64 v[80:81], s[6:7], 0, v[84:85]
	v_pk_mul_f32 v[78:79], v[82:83], v[78:79]
	v_lshl_add_u64 v[80:81], v[80:81], 0, v[146:147]
	s_waitcnt lgkmcnt(12)
	global_store_dwordx4 v[236:237], v[238:241], off offset:16
	s_nop 0
	ds_bpermute_b32 v238, v254, v76
	ds_bpermute_b32 v239, v254, v77
	ds_bpermute_b32 v240, v254, v78
	ds_bpermute_b32 v241, v254, v79
	ds_bpermute_b32 v236, v254, v80
	ds_bpermute_b32 v237, v254, v81
	s_waitcnt lgkmcnt(12)
	global_store_dwordx4 v[242:243], v[244:247], off offset:512
	s_nop 0
	ds_bpermute_b32 v244, v254, v72
	ds_bpermute_b32 v245, v254, v73
	ds_bpermute_b32 v246, v254, v74
	ds_bpermute_b32 v247, v254, v75
	ds_bpermute_b32 v242, v254, v80
	ds_bpermute_b32 v243, v254, v81
	v_add_u32_e32 v102, 0xb0, v148
	v_ashrrev_i32_e32 v97, 31, v96
	v_lshlrev_b32_e32 v72, 16, v190
	v_and_b32_e32 v73, 0xffff0000, v190
	v_pk_mul_f32 v[68:69], v[68:69], v[72:73]
	v_lshlrev_b32_e32 v72, 16, v191
	v_and_b32_e32 v73, 0xffff0000, v191
	v_pk_mul_f32 v[70:71], v[70:71], v[72:73]
	v_lshlrev_b32_e32 v72, 16, v192
	v_and_b32_e32 v73, 0xffff0000, v192
	v_pk_mul_f32 v[64:65], v[64:65], v[72:73]
	v_lshlrev_b32_e32 v72, 16, v193
	v_and_b32_e32 v73, 0xffff0000, v193
	v_pk_mul_f32 v[66:67], v[66:67], v[72:73]
	s_waitcnt lgkmcnt(12)
	global_store_dwordx4 v[248:249], v[250:253], off offset:528
	s_nop 0
	ds_bpermute_b32 v250, v254, v68
	ds_bpermute_b32 v251, v254, v69
	ds_bpermute_b32 v252, v254, v70
	ds_bpermute_b32 v253, v254, v71
	ds_bpermute_b32 v248, v254, v80
	ds_bpermute_b32 v249, v254, v81
	s_waitcnt lgkmcnt(12)
	global_store_dwordx4 v[236:237], v[238:241], off
	s_nop 0
	ds_bpermute_b32 v238, v254, v64
	ds_bpermute_b32 v239, v254, v65
	ds_bpermute_b32 v240, v254, v66
	ds_bpermute_b32 v241, v254, v67
	ds_bpermute_b32 v236, v254, v80
	ds_bpermute_b32 v237, v254, v81
	v_ashrrev_i32_e32 v99, 31, v98
	v_ashrrev_i32_e32 v101, 31, v100
	v_mad_i64_i32 v[64:65], s[54:55], v96, s71, v[150:151]
	v_lshl_add_u64 v[64:65], v[64:65], 0, v[152:153]
	v_add_co_u32_e32 v66, vcc, s72, v64
	v_lshlrev_b64 v[96:97], 13, v[96:97]
	s_nop 0
	v_addc_co_u32_e32 v67, vcc, 0, v65, vcc
	global_load_dwordx4 v[68:71], v[66:67], off offset:3072
	v_lshl_add_u64 v[64:65], v[64:65], 0, s[18:19]
	global_load_dwordx4 v[72:75], v[64:65], off offset:256
	v_mad_i64_i32 v[64:65], s[54:55], v98, s71, v[150:151]
	v_lshl_add_u64 v[64:65], v[64:65], 0, v[152:153]
	v_add_co_u32_e32 v66, vcc, s72, v64
	v_ashrrev_i32_e32 v103, 31, v102
	s_nop 0
	v_addc_co_u32_e32 v67, vcc, 0, v65, vcc
	global_load_dwordx4 v[76:79], v[66:67], off offset:3072
	v_lshl_add_u64 v[64:65], v[64:65], 0, s[18:19]
	global_load_dwordx4 v[80:83], v[64:65], off offset:256
	v_mad_i64_i32 v[64:65], s[54:55], v100, s71, v[150:151]
	v_lshl_add_u64 v[64:65], v[64:65], 0, v[152:153]
	v_add_co_u32_e32 v66, vcc, s72, v64
	s_waitcnt lgkmcnt(12)
	global_store_dwordx4 v[242:243], v[244:247], off offset:16
	s_waitcnt lgkmcnt(6)
	global_store_dwordx4 v[248:249], v[250:253], off offset:512
	s_waitcnt lgkmcnt(0)
	global_store_dwordx4 v[236:237], v[238:241], off offset:528
	s_waitcnt vmcnt(3)
	v_lshlrev_b32_e32 v104, 16, v68
	v_addc_co_u32_e32 v67, vcc, 0, v65, vcc
	global_load_dwordx4 v[84:87], v[66:67], off offset:3072
	v_lshl_add_u64 v[64:65], v[64:65], 0, s[18:19]
	global_load_dwordx4 v[88:91], v[64:65], off offset:256
	v_mad_i64_i32 v[64:65], s[54:55], v102, s71, v[150:151]
	v_lshl_add_u64 v[64:65], v[64:65], 0, v[152:153]
	v_lshl_add_u64 v[66:67], v[64:65], 0, s[18:19]
	v_add_co_u32_e32 v64, vcc, s72, v64
	v_and_b32_e32 v105, 0xffff0000, v68
	s_nop 0
	v_addc_co_u32_e32 v65, vcc, 0, v65, vcc
	global_load_dwordx4 v[92:95], v[64:65], off offset:3072
	s_nop 0
	global_load_dwordx4 v[64:67], v[66:67], off offset:256
	v_lshlrev_b32_e32 v68, 16, v69
	v_and_b32_e32 v69, 0xffff0000, v69
	v_pk_mul_f32 v[62:63], v[62:63], v[68:69]
	v_lshlrev_b32_e32 v68, 16, v70
	v_and_b32_e32 v69, 0xffff0000, v70
	v_pk_mul_f32 v[56:57], v[56:57], v[68:69]
	v_lshlrev_b32_e32 v68, 16, v71
	v_and_b32_e32 v69, 0xffff0000, v71
	v_pk_mul_f32 v[58:59], v[58:59], v[68:69]
	v_lshl_add_u64 v[68:69], s[6:7], 0, v[96:97]
	v_pk_mul_f32 v[60:61], v[60:61], v[104:105]
	v_lshl_add_u64 v[68:69], v[68:69], 0, v[146:147]
	ds_bpermute_b32 v244, v254, v60
	ds_bpermute_b32 v245, v254, v61
	ds_bpermute_b32 v246, v254, v62
	ds_bpermute_b32 v247, v254, v63
	ds_bpermute_b32 v242, v254, v68
	ds_bpermute_b32 v243, v254, v69
	ds_bpermute_b32 v250, v254, v56
	ds_bpermute_b32 v251, v254, v57
	ds_bpermute_b32 v252, v254, v58
	ds_bpermute_b32 v253, v254, v59
	ds_bpermute_b32 v248, v254, v68
	ds_bpermute_b32 v249, v254, v69
	s_andn2_b64 vcc, exec, s[4:5]
	s_mov_b64 s[4:5], -1
	s_waitcnt lgkmcnt(6)
	global_store_dwordx4 v[242:243], v[244:247], off
	s_waitcnt lgkmcnt(0)
	global_store_dwordx4 v[248:249], v[250:253], off offset:16
	s_waitcnt vmcnt(8)
	v_lshlrev_b32_e32 v56, 16, v72
	v_and_b32_e32 v57, 0xffff0000, v72
	v_pk_mul_f32 v[52:53], v[52:53], v[56:57]
	v_lshlrev_b32_e32 v56, 16, v73
	v_and_b32_e32 v57, 0xffff0000, v73
	v_pk_mul_f32 v[54:55], v[54:55], v[56:57]
	v_lshlrev_b32_e32 v56, 16, v74
	v_and_b32_e32 v57, 0xffff0000, v74
	v_pk_mul_f32 v[44:45], v[44:45], v[56:57]
	v_lshlrev_b32_e32 v56, 16, v75
	v_and_b32_e32 v57, 0xffff0000, v75
	v_pk_mul_f32 v[46:47], v[46:47], v[56:57]
	ds_bpermute_b32 v238, v254, v52
	ds_bpermute_b32 v239, v254, v53
	ds_bpermute_b32 v240, v254, v54
	ds_bpermute_b32 v241, v254, v55
	ds_bpermute_b32 v236, v254, v68
	ds_bpermute_b32 v237, v254, v69
	ds_bpermute_b32 v244, v254, v44
	ds_bpermute_b32 v245, v254, v45
	ds_bpermute_b32 v246, v254, v46
	ds_bpermute_b32 v247, v254, v47
	ds_bpermute_b32 v242, v254, v68
	ds_bpermute_b32 v243, v254, v69
	s_nop 0
	v_lshlrev_b64 v[52:53], 13, v[98:99]
	s_waitcnt lgkmcnt(6)
	global_store_dwordx4 v[236:237], v[238:241], off offset:512
	s_waitcnt lgkmcnt(0)
	global_store_dwordx4 v[242:243], v[244:247], off offset:528
	s_waitcnt vmcnt(9)
	v_lshlrev_b32_e32 v44, 16, v76
	v_and_b32_e32 v45, 0xffff0000, v76
	v_pk_mul_f32 v[44:45], v[48:49], v[44:45]
	v_lshlrev_b32_e32 v48, 16, v78
	v_and_b32_e32 v49, 0xffff0000, v78
	v_pk_mul_f32 v[40:41], v[40:41], v[48:49]
	v_lshlrev_b32_e32 v48, 16, v79
	v_and_b32_e32 v49, 0xffff0000, v79
	v_lshlrev_b32_e32 v46, 16, v77
	v_and_b32_e32 v47, 0xffff0000, v77
	v_pk_mul_f32 v[42:43], v[42:43], v[48:49]
	v_lshl_add_u64 v[48:49], s[6:7], 0, v[52:53]
	v_pk_mul_f32 v[46:47], v[50:51], v[46:47]
	v_lshl_add_u64 v[48:49], v[48:49], 0, v[146:147]
	ds_bpermute_b32 v250, v254, v44
	ds_bpermute_b32 v251, v254, v45
	ds_bpermute_b32 v252, v254, v46
	ds_bpermute_b32 v253, v254, v47
	ds_bpermute_b32 v248, v254, v48
	ds_bpermute_b32 v249, v254, v49
	ds_bpermute_b32 v238, v254, v40
	ds_bpermute_b32 v239, v254, v41
	ds_bpermute_b32 v240, v254, v42
	ds_bpermute_b32 v241, v254, v43
	ds_bpermute_b32 v236, v254, v48
	ds_bpermute_b32 v237, v254, v49
	s_waitcnt lgkmcnt(6)
	global_store_dwordx4 v[248:249], v[250:253], off
	s_waitcnt lgkmcnt(0)
	global_store_dwordx4 v[236:237], v[238:241], off offset:16
	s_waitcnt vmcnt(10)
	s_nop 0
	v_lshlrev_b32_e32 v40, 16, v80
	v_and_b32_e32 v41, 0xffff0000, v80
	v_pk_mul_f32 v[36:37], v[36:37], v[40:41]
	v_lshlrev_b32_e32 v40, 16, v81
	v_and_b32_e32 v41, 0xffff0000, v81
	v_pk_mul_f32 v[38:39], v[38:39], v[40:41]
	v_lshlrev_b32_e32 v40, 16, v82
	v_and_b32_e32 v41, 0xffff0000, v82
	v_pk_mul_f32 v[28:29], v[28:29], v[40:41]
	v_lshlrev_b32_e32 v40, 16, v83
	v_and_b32_e32 v41, 0xffff0000, v83
	v_pk_mul_f32 v[30:31], v[30:31], v[40:41]
	ds_bpermute_b32 v244, v254, v36
	ds_bpermute_b32 v245, v254, v37
	ds_bpermute_b32 v246, v254, v38
	ds_bpermute_b32 v247, v254, v39
	ds_bpermute_b32 v242, v254, v48
	ds_bpermute_b32 v243, v254, v49
	ds_bpermute_b32 v250, v254, v28
	ds_bpermute_b32 v251, v254, v29
	ds_bpermute_b32 v252, v254, v30
	ds_bpermute_b32 v253, v254, v31
	ds_bpermute_b32 v248, v254, v48
	ds_bpermute_b32 v249, v254, v49
	s_nop 0
	v_lshlrev_b64 v[36:37], 13, v[100:101]
	s_waitcnt lgkmcnt(6)
	global_store_dwordx4 v[242:243], v[244:247], off offset:512
	s_waitcnt lgkmcnt(0)
	global_store_dwordx4 v[248:249], v[250:253], off offset:528
	s_waitcnt vmcnt(11)
	v_lshlrev_b32_e32 v28, 16, v84
	v_and_b32_e32 v29, 0xffff0000, v84
	v_pk_mul_f32 v[28:29], v[32:33], v[28:29]
	v_lshlrev_b32_e32 v32, 16, v86
	v_and_b32_e32 v33, 0xffff0000, v86
	v_pk_mul_f32 v[24:25], v[24:25], v[32:33]
	v_lshlrev_b32_e32 v32, 16, v87
	v_and_b32_e32 v33, 0xffff0000, v87
	v_lshlrev_b32_e32 v30, 16, v85
	v_and_b32_e32 v31, 0xffff0000, v85
	v_pk_mul_f32 v[26:27], v[26:27], v[32:33]
	v_lshl_add_u64 v[32:33], s[6:7], 0, v[36:37]
	v_pk_mul_f32 v[30:31], v[34:35], v[30:31]
	v_lshl_add_u64 v[32:33], v[32:33], 0, v[146:147]
	ds_bpermute_b32 v238, v254, v28
	ds_bpermute_b32 v239, v254, v29
	ds_bpermute_b32 v240, v254, v30
	ds_bpermute_b32 v241, v254, v31
	ds_bpermute_b32 v236, v254, v32
	ds_bpermute_b32 v237, v254, v33
	ds_bpermute_b32 v244, v254, v24
	ds_bpermute_b32 v245, v254, v25
	ds_bpermute_b32 v246, v254, v26
	ds_bpermute_b32 v247, v254, v27
	ds_bpermute_b32 v242, v254, v32
	ds_bpermute_b32 v243, v254, v33
	s_waitcnt lgkmcnt(6)
	global_store_dwordx4 v[236:237], v[238:241], off
	s_waitcnt lgkmcnt(0)
	global_store_dwordx4 v[242:243], v[244:247], off offset:16
	s_waitcnt vmcnt(12)
	s_nop 0
	v_lshlrev_b32_e32 v24, 16, v88
	v_and_b32_e32 v25, 0xffff0000, v88
	v_pk_mul_f32 v[20:21], v[20:21], v[24:25]
	v_lshlrev_b32_e32 v24, 16, v89
	v_and_b32_e32 v25, 0xffff0000, v89
	v_pk_mul_f32 v[22:23], v[22:23], v[24:25]
	v_lshlrev_b32_e32 v24, 16, v90
	v_and_b32_e32 v25, 0xffff0000, v90
	v_pk_mul_f32 v[12:13], v[12:13], v[24:25]
	v_lshlrev_b32_e32 v24, 16, v91
	v_and_b32_e32 v25, 0xffff0000, v91
	v_pk_mul_f32 v[14:15], v[14:15], v[24:25]
	ds_bpermute_b32 v250, v254, v20
	ds_bpermute_b32 v251, v254, v21
	ds_bpermute_b32 v252, v254, v22
	ds_bpermute_b32 v253, v254, v23
	ds_bpermute_b32 v248, v254, v32
	ds_bpermute_b32 v249, v254, v33
	ds_bpermute_b32 v238, v254, v12
	ds_bpermute_b32 v239, v254, v13
	ds_bpermute_b32 v240, v254, v14
	ds_bpermute_b32 v241, v254, v15
	ds_bpermute_b32 v236, v254, v32
	ds_bpermute_b32 v237, v254, v33
	s_nop 0
	v_lshlrev_b64 v[20:21], 13, v[102:103]
	s_waitcnt lgkmcnt(6)
	global_store_dwordx4 v[248:249], v[250:253], off offset:512
	s_waitcnt lgkmcnt(0)
	global_store_dwordx4 v[236:237], v[238:241], off offset:528
	s_waitcnt vmcnt(13)
	v_lshlrev_b32_e32 v12, 16, v92
	v_and_b32_e32 v13, 0xffff0000, v92
	v_pk_mul_f32 v[12:13], v[16:17], v[12:13]
	v_lshlrev_b32_e32 v16, 16, v94
	v_and_b32_e32 v17, 0xffff0000, v94
	v_pk_mul_f32 v[8:9], v[8:9], v[16:17]
	v_lshlrev_b32_e32 v16, 16, v95
	v_and_b32_e32 v17, 0xffff0000, v95
	v_lshlrev_b32_e32 v14, 16, v93
	v_and_b32_e32 v15, 0xffff0000, v93
	v_pk_mul_f32 v[10:11], v[10:11], v[16:17]
	v_lshl_add_u64 v[16:17], s[6:7], 0, v[20:21]
	v_pk_mul_f32 v[14:15], v[18:19], v[14:15]
	v_lshl_add_u64 v[16:17], v[16:17], 0, v[146:147]
	ds_bpermute_b32 v244, v254, v12
	ds_bpermute_b32 v245, v254, v13
	ds_bpermute_b32 v246, v254, v14
	ds_bpermute_b32 v247, v254, v15
	ds_bpermute_b32 v242, v254, v16
	ds_bpermute_b32 v243, v254, v17
	ds_bpermute_b32 v250, v254, v8
	ds_bpermute_b32 v251, v254, v9
	ds_bpermute_b32 v252, v254, v10
	ds_bpermute_b32 v253, v254, v11
	ds_bpermute_b32 v248, v254, v16
	ds_bpermute_b32 v249, v254, v17
	s_waitcnt lgkmcnt(6)
	global_store_dwordx4 v[242:243], v[244:247], off
	s_waitcnt lgkmcnt(0)
	global_store_dwordx4 v[248:249], v[250:253], off offset:16
	s_waitcnt vmcnt(14)
	s_nop 0
	v_lshlrev_b32_e32 v8, 16, v64
	v_and_b32_e32 v9, 0xffff0000, v64
	v_pk_mul_f32 v[4:5], v[4:5], v[8:9]
	v_lshlrev_b32_e32 v8, 16, v65
	v_and_b32_e32 v9, 0xffff0000, v65
	v_pk_mul_f32 v[6:7], v[6:7], v[8:9]
	v_lshlrev_b32_e32 v8, 16, v66
	v_and_b32_e32 v9, 0xffff0000, v66
	v_pk_mul_f32 v[0:1], v[0:1], v[8:9]
	v_lshlrev_b32_e32 v8, 16, v67
	v_and_b32_e32 v9, 0xffff0000, v67
	v_pk_mul_f32 v[2:3], v[2:3], v[8:9]
	ds_bpermute_b32 v238, v254, v4
	ds_bpermute_b32 v239, v254, v5
	ds_bpermute_b32 v240, v254, v6
	ds_bpermute_b32 v241, v254, v7
	ds_bpermute_b32 v236, v254, v16
	ds_bpermute_b32 v237, v254, v17
	ds_bpermute_b32 v244, v254, v0
	ds_bpermute_b32 v245, v254, v1
	ds_bpermute_b32 v246, v254, v2
	ds_bpermute_b32 v247, v254, v3
	ds_bpermute_b32 v242, v254, v16
	ds_bpermute_b32 v243, v254, v17
	s_waitcnt lgkmcnt(6)
	global_store_dwordx4 v[236:237], v[238:241], off offset:512
	s_waitcnt lgkmcnt(0)
	global_store_dwordx4 v[242:243], v[244:247], off offset:528
	s_cbranch_vccnz .LBB0_1386
	s_andn2_b64 vcc, exec, s[10:11]
	s_cbranch_vccnz .LBB0_1385
	s_barrier
	s_branch .LBB0_1385

.LBB0_1409:
	v_and_b32_e32 v254, 63, v128
	v_and_b32_e32 v255, 3, v254
	v_lshrrev_b32_e32 v254, 2, v254
	v_lshl_or_b32 v254, v255, 4, v254
	v_lshlrev_b32_e32 v254, 2, v254
	v_lshl_add_u32 v148, s54, 8, v129
	v_lshl_or_b32 v152, s52, 8, v155
	v_ashrrev_i32_e32 v153, 31, v152
	v_mov_b64_e32 v[150:151], s[8:9]
	v_or_b32_e32 v208, 16, v148
	v_lshlrev_b64 v[146:147], 1, v[152:153]
	v_mad_i64_i32 v[164:165], s[56:57], v208, s74, v[150:151]
	v_lshl_add_u64 v[196:197], v[164:165], 0, v[146:147]
	v_mad_i64_i32 v[160:161], s[56:57], v148, s74, v[150:151]
	v_add_co_u32_e32 v164, vcc, s67, v196
	v_lshl_add_u64 v[168:169], v[160:161], 0, v[146:147]
	s_nop 0
	v_addc_co_u32_e32 v165, vcc, 0, v197, vcc
	v_ashrrev_i32_e32 v149, 31, v148
	v_lshl_add_u64 v[160:161], v[168:169], 0, s[20:21]
	v_add_co_u32_e32 v168, vcc, s67, v168
	v_lshl_add_u64 v[152:153], v[152:153], 2, s[6:7]
	v_lshlrev_b64 v[172:173], 13, v[148:149]
	v_ashrrev_i32_e32 v209, 31, v208
	global_load_dwordx4 v[160:163], v[160:161], off offset:256
	v_addc_co_u32_e32 v169, vcc, 0, v169, vcc
	v_lshl_add_u64 v[192:193], v[152:153], 0, v[172:173]
	v_lshlrev_b64 v[180:181], 13, v[208:209]
	global_load_dwordx4 v[164:167], v[164:165], off offset:3072
	v_lshl_add_u64 v[204:205], v[152:153], 0, v[180:181]
	global_load_dwordx4 v[168:171], v[168:169], off offset:3072
	s_nop 0
	global_load_dwordx4 v[172:175], v[192:193], off offset:528
	global_load_dwordx4 v[176:179], v[192:193], off offset:512
	global_load_dwordx4 v[180:183], v[204:205], off
	global_load_dwordx4 v[184:187], v[204:205], off offset:16
	global_load_dwordx4 v[188:191], v[192:193], off
	s_nop 0
	global_load_dwordx4 v[192:195], v[192:193], off offset:16
	v_lshl_add_u64 v[196:197], v[196:197], 0, s[20:21]
	global_load_dwordx4 v[196:199], v[196:197], off offset:256
	s_nop 0
	global_load_dwordx4 v[200:203], v[204:205], off offset:512
	s_nop 0
	global_load_dwordx4 v[204:207], v[204:205], off offset:528
	v_lshlrev_b64 v[210:211], 12, v[148:149]
	v_lshl_add_u64 v[210:211], s[14:15], 0, v[210:211]
	v_lshl_add_u64 v[210:211], v[210:211], 0, v[146:147]
	v_lshlrev_b64 v[208:209], 12, v[208:209]
	s_waitcnt vmcnt(0)
	v_lshlrev_b32_e32 v212, 16, v160
	v_and_b32_e32 v213, 0xffff0000, v160
	v_lshlrev_b32_e32 v160, 16, v161
	v_and_b32_e32 v161, 0xffff0000, v161
	v_lshlrev_b32_e32 v214, 16, v162
	v_and_b32_e32 v215, 0xffff0000, v162
	v_lshlrev_b32_e32 v162, 16, v163
	v_and_b32_e32 v163, 0xffff0000, v163
	v_lshlrev_b32_e32 v216, 16, v164
	v_and_b32_e32 v217, 0xffff0000, v164
	v_lshlrev_b32_e32 v164, 16, v165
	v_and_b32_e32 v165, 0xffff0000, v165
	v_lshlrev_b32_e32 v218, 16, v166
	v_and_b32_e32 v219, 0xffff0000, v166
	v_lshlrev_b32_e32 v220, 16, v168
	v_and_b32_e32 v221, 0xffff0000, v168
	v_lshlrev_b32_e32 v168, 16, v169
	v_and_b32_e32 v169, 0xffff0000, v169
	v_lshlrev_b32_e32 v222, 16, v170
	v_and_b32_e32 v223, 0xffff0000, v170
	v_lshlrev_b32_e32 v170, 16, v171
	v_and_b32_e32 v171, 0xffff0000, v171
	v_pk_fma_f32 v[112:113], v[112:113], v[212:213], v[176:177]
	v_pk_fma_f32 v[114:115], v[114:115], v[160:161], v[178:179]
	v_pk_fma_f32 v[160:161], v[108:109], v[214:215], v[172:173]
	v_pk_fma_f32 v[162:163], v[110:111], v[162:163], v[174:175]
	v_lshlrev_b32_e32 v166, 16, v167
	v_pk_fma_f32 v[122:123], v[122:123], v[164:165], v[182:183]
	v_pk_fma_f32 v[164:165], v[104:105], v[218:219], v[184:185]
	v_pk_fma_f32 v[104:105], v[124:125], v[220:221], v[188:189]
	v_pk_fma_f32 v[124:125], v[126:127], v[168:169], v[190:191]
	v_pk_fma_f32 v[116:117], v[116:117], v[222:223], v[192:193]
	v_pk_fma_f32 v[118:119], v[118:119], v[170:171], v[194:195]
	v_cvt_pk_bf16_f32 v108, v112, v113
	v_cvt_pk_bf16_f32 v109, v114, v115
	v_cvt_pk_bf16_f32 v110, v160, v161
	v_cvt_pk_bf16_f32 v111, v162, v163
	v_and_b32_e32 v167, 0xffff0000, v167
	v_cvt_pk_bf16_f32 v112, v104, v105
	v_cvt_pk_bf16_f32 v113, v124, v125
	v_cvt_pk_bf16_f32 v114, v116, v117
	v_cvt_pk_bf16_f32 v115, v118, v119
	ds_bpermute_b32 v238, v254, v108
	ds_bpermute_b32 v239, v254, v109
	ds_bpermute_b32 v240, v254, v110
	ds_bpermute_b32 v241, v254, v111
	ds_bpermute_b32 v236, v254, v210
	ds_bpermute_b32 v237, v254, v211
	ds_bpermute_b32 v244, v254, v112
	ds_bpermute_b32 v245, v254, v113
	ds_bpermute_b32 v246, v254, v114
	ds_bpermute_b32 v247, v254, v115
	ds_bpermute_b32 v242, v254, v210
	ds_bpermute_b32 v243, v254, v211
	v_pk_fma_f32 v[120:121], v[120:121], v[216:217], v[180:181]
	v_pk_fma_f32 v[108:109], v[106:107], v[166:167], v[186:187]
	v_cvt_pk_bf16_f32 v104, v120, v121
	v_cvt_pk_bf16_f32 v107, v108, v109
	v_lshl_add_u64 v[108:109], s[14:15], 0, v[208:209]
	v_cvt_pk_bf16_f32 v105, v122, v123
	v_cvt_pk_bf16_f32 v106, v164, v165
	v_lshl_add_u64 v[108:109], v[108:109], 0, v[146:147]
	ds_bpermute_b32 v250, v254, v104
	ds_bpermute_b32 v251, v254, v105
	ds_bpermute_b32 v252, v254, v106
	ds_bpermute_b32 v253, v254, v107
	ds_bpermute_b32 v248, v254, v108
	ds_bpermute_b32 v249, v254, v109
	v_or_b32_e32 v176, 32, v148
	v_ashrrev_i32_e32 v177, 31, v176
	v_lshlrev_b32_e32 v104, 16, v196
	v_and_b32_e32 v105, 0xffff0000, v196
	v_pk_fma_f32 v[100:101], v[100:101], v[104:105], v[200:201]
	v_lshlrev_b32_e32 v104, 16, v197
	v_and_b32_e32 v105, 0xffff0000, v197
	v_pk_fma_f32 v[104:105], v[102:103], v[104:105], v[202:203]
	v_lshlrev_b32_e32 v102, 16, v198
	v_and_b32_e32 v103, 0xffff0000, v198
	v_pk_fma_f32 v[106:107], v[96:97], v[102:103], v[204:205]
	v_lshlrev_b32_e32 v96, 16, v199
	v_and_b32_e32 v97, 0xffff0000, v199
	v_pk_fma_f32 v[110:111], v[98:99], v[96:97], v[206:207]
	v_mad_i64_i32 v[98:99], s[56:57], v176, s74, v[150:151]
	v_lshl_add_u64 v[112:113], v[98:99], 0, v[146:147]
	v_add_co_u32_e32 v98, vcc, s67, v112
	v_cvt_pk_bf16_f32 v96, v100, v101
	s_nop 0
	v_addc_co_u32_e32 v99, vcc, 0, v113, vcc
	global_load_dwordx4 v[100:103], v[98:99], off offset:3072
	v_cvt_pk_bf16_f32 v97, v104, v105
	v_cvt_pk_bf16_f32 v98, v106, v107
	v_cvt_pk_bf16_f32 v99, v110, v111
	v_lshlrev_b64 v[104:105], 13, v[176:177]
	s_waitcnt lgkmcnt(12)
	global_store_dwordx4 v[236:237], v[238:241], off offset:256
	s_nop 0
	ds_bpermute_b32 v238, v254, v96
	ds_bpermute_b32 v239, v254, v97
	ds_bpermute_b32 v240, v254, v98
	ds_bpermute_b32 v241, v254, v99
	ds_bpermute_b32 v236, v254, v108
	ds_bpermute_b32 v237, v254, v109
	v_lshl_add_u64 v[116:117], v[152:153], 0, v[104:105]
	v_or_b32_e32 v178, 48, v148
	v_lshl_add_u64 v[96:97], v[112:113], 0, s[20:21]
	global_load_dwordx4 v[96:99], v[96:97], off offset:256
	s_nop 0
	global_load_dwordx4 v[104:107], v[116:117], off
	global_load_dwordx4 v[108:111], v[116:117], off offset:16
	global_load_dwordx4 v[112:115], v[116:117], off offset:512
	s_nop 0
	global_load_dwordx4 v[116:119], v[116:117], off offset:528
	v_mad_i64_i32 v[120:121], s[56:57], v178, s74, v[150:151]
	v_lshl_add_u64 v[164:165], v[120:121], 0, v[146:147]
	v_add_co_u32_e32 v120, vcc, s67, v164
	v_ashrrev_i32_e32 v179, 31, v178
	s_nop 0
	v_addc_co_u32_e32 v121, vcc, 0, v165, vcc
	v_lshlrev_b64 v[124:125], 13, v[178:179]
	global_load_dwordx4 v[120:123], v[120:121], off offset:3072
	v_lshl_add_u64 v[172:173], v[152:153], 0, v[124:125]
	global_load_dwordx4 v[124:127], v[172:173], off
	global_load_dwordx4 v[160:163], v[172:173], off offset:16
	v_lshl_add_u64 v[164:165], v[164:165], 0, s[20:21]
	global_load_dwordx4 v[164:167], v[164:165], off offset:256
	s_nop 0
	global_load_dwordx4 v[168:171], v[172:173], off offset:512
	s_nop 0
	global_load_dwordx4 v[172:175], v[172:173], off offset:528
	v_lshlrev_b64 v[176:177], 12, v[176:177]
	v_lshl_add_u64 v[176:177], s[14:15], 0, v[176:177]
	v_lshl_add_u64 v[176:177], v[176:177], 0, v[146:147]
	s_waitcnt lgkmcnt(12)
	global_store_dwordx4 v[242:243], v[244:247], off
	s_waitcnt lgkmcnt(6)
	global_store_dwordx4 v[248:249], v[250:253], off
	s_waitcnt lgkmcnt(0)
	global_store_dwordx4 v[236:237], v[238:241], off offset:256
	s_waitcnt vmcnt(12)
	v_lshlrev_b32_e32 v180, 16, v100
	v_and_b32_e32 v181, 0xffff0000, v100
	v_lshlrev_b32_e32 v100, 16, v101
	v_and_b32_e32 v101, 0xffff0000, v101
	v_lshlrev_b32_e32 v182, 16, v102
	v_and_b32_e32 v183, 0xffff0000, v102
	v_lshlrev_b32_e32 v102, 16, v103
	v_and_b32_e32 v103, 0xffff0000, v103
	s_waitcnt vmcnt(9)
	v_pk_fma_f32 v[92:93], v[92:93], v[180:181], v[104:105]
	v_pk_fma_f32 v[94:95], v[94:95], v[100:101], v[106:107]
	s_waitcnt vmcnt(8)
	v_pk_fma_f32 v[100:101], v[88:89], v[182:183], v[108:109]
	v_pk_fma_f32 v[102:103], v[90:91], v[102:103], v[110:111]
	v_cvt_pk_bf16_f32 v88, v92, v93
	v_cvt_pk_bf16_f32 v89, v94, v95
	v_cvt_pk_bf16_f32 v90, v100, v101
	v_cvt_pk_bf16_f32 v91, v102, v103
	ds_bpermute_b32 v244, v254, v88
	ds_bpermute_b32 v245, v254, v89
	ds_bpermute_b32 v246, v254, v90
	ds_bpermute_b32 v247, v254, v91
	ds_bpermute_b32 v242, v254, v176
	ds_bpermute_b32 v243, v254, v177
	v_lshlrev_b32_e32 v184, 16, v96
	v_and_b32_e32 v185, 0xffff0000, v96
	v_lshlrev_b32_e32 v88, 16, v97
	v_and_b32_e32 v89, 0xffff0000, v97
	s_waitcnt lgkmcnt(0)
	global_store_dwordx4 v[242:243], v[244:247], off
	s_waitcnt vmcnt(8)
	v_pk_fma_f32 v[86:87], v[86:87], v[88:89], v[114:115]
	v_lshlrev_b32_e32 v88, 16, v98
	v_and_b32_e32 v89, 0xffff0000, v98
	s_waitcnt vmcnt(7)
	v_pk_fma_f32 v[88:89], v[76:77], v[88:89], v[116:117]
	v_lshlrev_b32_e32 v76, 16, v99
	v_and_b32_e32 v77, 0xffff0000, v99
	v_pk_fma_f32 v[84:85], v[84:85], v[184:185], v[112:113]
	v_pk_fma_f32 v[90:91], v[78:79], v[76:77], v[118:119]
	v_cvt_pk_bf16_f32 v76, v84, v85
	v_cvt_pk_bf16_f32 v77, v86, v87
	v_cvt_pk_bf16_f32 v78, v88, v89
	v_cvt_pk_bf16_f32 v79, v90, v91
	ds_bpermute_b32 v250, v254, v76
	ds_bpermute_b32 v251, v254, v77
	ds_bpermute_b32 v252, v254, v78
	ds_bpermute_b32 v253, v254, v79
	ds_bpermute_b32 v248, v254, v176
	ds_bpermute_b32 v249, v254, v177
	v_add_u32_e32 v112, 0x80, v148
	v_ashrrev_i32_e32 v113, 31, v112
	s_waitcnt lgkmcnt(0)
	global_store_dwordx4 v[248:249], v[250:253], off offset:256
	s_waitcnt vmcnt(7)
	v_lshlrev_b32_e32 v78, 16, v120
	v_and_b32_e32 v79, 0xffff0000, v120
	s_waitcnt vmcnt(6)
	v_pk_fma_f32 v[78:79], v[80:81], v[78:79], v[124:125]
	v_lshlrev_b32_e32 v80, 16, v121
	v_and_b32_e32 v81, 0xffff0000, v121
	v_pk_fma_f32 v[80:81], v[82:83], v[80:81], v[126:127]
	v_lshlrev_b32_e32 v82, 16, v122
	v_and_b32_e32 v83, 0xffff0000, v122
	v_lshlrev_b64 v[76:77], 12, v[178:179]
	s_waitcnt vmcnt(5)
	v_pk_fma_f32 v[82:83], v[72:73], v[82:83], v[160:161]
	v_lshlrev_b32_e32 v72, 16, v123
	v_and_b32_e32 v73, 0xffff0000, v123
	v_pk_fma_f32 v[84:85], v[74:75], v[72:73], v[162:163]
	v_lshl_add_u64 v[76:77], s[14:15], 0, v[76:77]
	v_cvt_pk_bf16_f32 v72, v78, v79
	v_cvt_pk_bf16_f32 v73, v80, v81
	v_cvt_pk_bf16_f32 v74, v82, v83
	v_cvt_pk_bf16_f32 v75, v84, v85
	v_lshl_add_u64 v[76:77], v[76:77], 0, v[146:147]
	ds_bpermute_b32 v238, v254, v72
	ds_bpermute_b32 v239, v254, v73
	ds_bpermute_b32 v240, v254, v74
	ds_bpermute_b32 v241, v254, v75
	ds_bpermute_b32 v236, v254, v76
	ds_bpermute_b32 v237, v254, v77
	v_add_u32_e32 v114, 0x90, v148
	v_mad_i64_i32 v[88:89], s[56:57], v114, s74, v[150:151]
	s_waitcnt lgkmcnt(0)
	global_store_dwordx4 v[236:237], v[238:241], off
	s_waitcnt vmcnt(5)
	v_lshlrev_b32_e32 v72, 16, v164
	v_and_b32_e32 v73, 0xffff0000, v164
	s_waitcnt vmcnt(4)
	v_pk_fma_f32 v[68:69], v[68:69], v[72:73], v[168:169]
	v_lshlrev_b32_e32 v72, 16, v165
	v_and_b32_e32 v73, 0xffff0000, v165
	v_pk_fma_f32 v[70:71], v[70:71], v[72:73], v[170:171]
	v_lshlrev_b32_e32 v72, 16, v166
	v_and_b32_e32 v73, 0xffff0000, v166
	s_waitcnt vmcnt(3)
	v_pk_fma_f32 v[72:73], v[64:65], v[72:73], v[172:173]
	v_lshlrev_b32_e32 v64, 16, v167
	v_and_b32_e32 v65, 0xffff0000, v167
	v_pk_fma_f32 v[74:75], v[66:67], v[64:65], v[174:175]
	v_cvt_pk_bf16_f32 v64, v68, v69
	v_cvt_pk_bf16_f32 v65, v70, v71
	v_cvt_pk_bf16_f32 v66, v72, v73
	v_cvt_pk_bf16_f32 v67, v74, v75
	ds_bpermute_b32 v244, v254, v64
	ds_bpermute_b32 v245, v254, v65
	ds_bpermute_b32 v246, v254, v66
	ds_bpermute_b32 v247, v254, v67
	ds_bpermute_b32 v242, v254, v76
	ds_bpermute_b32 v243, v254, v77
	v_lshlrev_b64 v[68:69], 13, v[112:113]
	v_lshl_add_u64 v[84:85], v[152:153], 0, v[68:69]
	v_mad_i64_i32 v[64:65], s[56:57], v112, s74, v[150:151]
	v_lshl_add_u64 v[76:77], v[64:65], 0, v[146:147]
	v_add_co_u32_e32 v64, vcc, s67, v76
	v_lshl_add_u64 v[100:101], v[88:89], 0, v[146:147]
	s_nop 0
	v_addc_co_u32_e32 v65, vcc, 0, v77, vcc
	global_load_dwordx4 v[64:67], v[64:65], off offset:3072
	s_nop 0
	global_load_dwordx4 v[68:71], v[84:85], off
	global_load_dwordx4 v[72:75], v[84:85], off offset:16
	v_lshl_add_u64 v[76:77], v[76:77], 0, s[20:21]
	global_load_dwordx4 v[76:79], v[76:77], off offset:256
	s_nop 0
	global_load_dwordx4 v[80:83], v[84:85], off offset:512
	s_nop 0
	global_load_dwordx4 v[84:87], v[84:85], off offset:528
	v_add_co_u32_e32 v88, vcc, s67, v100
	v_ashrrev_i32_e32 v115, 31, v114
	s_nop 0
	v_addc_co_u32_e32 v89, vcc, 0, v101, vcc
	v_lshlrev_b64 v[92:93], 13, v[114:115]
	global_load_dwordx4 v[88:91], v[88:89], off offset:3072
	v_lshl_add_u64 v[108:109], v[152:153], 0, v[92:93]
	global_load_dwordx4 v[92:95], v[108:109], off
	global_load_dwordx4 v[96:99], v[108:109], off offset:16
	v_lshl_add_u64 v[100:101], v[100:101], 0, s[20:21]
	global_load_dwordx4 v[100:103], v[100:101], off offset:256
	s_nop 0
	global_load_dwordx4 v[104:107], v[108:109], off offset:512
	s_nop 0
	global_load_dwordx4 v[108:111], v[108:109], off offset:528
	v_lshlrev_b64 v[112:113], 12, v[112:113]
	s_waitcnt lgkmcnt(0)
	global_store_dwordx4 v[242:243], v[244:247], off offset:256
	s_waitcnt vmcnt(11)
	v_lshlrev_b32_e32 v116, 16, v64
	v_and_b32_e32 v117, 0xffff0000, v64
	v_lshlrev_b32_e32 v64, 16, v65
	v_and_b32_e32 v65, 0xffff0000, v65
	s_waitcnt vmcnt(10)
	v_pk_fma_f32 v[62:63], v[62:63], v[64:65], v[70:71]
	v_lshlrev_b32_e32 v64, 16, v66
	v_and_b32_e32 v65, 0xffff0000, v66
	v_pk_fma_f32 v[60:61], v[60:61], v[116:117], v[68:69]
	s_waitcnt vmcnt(9)
	v_pk_fma_f32 v[64:65], v[56:57], v[64:65], v[72:73]
	v_lshlrev_b32_e32 v56, 16, v67
	v_and_b32_e32 v57, 0xffff0000, v67
	v_pk_fma_f32 v[66:67], v[58:59], v[56:57], v[74:75]
	v_cvt_pk_bf16_f32 v56, v60, v61
	v_lshl_add_u64 v[60:61], s[14:15], 0, v[112:113]
	v_cvt_pk_bf16_f32 v57, v62, v63
	v_cvt_pk_bf16_f32 v58, v64, v65
	v_cvt_pk_bf16_f32 v59, v66, v67
	v_lshl_add_u64 v[60:61], v[60:61], 0, v[146:147]
	ds_bpermute_b32 v250, v254, v56
	ds_bpermute_b32 v251, v254, v57
	ds_bpermute_b32 v252, v254, v58
	ds_bpermute_b32 v253, v254, v59
	ds_bpermute_b32 v248, v254, v60
	ds_bpermute_b32 v249, v254, v61
	s_waitcnt lgkmcnt(0)
	global_store_dwordx4 v[248:249], v[250:253], off
	s_waitcnt vmcnt(9)
	s_nop 0
	v_lshlrev_b32_e32 v56, 16, v76
	v_and_b32_e32 v57, 0xffff0000, v76
	s_waitcnt vmcnt(8)
	v_pk_fma_f32 v[52:53], v[52:53], v[56:57], v[80:81]
	v_lshlrev_b32_e32 v56, 16, v77
	v_and_b32_e32 v57, 0xffff0000, v77
	v_pk_fma_f32 v[54:55], v[54:55], v[56:57], v[82:83]
	v_lshlrev_b32_e32 v56, 16, v78
	v_and_b32_e32 v57, 0xffff0000, v78
	s_waitcnt vmcnt(7)
	v_pk_fma_f32 v[56:57], v[44:45], v[56:57], v[84:85]
	v_lshlrev_b32_e32 v44, 16, v79
	v_and_b32_e32 v45, 0xffff0000, v79
	v_pk_fma_f32 v[58:59], v[46:47], v[44:45], v[86:87]
	v_cvt_pk_bf16_f32 v44, v52, v53
	v_cvt_pk_bf16_f32 v45, v54, v55
	v_cvt_pk_bf16_f32 v46, v56, v57
	v_cvt_pk_bf16_f32 v47, v58, v59
	ds_bpermute_b32 v238, v254, v44
	ds_bpermute_b32 v239, v254, v45
	ds_bpermute_b32 v240, v254, v46
	ds_bpermute_b32 v241, v254, v47
	ds_bpermute_b32 v236, v254, v60
	ds_bpermute_b32 v237, v254, v61
	v_add_u32_e32 v80, 0xa0, v148
	v_ashrrev_i32_e32 v81, 31, v80
	s_waitcnt lgkmcnt(0)
	global_store_dwordx4 v[236:237], v[238:241], off offset:256
	s_waitcnt vmcnt(7)
	v_lshlrev_b32_e32 v46, 16, v88
	v_and_b32_e32 v47, 0xffff0000, v88
	s_waitcnt vmcnt(6)
	v_pk_fma_f32 v[46:47], v[48:49], v[46:47], v[92:93]
	v_lshlrev_b32_e32 v48, 16, v89
	v_and_b32_e32 v49, 0xffff0000, v89
	v_pk_fma_f32 v[48:49], v[50:51], v[48:49], v[94:95]
	v_lshlrev_b32_e32 v50, 16, v90
	v_and_b32_e32 v51, 0xffff0000, v90
	v_lshlrev_b64 v[44:45], 12, v[114:115]
	s_waitcnt vmcnt(5)
	v_pk_fma_f32 v[50:51], v[40:41], v[50:51], v[96:97]
	v_lshlrev_b32_e32 v40, 16, v91
	v_and_b32_e32 v41, 0xffff0000, v91
	v_pk_fma_f32 v[52:53], v[42:43], v[40:41], v[98:99]
	v_lshl_add_u64 v[44:45], s[14:15], 0, v[44:45]
	v_cvt_pk_bf16_f32 v40, v46, v47
	v_cvt_pk_bf16_f32 v41, v48, v49
	v_cvt_pk_bf16_f32 v42, v50, v51
	v_cvt_pk_bf16_f32 v43, v52, v53
	v_lshl_add_u64 v[44:45], v[44:45], 0, v[146:147]
	ds_bpermute_b32 v244, v254, v40
	ds_bpermute_b32 v245, v254, v41
	ds_bpermute_b32 v246, v254, v42
	ds_bpermute_b32 v247, v254, v43
	ds_bpermute_b32 v242, v254, v44
	ds_bpermute_b32 v243, v254, v45
	v_add_u32_e32 v82, 0xb0, v148
	v_mad_i64_i32 v[56:57], s[56:57], v82, s74, v[150:151]
	s_waitcnt lgkmcnt(0)
	global_store_dwordx4 v[242:243], v[244:247], off
	s_waitcnt vmcnt(5)
	v_lshlrev_b32_e32 v40, 16, v100
	v_and_b32_e32 v41, 0xffff0000, v100
	s_waitcnt vmcnt(4)
	v_pk_fma_f32 v[36:37], v[36:37], v[40:41], v[104:105]
	v_lshlrev_b32_e32 v40, 16, v101
	v_and_b32_e32 v41, 0xffff0000, v101
	v_pk_fma_f32 v[38:39], v[38:39], v[40:41], v[106:107]
	v_lshlrev_b32_e32 v40, 16, v102
	v_and_b32_e32 v41, 0xffff0000, v102
	s_waitcnt vmcnt(3)
	v_pk_fma_f32 v[40:41], v[32:33], v[40:41], v[108:109]
	v_lshlrev_b32_e32 v32, 16, v103
	v_and_b32_e32 v33, 0xffff0000, v103
	v_pk_fma_f32 v[42:43], v[34:35], v[32:33], v[110:111]
	v_cvt_pk_bf16_f32 v32, v36, v37
	v_cvt_pk_bf16_f32 v33, v38, v39
	v_cvt_pk_bf16_f32 v34, v40, v41
	v_cvt_pk_bf16_f32 v35, v42, v43
	ds_bpermute_b32 v250, v254, v32
	ds_bpermute_b32 v251, v254, v33
	ds_bpermute_b32 v252, v254, v34
	ds_bpermute_b32 v253, v254, v35
	ds_bpermute_b32 v248, v254, v44
	ds_bpermute_b32 v249, v254, v45
	v_lshlrev_b64 v[36:37], 13, v[80:81]
	v_lshl_add_u64 v[52:53], v[152:153], 0, v[36:37]
	v_mad_i64_i32 v[32:33], s[56:57], v80, s74, v[150:151]
	v_lshl_add_u64 v[44:45], v[32:33], 0, v[146:147]
	v_add_co_u32_e32 v32, vcc, s67, v44
	v_lshl_add_u64 v[68:69], v[56:57], 0, v[146:147]
	s_nop 0
	v_addc_co_u32_e32 v33, vcc, 0, v45, vcc
	global_load_dwordx4 v[32:35], v[32:33], off offset:3072
	s_nop 0
	global_load_dwordx4 v[36:39], v[52:53], off
	global_load_dwordx4 v[40:43], v[52:53], off offset:16
	v_lshl_add_u64 v[44:45], v[44:45], 0, s[20:21]
	global_load_dwordx4 v[44:47], v[44:45], off offset:256
	s_nop 0
	global_load_dwordx4 v[48:51], v[52:53], off offset:512
	s_nop 0
	global_load_dwordx4 v[52:55], v[52:53], off offset:528
	v_add_co_u32_e32 v56, vcc, s67, v68
	v_ashrrev_i32_e32 v83, 31, v82
	s_nop 0
	v_addc_co_u32_e32 v57, vcc, 0, v69, vcc
	v_lshlrev_b64 v[60:61], 13, v[82:83]
	global_load_dwordx4 v[56:59], v[56:57], off offset:3072
	v_lshl_add_u64 v[76:77], v[152:153], 0, v[60:61]
	global_load_dwordx4 v[60:63], v[76:77], off
	global_load_dwordx4 v[64:67], v[76:77], off offset:16
	v_lshl_add_u64 v[68:69], v[68:69], 0, s[20:21]
	global_load_dwordx4 v[68:71], v[68:69], off offset:256
	s_nop 0
	global_load_dwordx4 v[72:75], v[76:77], off offset:512
	s_nop 0
	global_load_dwordx4 v[76:79], v[76:77], off offset:528
	v_lshlrev_b64 v[80:81], 12, v[80:81]
	s_andn2_b64 vcc, exec, s[4:5]
	s_mov_b64 s[4:5], -1
	s_waitcnt lgkmcnt(0)
	global_store_dwordx4 v[248:249], v[250:253], off offset:256
	s_waitcnt vmcnt(11)
	v_lshlrev_b32_e32 v84, 16, v32
	v_and_b32_e32 v85, 0xffff0000, v32
	v_lshlrev_b32_e32 v32, 16, v33
	v_and_b32_e32 v33, 0xffff0000, v33
	s_waitcnt vmcnt(10)
	v_pk_fma_f32 v[30:31], v[30:31], v[32:33], v[38:39]
	v_lshlrev_b32_e32 v32, 16, v34
	v_and_b32_e32 v33, 0xffff0000, v34
	v_pk_fma_f32 v[28:29], v[28:29], v[84:85], v[36:37]
	s_waitcnt vmcnt(9)
	v_pk_fma_f32 v[32:33], v[24:25], v[32:33], v[40:41]
	v_lshlrev_b32_e32 v24, 16, v35
	v_and_b32_e32 v25, 0xffff0000, v35
	v_pk_fma_f32 v[34:35], v[26:27], v[24:25], v[42:43]
	v_cvt_pk_bf16_f32 v24, v28, v29
	v_lshl_add_u64 v[28:29], s[14:15], 0, v[80:81]
	v_cvt_pk_bf16_f32 v25, v30, v31
	v_cvt_pk_bf16_f32 v26, v32, v33
	v_cvt_pk_bf16_f32 v27, v34, v35
	v_lshl_add_u64 v[28:29], v[28:29], 0, v[146:147]
	ds_bpermute_b32 v238, v254, v24
	ds_bpermute_b32 v239, v254, v25
	ds_bpermute_b32 v240, v254, v26
	ds_bpermute_b32 v241, v254, v27
	ds_bpermute_b32 v236, v254, v28
	ds_bpermute_b32 v237, v254, v29
	s_waitcnt lgkmcnt(0)
	global_store_dwordx4 v[236:237], v[238:241], off
	s_waitcnt vmcnt(9)
	s_nop 0
	v_lshlrev_b32_e32 v24, 16, v44
	v_and_b32_e32 v25, 0xffff0000, v44
	s_waitcnt vmcnt(8)
	v_pk_fma_f32 v[20:21], v[20:21], v[24:25], v[48:49]
	v_lshlrev_b32_e32 v24, 16, v45
	v_and_b32_e32 v25, 0xffff0000, v45
	v_pk_fma_f32 v[22:23], v[22:23], v[24:25], v[50:51]
	v_lshlrev_b32_e32 v24, 16, v46
	v_and_b32_e32 v25, 0xffff0000, v46
	s_waitcnt vmcnt(7)
	v_pk_fma_f32 v[24:25], v[12:13], v[24:25], v[52:53]
	v_lshlrev_b32_e32 v12, 16, v47
	v_and_b32_e32 v13, 0xffff0000, v47
	v_pk_fma_f32 v[26:27], v[14:15], v[12:13], v[54:55]
	v_cvt_pk_bf16_f32 v12, v20, v21
	v_cvt_pk_bf16_f32 v13, v22, v23
	v_cvt_pk_bf16_f32 v14, v24, v25
	v_cvt_pk_bf16_f32 v15, v26, v27
	ds_bpermute_b32 v244, v254, v12
	ds_bpermute_b32 v245, v254, v13
	ds_bpermute_b32 v246, v254, v14
	ds_bpermute_b32 v247, v254, v15
	ds_bpermute_b32 v242, v254, v28
	ds_bpermute_b32 v243, v254, v29
	s_waitcnt lgkmcnt(0)
	global_store_dwordx4 v[242:243], v[244:247], off offset:256
	s_waitcnt vmcnt(7)
	s_nop 0
	v_lshlrev_b32_e32 v14, 16, v56
	v_and_b32_e32 v15, 0xffff0000, v56
	s_waitcnt vmcnt(6)
	v_pk_fma_f32 v[14:15], v[16:17], v[14:15], v[60:61]
	v_lshlrev_b32_e32 v16, 16, v57
	v_and_b32_e32 v17, 0xffff0000, v57
	v_pk_fma_f32 v[16:17], v[18:19], v[16:17], v[62:63]
	v_lshlrev_b32_e32 v18, 16, v58
	v_and_b32_e32 v19, 0xffff0000, v58
	v_lshlrev_b64 v[12:13], 12, v[82:83]
	s_waitcnt vmcnt(5)
	v_pk_fma_f32 v[18:19], v[8:9], v[18:19], v[64:65]
	v_lshlrev_b32_e32 v8, 16, v59
	v_and_b32_e32 v9, 0xffff0000, v59
	v_pk_fma_f32 v[20:21], v[10:11], v[8:9], v[66:67]
	v_lshl_add_u64 v[12:13], s[14:15], 0, v[12:13]
	v_cvt_pk_bf16_f32 v8, v14, v15
	v_cvt_pk_bf16_f32 v9, v16, v17
	v_cvt_pk_bf16_f32 v10, v18, v19
	v_cvt_pk_bf16_f32 v11, v20, v21
	v_lshl_add_u64 v[12:13], v[12:13], 0, v[146:147]
	ds_bpermute_b32 v250, v254, v8
	ds_bpermute_b32 v251, v254, v9
	ds_bpermute_b32 v252, v254, v10
	ds_bpermute_b32 v253, v254, v11
	ds_bpermute_b32 v248, v254, v12
	ds_bpermute_b32 v249, v254, v13
	s_waitcnt lgkmcnt(0)
	global_store_dwordx4 v[248:249], v[250:253], off
	s_waitcnt vmcnt(5)
	s_nop 0
	v_lshlrev_b32_e32 v8, 16, v68
	v_and_b32_e32 v9, 0xffff0000, v68
	s_waitcnt vmcnt(4)
	v_pk_fma_f32 v[4:5], v[4:5], v[8:9], v[72:73]
	v_lshlrev_b32_e32 v8, 16, v69
	v_and_b32_e32 v9, 0xffff0000, v69
	v_pk_fma_f32 v[6:7], v[6:7], v[8:9], v[74:75]
	v_lshlrev_b32_e32 v8, 16, v70
	v_and_b32_e32 v9, 0xffff0000, v70
	s_waitcnt vmcnt(3)
	v_pk_fma_f32 v[8:9], v[0:1], v[8:9], v[76:77]
	v_lshlrev_b32_e32 v0, 16, v71
	v_and_b32_e32 v1, 0xffff0000, v71
	v_pk_fma_f32 v[10:11], v[2:3], v[0:1], v[78:79]
	v_cvt_pk_bf16_f32 v0, v4, v5
	v_cvt_pk_bf16_f32 v1, v6, v7
	v_cvt_pk_bf16_f32 v2, v8, v9
	v_cvt_pk_bf16_f32 v3, v10, v11
	ds_bpermute_b32 v238, v254, v0
	ds_bpermute_b32 v239, v254, v1
	ds_bpermute_b32 v240, v254, v2
	ds_bpermute_b32 v241, v254, v3
	ds_bpermute_b32 v236, v254, v12
	ds_bpermute_b32 v237, v254, v13
	s_waitcnt lgkmcnt(0)
	global_store_dwordx4 v[236:237], v[238:241], off offset:256
	s_cbranch_vccnz .LBB0_1402
	s_andn2_b64 vcc, exec, s[12:13]
	s_cbranch_vccnz .LBB0_1401
	s_barrier
	s_branch .LBB0_1401

.LBB0_1694:
	v_and_b32_e32 v254, 63, v128
	v_and_b32_e32 v255, 3, v254
	v_lshrrev_b32_e32 v254, 2, v254
	v_lshl_or_b32 v254, v255, 4, v254
	v_lshlrev_b32_e32 v254, 2, v254
	v_mul_f32_e32 v158, 0xbfb8aa3b, v124
	v_mul_f32_e32 v159, 0xbfb8aa3b, v125
	v_exp_f32_e32 v158, v158
	v_exp_f32_e32 v159, v159
	v_mul_f32_e32 v160, 0xbfb8aa3b, v126
	v_mul_f32_e32 v161, 0xbfb8aa3b, v127
	v_exp_f32_e32 v160, v160
	v_exp_f32_e32 v161, v161
	v_add_f32_e32 v158, 1.0, v158
	v_add_f32_e32 v159, 1.0, v159
	v_rcp_f32_e32 v158, v158
	v_rcp_f32_e32 v159, v159
	v_add_f32_e32 v160, 1.0, v160
	v_add_f32_e32 v161, 1.0, v161
	v_rcp_f32_e32 v160, v160
	v_rcp_f32_e32 v161, v161
	v_pk_mul_f32 v[124:125], v[124:125], v[158:159]
	v_lshl_add_u32 v155, s24, 8, v129
	v_pk_mul_f32 v[120:121], v[124:125], v[120:121]
	v_pk_mul_f32 v[124:125], v[126:127], v[160:161]
	v_cvt_pk_bf16_f32 v120, v120, v121
	v_mul_f32_e32 v121, 0xbfb8aa3b, v116
	v_pk_mul_f32 v[122:123], v[124:125], v[122:123]
	v_exp_f32_e32 v124, v121
	v_mul_f32_e32 v121, 0xbfb8aa3b, v117
	v_exp_f32_e32 v125, v121
	v_cvt_pk_bf16_f32 v121, v122, v123
	v_add_f32_e32 v122, 1.0, v124
	v_mul_f32_e32 v124, 0xbfb8aa3b, v118
	v_add_f32_e32 v123, 1.0, v125
	v_mul_f32_e32 v125, 0xbfb8aa3b, v119
	v_exp_f32_e32 v124, v124
	v_exp_f32_e32 v125, v125
	v_rcp_f32_e32 v122, v122
	v_rcp_f32_e32 v123, v123
	v_add_f32_e32 v124, 1.0, v124
	v_add_f32_e32 v125, 1.0, v125
	v_rcp_f32_e32 v124, v124
	v_rcp_f32_e32 v125, v125
	v_pk_mul_f32 v[116:117], v[116:117], v[122:123]
	v_lshl_or_b32 v146, s22, 7, v151
	v_pk_mul_f32 v[112:113], v[116:117], v[112:113]
	v_mul_f32_e32 v116, 0xbfb8aa3b, v110
	v_cvt_pk_bf16_f32 v122, v112, v113
	v_pk_mul_f32 v[112:113], v[118:119], v[124:125]
	v_mul_f32_e32 v117, 0xbfb8aa3b, v111
	v_pk_mul_f32 v[112:113], v[112:113], v[114:115]
	v_mul_f32_e32 v114, 0xbfb8aa3b, v108
	v_mul_f32_e32 v115, 0xbfb8aa3b, v109
	v_exp_f32_e32 v114, v114
	v_exp_f32_e32 v115, v115
	v_exp_f32_e32 v116, v116
	v_exp_f32_e32 v117, v117
	v_add_f32_e32 v114, 1.0, v114
	v_add_f32_e32 v115, 1.0, v115
	v_rcp_f32_e32 v114, v114
	v_rcp_f32_e32 v115, v115
	v_add_f32_e32 v116, 1.0, v116
	v_add_f32_e32 v117, 1.0, v117
	v_rcp_f32_e32 v116, v116
	v_rcp_f32_e32 v117, v117
	v_pk_mul_f32 v[108:109], v[108:109], v[114:115]
	v_ashrrev_i32_e32 v147, 31, v146
	v_pk_mul_f32 v[104:105], v[108:109], v[104:105]
	v_pk_mul_f32 v[108:109], v[110:111], v[116:117]
	v_cvt_pk_bf16_f32 v104, v104, v105
	v_mul_f32_e32 v105, 0xbfb8aa3b, v100
	v_pk_mul_f32 v[106:107], v[108:109], v[106:107]
	v_exp_f32_e32 v108, v105
	v_mul_f32_e32 v105, 0xbfb8aa3b, v101
	v_exp_f32_e32 v109, v105
	v_cvt_pk_bf16_f32 v105, v106, v107
	v_add_f32_e32 v106, 1.0, v108
	v_mul_f32_e32 v108, 0xbfb8aa3b, v102
	v_add_f32_e32 v107, 1.0, v109
	v_mul_f32_e32 v109, 0xbfb8aa3b, v103
	v_exp_f32_e32 v108, v108
	v_exp_f32_e32 v109, v109
	v_rcp_f32_e32 v106, v106
	v_rcp_f32_e32 v107, v107
	v_add_f32_e32 v108, 1.0, v108
	v_add_f32_e32 v109, 1.0, v109
	v_rcp_f32_e32 v108, v108
	v_rcp_f32_e32 v109, v109
	v_pk_mul_f32 v[100:101], v[100:101], v[106:107]
	v_mov_b64_e32 v[148:149], s[6:7]
	v_pk_mul_f32 v[96:97], v[100:101], v[96:97]
	v_mul_f32_e32 v100, 0xbfb8aa3b, v94
	v_cvt_pk_bf16_f32 v106, v96, v97
	v_pk_mul_f32 v[96:97], v[102:103], v[108:109]
	v_mul_f32_e32 v101, 0xbfb8aa3b, v95
	v_pk_mul_f32 v[96:97], v[96:97], v[98:99]
	v_mul_f32_e32 v98, 0xbfb8aa3b, v92
	v_mul_f32_e32 v99, 0xbfb8aa3b, v93
	v_exp_f32_e32 v98, v98
	v_exp_f32_e32 v99, v99
	v_exp_f32_e32 v100, v100
	v_exp_f32_e32 v101, v101
	v_add_f32_e32 v98, 1.0, v98
	v_add_f32_e32 v99, 1.0, v99
	v_rcp_f32_e32 v98, v98
	v_rcp_f32_e32 v99, v99
	v_add_f32_e32 v100, 1.0, v100
	v_add_f32_e32 v101, 1.0, v101
	v_rcp_f32_e32 v100, v100
	v_rcp_f32_e32 v101, v101
	v_pk_mul_f32 v[92:93], v[92:93], v[98:99]
	v_cvt_pk_bf16_f32 v123, v112, v113
	v_pk_mul_f32 v[88:89], v[92:93], v[88:89]
	v_pk_mul_f32 v[92:93], v[94:95], v[100:101]
	v_cvt_pk_bf16_f32 v88, v88, v89
	v_mul_f32_e32 v89, 0xbfb8aa3b, v84
	v_pk_mul_f32 v[90:91], v[92:93], v[90:91]
	v_exp_f32_e32 v92, v89
	v_mul_f32_e32 v89, 0xbfb8aa3b, v85
	v_exp_f32_e32 v93, v89
	v_cvt_pk_bf16_f32 v89, v90, v91
	v_add_f32_e32 v90, 1.0, v92
	v_mul_f32_e32 v92, 0xbfb8aa3b, v86
	v_add_f32_e32 v91, 1.0, v93
	v_mul_f32_e32 v93, 0xbfb8aa3b, v87
	v_exp_f32_e32 v92, v92
	v_exp_f32_e32 v93, v93
	v_rcp_f32_e32 v90, v90
	v_rcp_f32_e32 v91, v91
	v_add_f32_e32 v92, 1.0, v92
	v_add_f32_e32 v93, 1.0, v93
	v_rcp_f32_e32 v92, v92
	v_rcp_f32_e32 v93, v93
	v_pk_mul_f32 v[84:85], v[84:85], v[90:91]
	v_or_b32_e32 v112, 16, v155
	v_pk_mul_f32 v[80:81], v[84:85], v[80:81]
	v_mul_f32_e32 v84, 0xbfb8aa3b, v78
	v_cvt_pk_bf16_f32 v90, v80, v81
	v_pk_mul_f32 v[80:81], v[86:87], v[92:93]
	v_mul_f32_e32 v85, 0xbfb8aa3b, v79
	v_pk_mul_f32 v[80:81], v[80:81], v[82:83]
	v_mul_f32_e32 v82, 0xbfb8aa3b, v76
	v_mul_f32_e32 v83, 0xbfb8aa3b, v77
	v_exp_f32_e32 v82, v82
	v_exp_f32_e32 v83, v83
	v_exp_f32_e32 v84, v84
	v_exp_f32_e32 v85, v85
	v_add_f32_e32 v82, 1.0, v82
	v_add_f32_e32 v83, 1.0, v83
	v_rcp_f32_e32 v82, v82
	v_rcp_f32_e32 v83, v83
	v_add_f32_e32 v84, 1.0, v84
	v_add_f32_e32 v85, 1.0, v85
	v_rcp_f32_e32 v84, v84
	v_rcp_f32_e32 v85, v85
	v_pk_mul_f32 v[76:77], v[76:77], v[82:83]
	v_cvt_pk_bf16_f32 v107, v96, v97
	v_pk_mul_f32 v[72:73], v[76:77], v[72:73]
	v_pk_mul_f32 v[76:77], v[78:79], v[84:85]
	v_cvt_pk_bf16_f32 v72, v72, v73
	v_mul_f32_e32 v73, 0xbfb8aa3b, v68
	v_pk_mul_f32 v[74:75], v[76:77], v[74:75]
	v_exp_f32_e32 v76, v73
	v_mul_f32_e32 v73, 0xbfb8aa3b, v69
	v_exp_f32_e32 v77, v73
	v_cvt_pk_bf16_f32 v73, v74, v75
	v_add_f32_e32 v74, 1.0, v76
	v_mul_f32_e32 v76, 0xbfb8aa3b, v70
	v_add_f32_e32 v75, 1.0, v77
	v_mul_f32_e32 v77, 0xbfb8aa3b, v71
	v_exp_f32_e32 v76, v76
	v_exp_f32_e32 v77, v77
	v_rcp_f32_e32 v74, v74
	v_rcp_f32_e32 v75, v75
	v_add_f32_e32 v76, 1.0, v76
	v_add_f32_e32 v77, 1.0, v77
	v_rcp_f32_e32 v76, v76
	v_rcp_f32_e32 v77, v77
	v_pk_mul_f32 v[68:69], v[68:69], v[74:75]
	v_or_b32_e32 v96, 32, v155
	v_pk_mul_f32 v[64:65], v[68:69], v[64:65]
	v_mul_f32_e32 v68, 0xbfb8aa3b, v62
	v_cvt_pk_bf16_f32 v74, v64, v65
	v_pk_mul_f32 v[64:65], v[70:71], v[76:77]
	v_mul_f32_e32 v69, 0xbfb8aa3b, v63
	v_pk_mul_f32 v[64:65], v[64:65], v[66:67]
	v_mul_f32_e32 v66, 0xbfb8aa3b, v60
	v_mul_f32_e32 v67, 0xbfb8aa3b, v61
	v_exp_f32_e32 v66, v66
	v_exp_f32_e32 v67, v67
	v_exp_f32_e32 v68, v68
	v_exp_f32_e32 v69, v69
	v_add_f32_e32 v66, 1.0, v66
	v_add_f32_e32 v67, 1.0, v67
	v_rcp_f32_e32 v66, v66
	v_rcp_f32_e32 v67, v67
	v_add_f32_e32 v68, 1.0, v68
	v_add_f32_e32 v69, 1.0, v69
	v_rcp_f32_e32 v68, v68
	v_rcp_f32_e32 v69, v69
	v_pk_mul_f32 v[60:61], v[60:61], v[66:67]
	v_cvt_pk_bf16_f32 v91, v80, v81
	v_pk_mul_f32 v[56:57], v[60:61], v[56:57]
	v_pk_mul_f32 v[60:61], v[62:63], v[68:69]
	v_cvt_pk_bf16_f32 v56, v56, v57
	v_mul_f32_e32 v57, 0xbfb8aa3b, v52
	v_pk_mul_f32 v[58:59], v[60:61], v[58:59]
	v_exp_f32_e32 v60, v57
	v_mul_f32_e32 v57, 0xbfb8aa3b, v53
	v_exp_f32_e32 v61, v57
	v_cvt_pk_bf16_f32 v57, v58, v59
	v_add_f32_e32 v58, 1.0, v60
	v_mul_f32_e32 v60, 0xbfb8aa3b, v54
	v_add_f32_e32 v59, 1.0, v61
	v_mul_f32_e32 v61, 0xbfb8aa3b, v55
	v_exp_f32_e32 v60, v60
	v_exp_f32_e32 v61, v61
	v_rcp_f32_e32 v58, v58
	v_rcp_f32_e32 v59, v59
	v_add_f32_e32 v60, 1.0, v60
	v_add_f32_e32 v61, 1.0, v61
	v_rcp_f32_e32 v60, v60
	v_rcp_f32_e32 v61, v61
	v_pk_mul_f32 v[52:53], v[52:53], v[58:59]
	v_or_b32_e32 v80, 48, v155
	v_pk_mul_f32 v[48:49], v[52:53], v[48:49]
	v_mul_f32_e32 v52, 0xbfb8aa3b, v46
	v_cvt_pk_bf16_f32 v58, v48, v49
	v_pk_mul_f32 v[48:49], v[54:55], v[60:61]
	v_mul_f32_e32 v53, 0xbfb8aa3b, v47
	v_pk_mul_f32 v[48:49], v[48:49], v[50:51]
	v_mul_f32_e32 v50, 0xbfb8aa3b, v44
	v_mul_f32_e32 v51, 0xbfb8aa3b, v45
	v_exp_f32_e32 v50, v50
	v_exp_f32_e32 v51, v51
	v_exp_f32_e32 v52, v52
	v_exp_f32_e32 v53, v53
	v_add_f32_e32 v50, 1.0, v50
	v_add_f32_e32 v51, 1.0, v51
	v_rcp_f32_e32 v50, v50
	v_rcp_f32_e32 v51, v51
	v_add_f32_e32 v52, 1.0, v52
	v_add_f32_e32 v53, 1.0, v53
	v_rcp_f32_e32 v52, v52
	v_rcp_f32_e32 v53, v53
	v_pk_mul_f32 v[44:45], v[44:45], v[50:51]
	v_cvt_pk_bf16_f32 v75, v64, v65
	v_pk_mul_f32 v[40:41], v[44:45], v[40:41]
	v_pk_mul_f32 v[44:45], v[46:47], v[52:53]
	v_cvt_pk_bf16_f32 v40, v40, v41
	v_mul_f32_e32 v41, 0xbfb8aa3b, v36
	v_pk_mul_f32 v[42:43], v[44:45], v[42:43]
	v_exp_f32_e32 v44, v41
	v_mul_f32_e32 v41, 0xbfb8aa3b, v37
	v_exp_f32_e32 v45, v41
	v_cvt_pk_bf16_f32 v41, v42, v43
	v_add_f32_e32 v42, 1.0, v44
	v_mul_f32_e32 v44, 0xbfb8aa3b, v38
	v_add_f32_e32 v43, 1.0, v45
	v_mul_f32_e32 v45, 0xbfb8aa3b, v39
	v_exp_f32_e32 v44, v44
	v_exp_f32_e32 v45, v45
	v_rcp_f32_e32 v42, v42
	v_rcp_f32_e32 v43, v43
	v_add_f32_e32 v44, 1.0, v44
	v_add_f32_e32 v45, 1.0, v45
	v_rcp_f32_e32 v44, v44
	v_rcp_f32_e32 v45, v45
	v_pk_mul_f32 v[36:37], v[36:37], v[42:43]
	v_add_u32_e32 v64, 0x80, v155
	v_pk_mul_f32 v[32:33], v[36:37], v[32:33]
	v_mul_f32_e32 v36, 0xbfb8aa3b, v30
	v_cvt_pk_bf16_f32 v42, v32, v33
	v_pk_mul_f32 v[32:33], v[38:39], v[44:45]
	v_mul_f32_e32 v37, 0xbfb8aa3b, v31
	v_pk_mul_f32 v[32:33], v[32:33], v[34:35]
	v_mul_f32_e32 v34, 0xbfb8aa3b, v28
	v_mul_f32_e32 v35, 0xbfb8aa3b, v29
	v_exp_f32_e32 v34, v34
	v_exp_f32_e32 v35, v35
	v_exp_f32_e32 v36, v36
	v_exp_f32_e32 v37, v37
	v_add_f32_e32 v34, 1.0, v34
	v_add_f32_e32 v35, 1.0, v35
	v_rcp_f32_e32 v34, v34
	v_rcp_f32_e32 v35, v35
	v_add_f32_e32 v36, 1.0, v36
	v_add_f32_e32 v37, 1.0, v37
	v_rcp_f32_e32 v36, v36
	v_rcp_f32_e32 v37, v37
	v_pk_mul_f32 v[28:29], v[28:29], v[34:35]
	v_cvt_pk_bf16_f32 v59, v48, v49
	v_pk_mul_f32 v[24:25], v[28:29], v[24:25]
	v_pk_mul_f32 v[28:29], v[30:31], v[36:37]
	v_cvt_pk_bf16_f32 v24, v24, v25
	v_mul_f32_e32 v25, 0xbfb8aa3b, v20
	v_pk_mul_f32 v[26:27], v[28:29], v[26:27]
	v_exp_f32_e32 v28, v25
	v_mul_f32_e32 v25, 0xbfb8aa3b, v21
	v_exp_f32_e32 v29, v25
	v_cvt_pk_bf16_f32 v25, v26, v27
	v_add_f32_e32 v26, 1.0, v28
	v_mul_f32_e32 v28, 0xbfb8aa3b, v22
	v_add_f32_e32 v27, 1.0, v29
	v_mul_f32_e32 v29, 0xbfb8aa3b, v23
	v_exp_f32_e32 v28, v28
	v_exp_f32_e32 v29, v29
	v_rcp_f32_e32 v26, v26
	v_rcp_f32_e32 v27, v27
	v_add_f32_e32 v28, 1.0, v28
	v_add_f32_e32 v29, 1.0, v29
	v_rcp_f32_e32 v28, v28
	v_rcp_f32_e32 v29, v29
	v_pk_mul_f32 v[20:21], v[20:21], v[26:27]
	v_add_u32_e32 v48, 0x90, v155
	v_pk_mul_f32 v[16:17], v[20:21], v[16:17]
	v_mul_f32_e32 v20, 0xbfb8aa3b, v14
	v_cvt_pk_bf16_f32 v26, v16, v17
	v_pk_mul_f32 v[16:17], v[22:23], v[28:29]
	v_mul_f32_e32 v21, 0xbfb8aa3b, v15
	v_pk_mul_f32 v[16:17], v[16:17], v[18:19]
	v_mul_f32_e32 v18, 0xbfb8aa3b, v12
	v_mul_f32_e32 v19, 0xbfb8aa3b, v13
	v_exp_f32_e32 v18, v18
	v_exp_f32_e32 v19, v19
	v_exp_f32_e32 v20, v20
	v_exp_f32_e32 v21, v21
	v_add_f32_e32 v18, 1.0, v18
	v_add_f32_e32 v19, 1.0, v19
	v_rcp_f32_e32 v18, v18
	v_rcp_f32_e32 v19, v19
	v_add_f32_e32 v20, 1.0, v20
	v_add_f32_e32 v21, 1.0, v21
	v_rcp_f32_e32 v20, v20
	v_rcp_f32_e32 v21, v21
	v_pk_mul_f32 v[12:13], v[12:13], v[18:19]
	v_cvt_pk_bf16_f32 v43, v32, v33
	v_pk_mul_f32 v[8:9], v[12:13], v[8:9]
	v_pk_mul_f32 v[12:13], v[14:15], v[20:21]
	v_cvt_pk_bf16_f32 v8, v8, v9
	v_mul_f32_e32 v9, 0xbfb8aa3b, v4
	v_pk_mul_f32 v[10:11], v[12:13], v[10:11]
	v_exp_f32_e32 v12, v9
	v_mul_f32_e32 v9, 0xbfb8aa3b, v5
	v_exp_f32_e32 v13, v9
	v_cvt_pk_bf16_f32 v9, v10, v11
	v_add_f32_e32 v10, 1.0, v12
	v_mul_f32_e32 v12, 0xbfb8aa3b, v6
	v_add_f32_e32 v11, 1.0, v13
	v_mul_f32_e32 v13, 0xbfb8aa3b, v7
	v_exp_f32_e32 v12, v12
	v_exp_f32_e32 v13, v13
	v_rcp_f32_e32 v10, v10
	v_rcp_f32_e32 v11, v11
	v_add_f32_e32 v12, 1.0, v12
	v_add_f32_e32 v13, 1.0, v13
	v_rcp_f32_e32 v12, v12
	v_rcp_f32_e32 v13, v13
	v_pk_mul_f32 v[4:5], v[4:5], v[10:11]
	v_add_u32_e32 v32, 0xa0, v155
	v_pk_mul_f32 v[0:1], v[4:5], v[0:1]
	v_cvt_pk_bf16_f32 v27, v16, v17
	v_add_u32_e32 v16, 0xb0, v155
	v_cvt_pk_bf16_f32 v10, v0, v1
	v_pk_mul_f32 v[0:1], v[6:7], v[12:13]
	v_mad_i64_i32 v[156:157], s[26:27], v155, s54, v[148:149]
	v_lshlrev_b64 v[146:147], 1, v[146:147]
	v_mad_i64_i32 v[112:113], s[26:27], v112, s54, v[148:149]
	v_mad_i64_i32 v[96:97], s[26:27], v96, s54, v[148:149]
	v_mad_i64_i32 v[80:81], s[26:27], v80, s54, v[148:149]
	v_mad_i64_i32 v[64:65], s[26:27], v64, s54, v[148:149]
	v_mad_i64_i32 v[48:49], s[26:27], v48, s54, v[148:149]
	v_mad_i64_i32 v[32:33], s[26:27], v32, s54, v[148:149]
	v_mad_i64_i32 v[16:17], s[26:27], v16, s54, v[148:149]
	v_pk_mul_f32 v[0:1], v[0:1], v[2:3]
	v_lshl_add_u64 v[156:157], v[156:157], 0, v[146:147]
	v_lshl_add_u64 v[112:113], v[112:113], 0, v[146:147]
	v_lshl_add_u64 v[96:97], v[96:97], 0, v[146:147]
	v_lshl_add_u64 v[80:81], v[80:81], 0, v[146:147]
	v_lshl_add_u64 v[64:65], v[64:65], 0, v[146:147]
	v_lshl_add_u64 v[48:49], v[48:49], 0, v[146:147]
	v_lshl_add_u64 v[32:33], v[32:33], 0, v[146:147]
	v_lshl_add_u64 v[16:17], v[16:17], 0, v[146:147]
	v_cvt_pk_bf16_f32 v11, v0, v1
	s_andn2_b64 vcc, exec, s[4:5]
	s_mov_b64 s[4:5], -1
	ds_bpermute_b32 v238, v254, v120
	ds_bpermute_b32 v239, v254, v121
	ds_bpermute_b32 v240, v254, v122
	ds_bpermute_b32 v241, v254, v123
	ds_bpermute_b32 v236, v254, v156
	ds_bpermute_b32 v237, v254, v157
	ds_bpermute_b32 v244, v254, v104
	ds_bpermute_b32 v245, v254, v105
	ds_bpermute_b32 v246, v254, v106
	ds_bpermute_b32 v247, v254, v107
	ds_bpermute_b32 v242, v254, v112
	ds_bpermute_b32 v243, v254, v113
	ds_bpermute_b32 v250, v254, v88
	ds_bpermute_b32 v251, v254, v89
	ds_bpermute_b32 v252, v254, v90
	ds_bpermute_b32 v253, v254, v91
	ds_bpermute_b32 v248, v254, v96
	ds_bpermute_b32 v249, v254, v97
	s_waitcnt lgkmcnt(12)
	global_store_dwordx4 v[236:237], v[238:241], off
	s_nop 0
	ds_bpermute_b32 v238, v254, v72
	ds_bpermute_b32 v239, v254, v73
	ds_bpermute_b32 v240, v254, v74
	ds_bpermute_b32 v241, v254, v75
	ds_bpermute_b32 v236, v254, v80
	ds_bpermute_b32 v237, v254, v81
	s_waitcnt lgkmcnt(12)
	global_store_dwordx4 v[242:243], v[244:247], off
	s_nop 0
	ds_bpermute_b32 v244, v254, v56
	ds_bpermute_b32 v245, v254, v57
	ds_bpermute_b32 v246, v254, v58
	ds_bpermute_b32 v247, v254, v59
	ds_bpermute_b32 v242, v254, v64
	ds_bpermute_b32 v243, v254, v65
	s_waitcnt lgkmcnt(12)
	global_store_dwordx4 v[248:249], v[250:253], off
	s_nop 0
	ds_bpermute_b32 v250, v254, v40
	ds_bpermute_b32 v251, v254, v41
	ds_bpermute_b32 v252, v254, v42
	ds_bpermute_b32 v253, v254, v43
	ds_bpermute_b32 v248, v254, v48
	ds_bpermute_b32 v249, v254, v49
	s_waitcnt lgkmcnt(12)
	global_store_dwordx4 v[236:237], v[238:241], off
	s_nop 0
	ds_bpermute_b32 v238, v254, v24
	ds_bpermute_b32 v239, v254, v25
	ds_bpermute_b32 v240, v254, v26
	ds_bpermute_b32 v241, v254, v27
	ds_bpermute_b32 v236, v254, v32
	ds_bpermute_b32 v237, v254, v33
	s_waitcnt lgkmcnt(12)
	global_store_dwordx4 v[242:243], v[244:247], off
	s_nop 0
	ds_bpermute_b32 v244, v254, v8
	ds_bpermute_b32 v245, v254, v9
	ds_bpermute_b32 v246, v254, v10
	ds_bpermute_b32 v247, v254, v11
	ds_bpermute_b32 v242, v254, v16
	ds_bpermute_b32 v243, v254, v17
	s_waitcnt lgkmcnt(12)
	global_store_dwordx4 v[248:249], v[250:253], off
	s_waitcnt lgkmcnt(6)
	global_store_dwordx4 v[236:237], v[238:241], off
	s_waitcnt lgkmcnt(0)
	global_store_dwordx4 v[242:243], v[244:247], off
	s_cbranch_vccnz .LBB0_1687
	s_andn2_b64 vcc, exec, s[2:3]
	s_cbranch_vccnz .LBB0_1686
	s_barrier
	s_branch .LBB0_1686
